# attention: removed the 58 XNACK-replay-only s_nop 0 between back-to-back global loads (process runs xnack-)
# speedup vs baseline: 1.0033x; 1.0033x over previous
.LBB0_246:
	s_lshl_b32 s1, s71, 2
	s_and_b32 s22, s1, 0xffffff00
	s_lshr_b32 s0, s71, 3
	s_bfe_u32 s56, s71, 0x30003
	s_or_b32 s24, s22, s72
	s_cmp_lt_i32 s24, 0x8000
	s_movk_i32 s22, 0xfff
	s_cselect_b32 s75, s22, 0x1fff
	s_bfe_u32 s0, s0, 0x10002
	s_andn2_b32 s74, s1, s75
	s_mul_i32 s0, s0, 0x1800000
	s_add_u32 s0, s96, s0
	s_addc_u32 s1, s97, 0
	s_lshl_b32 s22, s71, 4
	s_and_b32 s22, s22, 0x180
	s_add_u32 s22, s0, s22
	v_or_b32_e32 v162, s24, v167
	s_addc_u32 s23, s1, 0
	v_ashrrev_i32_e32 v163, 31, v162
	v_lshl_add_u64 v[12:13], s[22:23], 0, v[158:159]
	v_lshlrev_b64 v[0:1], 9, v[162:163]
	v_lshl_add_u64 v[8:9], v[12:13], 0, v[0:1]
	global_load_dwordx4 v[0:3], v[8:9], off
	v_or_b32_e32 v160, 8, v162
	v_ashrrev_i32_e32 v161, 31, v160
	global_load_dwordx4 v[64:67], v[8:9], off offset:64
	v_lshlrev_b64 v[72:73], 9, v[160:161]
	v_lshl_add_u64 v[72:73], v[12:13], 0, v[72:73]
	global_load_dwordx4 v[68:71], v[72:73], off
	global_load_dwordx4 v[76:79], v[72:73], off offset:64
	s_add_u32 s68, s22, 0x3000000
	s_addc_u32 s69, s23, 0
	s_lshl_b32 s98, s74, 9
	s_add_u32 s100, s68, s98
	s_addc_u32 s101, s69, 0
	s_add_u32 s98, s100, 0x3000000
	s_addc_u32 s99, s101, 0
	s_sub_i32 s76, s24, s74
	s_sub_i32 s0, s76, 64
	s_waitcnt vmcnt(7)
	v_add_u32_e32 v20, s0, v172
	v_min_i32_e32 v21, s75, v20
	s_waitcnt vmcnt(6)
	v_add_u32_e32 v24, s0, v173
	v_min_i32_e32 v25, s75, v24
	s_waitcnt vmcnt(5)
	v_add_u32_e32 v28, s0, v182
	v_min_i32_e32 v29, s75, v28
	s_waitcnt vmcnt(2)
	v_add_u32_e32 v40, s0, v166
	v_min_i32_e32 v32, s75, v40
	v_add_u32_e32 v41, 16, v40
	s_movk_i32 s1, 0xffef
	v_min_i32_e32 v41, s75, v41
	v_or_b32_e32 v128, 32, v166
	v_add_u32_e32 v56, s0, v128
	v_add_u32_e32 v149, s76, v155
	v_add_u32_e32 v150, s76, v172
	v_add_u32_e32 v151, s76, v173
	v_add_u32_e32 v252, s76, v182
	v_or_b32_e32 v251, s76, v167
	v_subrev_u32_e32 v250, s76, v251
	v_or_b32_e32 v144, 8, v251
	v_subrev_u32_e32 v249, s76, v144
	v_add_u32_e32 v196, 0x60, v155
	v_add_u32_e32 v168, 0x60, v172
	v_add_u32_e32 v193, 0x60, v173
	v_add_u32_e32 v194, 0x60, v182
	v_add_u32_e32 v186, s76, v206
	s_waitcnt vmcnt(3)
	v_lshlrev_b32_e32 v4, 16, v0
	v_and_b32_e32 v5, 0xffff0000, v0
	v_lshlrev_b32_e32 v0, 16, v1
	v_and_b32_e32 v1, 0xffff0000, v1
	v_pk_mul_f32 v[4:5], v[4:5], s[58:59] op_sel_hi:[1,0]
	v_pk_mul_f32 v[0:1], v[0:1], s[58:59] op_sel_hi:[1,0]
	v_cvt_pk_bf16_f32 v4, v4, v5
	v_cvt_pk_bf16_f32 v5, v0, v1
	v_lshlrev_b32_e32 v0, 16, v2
	v_and_b32_e32 v1, 0xffff0000, v2
	v_pk_mul_f32 v[0:1], v[0:1], s[58:59] op_sel_hi:[1,0]
	s_nop 0
	v_cvt_pk_bf16_f32 v6, v0, v1
	v_lshlrev_b32_e32 v0, 16, v3
	v_and_b32_e32 v1, 0xffff0000, v3
	v_pk_mul_f32 v[0:1], v[0:1], s[58:59] op_sel_hi:[1,0]
	s_nop 0
	v_cvt_pk_bf16_f32 v7, v0, v1
	s_waitcnt vmcnt(2)
	v_lshlrev_b32_e32 v8, 16, v64
	v_and_b32_e32 v9, 0xffff0000, v64
	v_lshlrev_b32_e32 v0, 16, v65
	v_and_b32_e32 v1, 0xffff0000, v65
	v_pk_mul_f32 v[8:9], v[8:9], s[58:59] op_sel_hi:[1,0]
	v_pk_mul_f32 v[0:1], v[0:1], s[58:59] op_sel_hi:[1,0]
	v_cvt_pk_bf16_f32 v8, v8, v9
	v_cvt_pk_bf16_f32 v9, v0, v1
	v_lshlrev_b32_e32 v0, 16, v66
	v_and_b32_e32 v1, 0xffff0000, v66
	v_pk_mul_f32 v[0:1], v[0:1], s[58:59] op_sel_hi:[1,0]
	s_nop 0
	v_cvt_pk_bf16_f32 v10, v0, v1
	v_lshlrev_b32_e32 v0, 16, v67
	v_and_b32_e32 v1, 0xffff0000, v67
	v_pk_mul_f32 v[0:1], v[0:1], s[58:59] op_sel_hi:[1,0]
	s_nop 0
	v_cvt_pk_bf16_f32 v11, v0, v1
	s_waitcnt vmcnt(1)
	v_lshlrev_b32_e32 v12, 16, v68
	v_and_b32_e32 v13, 0xffff0000, v68
	v_lshlrev_b32_e32 v0, 16, v69
	v_and_b32_e32 v1, 0xffff0000, v69
	v_pk_mul_f32 v[12:13], v[12:13], s[58:59] op_sel_hi:[1,0]
	v_pk_mul_f32 v[0:1], v[0:1], s[58:59] op_sel_hi:[1,0]
	v_cvt_pk_bf16_f32 v12, v12, v13
	v_cvt_pk_bf16_f32 v13, v0, v1
	v_lshlrev_b32_e32 v0, 16, v70
	v_and_b32_e32 v1, 0xffff0000, v70
	v_pk_mul_f32 v[0:1], v[0:1], s[58:59] op_sel_hi:[1,0]
	s_nop 0
	v_cvt_pk_bf16_f32 v14, v0, v1
	v_lshlrev_b32_e32 v0, 16, v71
	v_and_b32_e32 v1, 0xffff0000, v71
	v_pk_mul_f32 v[0:1], v[0:1], s[58:59] op_sel_hi:[1,0]
	s_nop 0
	v_cvt_pk_bf16_f32 v15, v0, v1
	s_waitcnt vmcnt(0)
	v_lshlrev_b32_e32 v16, 16, v76
	v_and_b32_e32 v17, 0xffff0000, v76
	v_pk_mul_f32 v[16:17], v[16:17], s[58:59] op_sel_hi:[1,0]
	s_nop 0
	v_cvt_pk_bf16_f32 v0, v16, v17
	v_lshlrev_b32_e32 v16, 16, v77
	v_and_b32_e32 v17, 0xffff0000, v77
	v_pk_mul_f32 v[16:17], v[16:17], s[58:59] op_sel_hi:[1,0]
	s_nop 0
	v_cvt_pk_bf16_f32 v1, v16, v17
	v_lshlrev_b32_e32 v16, 16, v78
	v_and_b32_e32 v17, 0xffff0000, v78
	v_pk_mul_f32 v[16:17], v[16:17], s[58:59] op_sel_hi:[1,0]
	s_nop 0
	v_cvt_pk_bf16_f32 v2, v16, v17
	v_lshlrev_b32_e32 v16, 16, v79
	v_and_b32_e32 v17, 0xffff0000, v79
	v_pk_mul_f32 v[16:17], v[16:17], s[58:59] op_sel_hi:[1,0]
	s_nop 0
	v_cvt_pk_bf16_f32 v3, v16, v17
	s_mov_b64 s[22:23], 0x6000000
	v_add_u32_e32 v16, s0, v155
	s_sub_i32 s22, 0x80, s76
	s_nop 0
	v_med3_i32 v16, v16, 0, s75
	v_cmp_lt_i32_e32 vcc, -1, v20
	s_nop 1
	v_cndmask_b32_e32 v20, 0, v21, vcc
	v_cmp_lt_i32_e32 vcc, -1, v24
	s_nop 1
	v_cndmask_b32_e32 v24, 0, v25, vcc
	v_cmp_lt_i32_e32 vcc, -1, v28
	s_nop 1
	v_cndmask_b32_e32 v28, 0, v29, vcc
	v_lshl_add_u32 v16, v16, 9, v152
	global_load_dwordx4 v[16:19], v16, s[98:99]
	v_lshl_add_u32 v20, v20, 9, v152
	v_cmp_lt_i32_e32 vcc, -1, v40
	global_load_dwordx4 v[20:23], v20, s[98:99]
	v_lshl_add_u32 v24, v24, 9, v152
	v_cndmask_b32_e32 v32, 0, v32, vcc
	v_cmp_lt_i32_e32 vcc, s1, v40
	global_load_dwordx4 v[24:27], v24, s[98:99]
	v_lshl_add_u32 v28, v28, 9, v152
	v_cndmask_b32_e32 v40, 0, v41, vcc
	global_load_dwordx4 v[28:31], v28, s[98:99]
	v_lshl_add_u32 v36, v32, 9, v158
	v_lshl_add_u32 v40, v40, 9, v158
	s_sub_i32 s1, s76, 32
	global_load_dwordx4 v[32:35], v36, s[100:101]
	global_load_dwordx4 v[36:39], v36, s[100:101] offset:64
	global_load_dwordx4 v[48:51], v40, s[100:101]
	global_load_dwordx4 v[52:55], v40, s[100:101] offset:64
	v_add_u32_e32 v40, s1, v155
	v_med3_i32 v40, v40, 0, s75
	v_lshl_add_u32 v40, v40, 9, v152
	global_load_dwordx4 v[76:79], v40, s[98:99]
	v_add_u32_e32 v40, s1, v172
	v_med3_i32 v40, v40, 0, s75
	v_lshl_add_u32 v40, v40, 9, v152
	global_load_dwordx4 v[84:87], v40, s[98:99]
	v_add_u32_e32 v40, s1, v173
	v_med3_i32 v40, v40, 0, s75
	v_lshl_add_u32 v40, v40, 9, v152
	global_load_dwordx4 v[88:91], v40, s[98:99]
	v_add_u32_e32 v40, s1, v182
	s_min_i32 s1, s0, 0
	s_sub_i32 s1, 0, s1
	v_med3_i32 v40, v40, 0, s75
	v_lshl_add_u32 v40, v40, 9, v152
	global_load_dwordx4 v[92:95], v40, s[98:99]
	v_min_i32_e32 v40, s75, v56
	v_cmp_lt_i32_e32 vcc, -1, v56
	v_add_u32_e32 v56, 16, v56
	s_nop 0
	v_cndmask_b32_e32 v40, 0, v40, vcc
	v_med3_i32 v56, v56, 0, s75
	v_lshl_add_u32 v44, v40, 9, v158
	v_lshl_add_u32 v60, v56, 9, v158
	global_load_dwordx4 v[40:43], v44, s[100:101]
	global_load_dwordx4 v[44:47], v44, s[100:101] offset:64
	global_load_dwordx4 v[56:59], v60, s[100:101]
	global_load_dwordx4 v[60:63], v60, s[100:101] offset:64
	s_waitcnt vmcnt(15)
	ds_write_b128 v241, v[16:19]
	s_waitcnt vmcnt(14)
	ds_write_b128 v242, v[20:23]
	s_waitcnt vmcnt(13)
	ds_write_b128 v243, v[24:27]
	s_waitcnt vmcnt(12)
	ds_write_b128 v244, v[28:31]
	v_or_b32_e32 v24, 16, v166
	v_add_u32_e32 v24, s76, v24
	v_med3_i32 v16, v149, 0, s75
	v_lshl_add_u32 v16, v16, 9, v152
	global_load_dwordx4 v[64:67], v16, s[98:99]
	s_sub_i32 s0, s75, s0
	v_med3_i32 v16, v150, 0, s75
	v_lshl_add_u32 v16, v16, 9, v152
	global_load_dwordx4 v[68:71], v16, s[98:99]
	v_max_i32_e32 v147, s1, v250
	v_max_i32_e32 v148, s1, v249
	v_med3_i32 v16, v151, 0, s75
	v_lshl_add_u32 v16, v16, 9, v152
	global_load_dwordx4 v[72:75], v16, s[98:99]
	v_med3_i32 v16, v252, 0, s75
	v_lshl_add_u32 v16, v16, 9, v152
	global_load_dwordx4 v[80:83], v16, s[98:99]
	v_add_u32_e32 v16, s76, v166
	v_med3_i32 v16, v16, 0, s75
	v_med3_i32 v24, v24, 0, s75
	v_lshl_add_u32 v20, v16, 9, v158
	v_lshl_add_u32 v28, v24, 9, v158
	global_load_dwordx4 v[16:19], v20, s[100:101]
	global_load_dwordx4 v[20:23], v20, s[100:101] offset:64
	global_load_dwordx4 v[24:27], v28, s[100:101]
	global_load_dwordx4 v[28:31], v28, s[100:101] offset:64
	ds_read_b64_tr_b16 v[98:99], v169 offset:2304
	ds_read_b64_tr_b16 v[96:97], v169
	ds_read_b64_tr_b16 v[100:101], v169 offset:32
	ds_read_b64_tr_b16 v[102:103], v169 offset:2336
	ds_read_b64_tr_b16 v[116:117], v169 offset:64
	ds_read_b64_tr_b16 v[118:119], v169 offset:2368
	ds_read_b64_tr_b16 v[134:135], v169 offset:96
	ds_read_b64_tr_b16 v[136:137], v169 offset:2400
	s_waitcnt vmcnt(15)
	ds_write_b128 v241, v[76:79] offset:4608
	s_waitcnt vmcnt(14)
	ds_write_b128 v242, v[84:87] offset:4608
	s_waitcnt vmcnt(13)
	ds_write_b128 v243, v[88:91] offset:4608
	s_waitcnt vmcnt(12)
	ds_write_b128 v244, v[92:95] offset:4608
	v_mfma_f32_16x16x32_bf16 v[76:79], v[32:35], v[4:7], 0
	v_mfma_f32_16x16x32_bf16 v[32:35], v[32:35], v[12:15], 0
	v_mfma_f32_16x16x32_bf16 v[76:79], v[36:39], v[8:11], v[76:79]
	v_mfma_f32_16x16x32_bf16 v[84:87], v[48:51], v[4:7], 0
	v_mfma_f32_16x16x32_bf16 v[32:35], v[36:39], v[0:3], v[32:35]
	v_mfma_f32_16x16x32_bf16 v[36:39], v[48:51], v[12:15], 0
	v_add_u32_e32 v48, s22, v251
	v_min3_i32 v48, v48, s0, v245
	v_sub_u32_e32 v49, v154, v147
	v_sub_u32_e32 v146, v48, v147
	v_add_u32_e32 v48, s22, v144
	v_min3_i32 v48, v48, s0, v245
	v_add_u32_e32 v51, 1, v49
	v_sub_u32_e32 v145, v48, v148
	v_cmp_gt_u32_e64 s[0:1], v51, v146
	v_cmp_gt_u32_e32 vcc, v49, v146
	s_nop 0
	v_cndmask_b32_e64 v77, v77, v246, s[0:1]
	s_nop 0
	v_cndmask_b32_e32 v76, v76, v246, vcc
	v_mfma_f32_16x16x32_bf16 v[84:87], v[52:55], v[8:11], v[84:87]
	v_max_f32_e32 v48, v76, v77
	v_add_u32_e32 v51, 2, v49
	v_cmp_gt_u32_e64 s[22:23], v51, v146
	v_mfma_f32_16x16x32_bf16 v[36:39], v[52:55], v[0:3], v[36:39]
	v_add_u32_e32 v52, 3, v49
	v_cmp_gt_u32_e64 s[24:25], v52, v146
	v_cndmask_b32_e64 v78, v78, v246, s[22:23]
	v_sub_u32_e32 v50, v154, v148
	v_cndmask_b32_e64 v79, v79, v246, s[24:25]
	v_max3_f32 v48, v48, v78, v79
	v_add_u32_e32 v51, 16, v49
	v_add_u32_e32 v52, 17, v49
	v_cmp_gt_u32_e64 s[26:27], v51, v146
	v_cmp_gt_u32_e64 s[28:29], v52, v146
	v_cmp_gt_u32_e64 s[38:39], v50, v145
	v_cndmask_b32_e64 v84, v84, v246, s[26:27]
	v_cndmask_b32_e64 v85, v85, v246, s[28:29]
	v_max3_f32 v48, v48, v84, v85
	v_add_u32_e32 v51, 18, v49
	v_add_u32_e32 v49, 19, v49
	v_cmp_gt_u32_e64 s[30:31], v51, v146
	v_cmp_gt_u32_e64 s[34:35], v49, v146
	v_add_u32_e32 v52, 3, v50
	v_cndmask_b32_e64 v86, v86, v246, s[30:31]
	v_cndmask_b32_e64 v87, v87, v246, s[34:35]
	v_max3_f32 v48, v48, v86, v87
	v_add_u32_e32 v51, 1, v50
	v_cmp_gt_u32_e64 s[40:41], v51, v145
	v_cndmask_b32_e64 v32, v32, v246, s[38:39]
	s_nop 0
	v_cndmask_b32_e64 v33, v33, v246, s[40:41]
	v_max_f32_e32 v49, v32, v33
	v_add_u32_e32 v51, 2, v50
	v_cmp_gt_u32_e64 s[42:43], v51, v145
	v_cmp_gt_u32_e64 s[44:45], v52, v145
	s_nop 0
	v_cndmask_b32_e64 v34, v34, v246, s[42:43]
	v_cndmask_b32_e64 v35, v35, v246, s[44:45]
	v_max3_f32 v49, v49, v34, v35
	v_add_u32_e32 v51, 16, v50
	v_add_u32_e32 v52, 17, v50
	v_cmp_gt_u32_e64 s[46:47], v51, v145
	v_cmp_gt_u32_e64 s[48:49], v52, v145
	s_nop 0
	v_cndmask_b32_e64 v36, v36, v246, s[46:47]
	v_cndmask_b32_e64 v37, v37, v246, s[48:49]
	v_max3_f32 v49, v49, v36, v37
	v_add_u32_e32 v51, 18, v50
	v_add_u32_e32 v50, 19, v50
	v_cmp_gt_u32_e64 s[50:51], v51, v145
	v_cmp_gt_u32_e64 s[52:53], v50, v145
	s_nop 0
	v_cndmask_b32_e64 v38, v38, v246, s[50:51]
	v_cndmask_b32_e64 v39, v39, v246, s[52:53]
	v_max3_f32 v49, v49, v38, v39
	v_mov_b32_e32 v50, v48
	s_nop 1
	v_permlane32_swap_b32_e32 v50, v48
	v_max_f32_e32 v48, v48, v50
	v_mov_b32_e32 v50, v49
	s_nop 1
	v_permlane32_swap_b32_e32 v50, v49
	v_max_f32_e32 v49, v49, v50
	v_mov_b32_e32 v50, v48
	s_nop 1
	v_permlane16_swap_b32_e32 v50, v48
	v_max_f32_e32 v48, v48, v50
	v_mov_b32_e32 v50, v49
	s_nop 1
	v_permlane16_swap_b32_e32 v50, v49
	v_max_f32_e32 v129, s73, v48
	v_sub_f32_e32 v48, 0xf149f2ca, v129
	v_max_f32_e32 v49, v49, v50
	v_exp_f32_e32 v50, v48
	v_sub_f32_e32 v48, v76, v129
	v_exp_f32_e32 v48, v48
	v_sub_f32_e32 v52, v77, v129
	v_max_f32_e32 v131, s73, v49
	v_exp_f32_e32 v52, v52
	v_sub_f32_e32 v36, v36, v131
	v_sub_f32_e32 v53, v78, v129
	v_exp_f32_e32 v36, v36
	v_exp_f32_e32 v53, v53
	v_sub_f32_e32 v54, v79, v129
	v_cndmask_b32_e64 v51, v48, 0, vcc
	v_exp_f32_e32 v54, v54
	v_sub_f32_e32 v55, v84, v129
	v_exp_f32_e32 v55, v55
	v_sub_f32_e32 v76, v85, v129
	v_add_f32_e32 v48, v52, v51
	v_exp_f32_e32 v76, v76
	v_sub_f32_e32 v77, v86, v129
	v_cvt_pk_bf16_f32 v52, v51, v52
	v_cndmask_b32_e64 v51, v36, 0, s[46:47]
	v_sub_f32_e32 v36, v37, v131
	v_exp_f32_e32 v77, v77
	v_sub_f32_e32 v78, v87, v129
	v_exp_f32_e32 v36, v36
	v_add_f32_e32 v48, v53, v48
	v_exp_f32_e32 v78, v78
	v_add_f32_e32 v48, v54, v48
	v_sub_f32_e32 v32, v32, v131
	v_add_f32_e32 v48, v55, v48
	v_exp_f32_e32 v32, v32
	v_sub_f32_e32 v33, v33, v131
	v_add_f32_e32 v48, v76, v48
	v_cvt_pk_bf16_f32 v53, v53, v54
	v_cvt_pk_bf16_f32 v54, v55, v76
	v_exp_f32_e32 v33, v33
	v_sub_f32_e32 v34, v34, v131
	v_cndmask_b32_e64 v76, v36, 0, s[48:49]
	v_sub_f32_e32 v36, v38, v131
	v_add_f32_e32 v48, v77, v48
	v_exp_f32_e32 v34, v34
	v_sub_f32_e32 v35, v35, v131
	v_exp_f32_e32 v36, v36
	v_add_f32_e32 v130, v78, v48
	v_exp_f32_e32 v35, v35
	v_mul_f32_e32 v48, 0, v50
	v_fmac_f32_e32 v130, 0, v50
	v_cndmask_b32_e64 v50, v32, 0, s[38:39]
	v_cvt_pk_bf16_f32 v55, v77, v78
	v_add_f32_e32 v32, v33, v50
	v_cndmask_b32_e64 v77, v36, 0, s[50:51]
	v_sub_f32_e32 v36, v39, v131
	v_sub_f32_e32 v49, 0xf149f2ca, v131
	v_add_f32_e32 v32, v34, v32
	v_exp_f32_e32 v36, v36
	v_exp_f32_e32 v49, v49
	v_add_f32_e32 v32, v35, v32
	v_add_f32_e32 v32, v51, v32
	v_add_f32_e32 v32, v76, v32
	v_add_f32_e32 v32, v77, v32
	v_cndmask_b32_e64 v39, v36, 0, s[52:53]
	v_add_f32_e32 v132, v39, v32
	v_mul_f32_e32 v32, 0, v49
	v_fmac_f32_e32 v132, 0, v49
	v_cvt_pk_bf16_f32 v36, v50, v33
	v_cvt_pk_bf16_f32 v37, v34, v35
	v_cvt_pk_bf16_f32 v38, v51, v76
	v_cvt_pk_bf16_f32 v39, v77, v39
	v_mov_b32_e32 v49, v48
	v_mov_b32_e32 v50, v48
	v_mov_b32_e32 v51, v48
	v_mov_b32_e32 v33, v32
	v_mov_b32_e32 v34, v32
	v_mov_b32_e32 v35, v32
	s_waitcnt lgkmcnt(6)
	v_mfma_f32_16x16x32_bf16 v[112:115], v[116:119], v[52:55], v[48:51]
	v_mfma_f32_16x16x32_bf16 v[124:127], v[96:99], v[36:39], v[32:35]
	v_mfma_f32_16x16x32_bf16 v[108:111], v[100:103], v[36:39], v[32:35]
	v_mfma_f32_16x16x32_bf16 v[116:119], v[116:119], v[36:39], v[32:35]
	s_waitcnt lgkmcnt(4)
	v_mfma_f32_16x16x32_bf16 v[88:91], v[134:137], v[36:39], v[32:35]
	s_nop 2
	v_add_u32_e32 v32, 32, v155
	v_add_u32_e32 v32, s76, v32
	v_mfma_f32_16x16x32_bf16 v[120:123], v[96:99], v[52:55], v[48:51]
	s_nop 0
	v_med3_i32 v32, v32, 0, s75
	v_lshl_add_u32 v32, v32, 9, v152
	global_load_dwordx4 v[76:79], v32, s[98:99]
	v_add_u32_e32 v32, 32, v172
	v_add_u32_e32 v32, s76, v32
	v_mfma_f32_16x16x32_bf16 v[104:107], v[100:103], v[52:55], v[48:51]
	s_nop 0
	v_med3_i32 v32, v32, 0, s75
	v_lshl_add_u32 v32, v32, 9, v152
	global_load_dwordx4 v[84:87], v32, s[98:99]
	v_add_u32_e32 v32, 32, v173
	v_add_u32_e32 v32, s76, v32
	v_mfma_f32_16x16x32_bf16 v[96:99], v[134:137], v[52:55], v[48:51]
	s_nop 0
	v_med3_i32 v32, v32, 0, s75
	v_lshl_add_u32 v32, v32, 9, v152
	global_load_dwordx4 v[92:95], v32, s[98:99]
	v_add_u32_e32 v32, 32, v182
	v_add_u32_e32 v32, s76, v32
	v_or_b32_e32 v48, 48, v166
	v_add_u32_e32 v48, s76, v48
	v_med3_i32 v32, v32, 0, s75
	v_lshl_add_u32 v32, v32, 9, v152
	global_load_dwordx4 v[100:103], v32, s[98:99]
	v_add_u32_e32 v32, s76, v128
	s_nop 0
	v_med3_i32 v32, v32, 0, s75
	v_med3_i32 v48, v48, 0, s75
	v_lshl_add_u32 v36, v32, 9, v158
	v_lshl_add_u32 v52, v48, 9, v158
	global_load_dwordx4 v[32:35], v36, s[100:101]
	global_load_dwordx4 v[36:39], v36, s[100:101] offset:64
	global_load_dwordx4 v[48:51], v52, s[100:101]
	global_load_dwordx4 v[52:55], v52, s[100:101] offset:64
	ds_read_b64_tr_b16 v[136:137], v169 offset:6912
	ds_read_b64_tr_b16 v[134:135], v169 offset:4608
	ds_read_b64_tr_b16 v[138:139], v169 offset:4640
	ds_read_b64_tr_b16 v[140:141], v169 offset:6944
	ds_read_b64_tr_b16 v[176:177], v169 offset:4672
	ds_read_b64_tr_b16 v[178:179], v169 offset:6976
	ds_read_b64_tr_b16 v[188:189], v169 offset:4704
	ds_read_b64_tr_b16 v[190:191], v169 offset:7008
	s_waitcnt vmcnt(15)
	ds_write_b128 v241, v[64:67]
	s_waitcnt vmcnt(14)
	ds_write_b128 v242, v[68:71]
	s_waitcnt vmcnt(13)
	ds_write_b128 v243, v[72:75]
	s_waitcnt vmcnt(12)
	ds_write_b128 v244, v[80:83]
	v_mfma_f32_16x16x32_bf16 v[64:67], v[40:43], v[4:7], 0
	v_mfma_f32_16x16x32_bf16 v[40:43], v[40:43], v[12:15], 0
	v_mfma_f32_16x16x32_bf16 v[64:67], v[44:47], v[8:11], v[64:67]
	v_mfma_f32_16x16x32_bf16 v[68:71], v[56:59], v[4:7], 0
	v_mfma_f32_16x16x32_bf16 v[40:43], v[44:47], v[0:3], v[40:43]
	v_mfma_f32_16x16x32_bf16 v[44:47], v[56:59], v[12:15], 0
	v_sub_u32_e32 v56, v187, v147
	v_add_u32_e32 v59, 1, v56
	s_nop 2
	v_cmp_gt_u32_e64 s[0:1], v59, v146
	v_cmp_gt_u32_e32 vcc, v56, v146
	s_nop 0
	v_cndmask_b32_e64 v65, v65, v246, s[0:1]
	s_nop 0
	v_cndmask_b32_e32 v64, v64, v246, vcc
	v_mfma_f32_16x16x32_bf16 v[68:71], v[60:63], v[8:11], v[68:71]
	v_max_f32_e32 v58, v64, v65
	v_add_u32_e32 v59, 2, v56
	v_cmp_gt_u32_e64 s[22:23], v59, v146
	v_mfma_f32_16x16x32_bf16 v[44:47], v[60:63], v[0:3], v[44:47]
	v_add_u32_e32 v60, 3, v56
	v_cmp_gt_u32_e64 s[24:25], v60, v146
	v_cndmask_b32_e64 v66, v66, v246, s[22:23]
	v_sub_u32_e32 v57, v187, v148
	v_cndmask_b32_e64 v67, v67, v246, s[24:25]
	v_max3_f32 v58, v58, v66, v67
	v_add_u32_e32 v59, 16, v56
	v_add_u32_e32 v60, 17, v56
	v_cmp_gt_u32_e64 s[26:27], v59, v146
	v_cmp_gt_u32_e64 s[28:29], v60, v146
	v_cmp_gt_u32_e64 s[38:39], v57, v145
	v_cndmask_b32_e64 v68, v68, v246, s[26:27]
	v_cndmask_b32_e64 v69, v69, v246, s[28:29]
	v_max3_f32 v58, v58, v68, v69
	v_add_u32_e32 v59, 18, v56
	v_add_u32_e32 v56, 19, v56
	v_cmp_gt_u32_e64 s[30:31], v59, v146
	v_cmp_gt_u32_e64 s[34:35], v56, v146
	v_add_u32_e32 v60, 3, v57
	v_cndmask_b32_e64 v70, v70, v246, s[30:31]
	v_cndmask_b32_e64 v71, v71, v246, s[34:35]
	v_max3_f32 v56, v58, v70, v71
	v_add_u32_e32 v59, 1, v57
	v_cmp_gt_u32_e64 s[40:41], v59, v145
	v_cndmask_b32_e64 v40, v40, v246, s[38:39]
	s_nop 0
	v_cndmask_b32_e64 v41, v41, v246, s[40:41]
	v_max_f32_e32 v58, v40, v41
	v_add_u32_e32 v59, 2, v57
	v_cmp_gt_u32_e64 s[42:43], v59, v145
	v_cmp_gt_u32_e64 s[44:45], v60, v145
	s_nop 0
	v_cndmask_b32_e64 v42, v42, v246, s[42:43]
	v_cndmask_b32_e64 v43, v43, v246, s[44:45]
	v_max3_f32 v58, v58, v42, v43
	v_add_u32_e32 v59, 16, v57
	v_add_u32_e32 v60, 17, v57
	v_cmp_gt_u32_e64 s[46:47], v59, v145
	v_cmp_gt_u32_e64 s[48:49], v60, v145
	s_nop 0
	v_cndmask_b32_e64 v44, v44, v246, s[46:47]
	v_cndmask_b32_e64 v45, v45, v246, s[48:49]
	v_max3_f32 v58, v58, v44, v45
	v_add_u32_e32 v59, 18, v57
	v_add_u32_e32 v57, 19, v57
	v_cmp_gt_u32_e64 s[50:51], v59, v145
	v_cmp_gt_u32_e64 s[52:53], v57, v145
	s_nop 0
	v_cndmask_b32_e64 v46, v46, v246, s[50:51]
	v_cndmask_b32_e64 v47, v47, v246, s[52:53]
	v_max3_f32 v57, v58, v46, v47
	v_mov_b32_e32 v58, v56
	s_nop 1
	v_permlane32_swap_b32_e32 v58, v56
	v_max_f32_e32 v56, v56, v58
	v_mov_b32_e32 v58, v57
	s_nop 1
	v_permlane32_swap_b32_e32 v58, v57
	v_max_f32_e32 v57, v57, v58
	v_mov_b32_e32 v58, v56
	s_nop 1
	v_permlane16_swap_b32_e32 v58, v56
	v_max_f32_e32 v56, v56, v58
	v_mov_b32_e32 v58, v57
	v_mov_b32_e32 v61, v57
	v_max_f32_e32 v128, v129, v56
	s_nop 0
	v_permlane16_swap_b32_e32 v58, v61
	v_sub_f32_e32 v56, v129, v128
	v_exp_f32_e32 v60, v56
	v_sub_f32_e32 v56, v64, v128
	v_max_f32_e32 v62, v57, v58
	v_exp_f32_e32 v56, v56
	v_sub_f32_e32 v58, v65, v128
	v_exp_f32_e32 v58, v58
	v_sub_f32_e32 v59, v66, v128
	v_exp_f32_e32 v59, v59
	v_sub_f32_e32 v63, v67, v128
	v_exp_f32_e32 v63, v63
	v_sub_f32_e32 v64, v68, v128
	v_exp_f32_e32 v64, v64
	v_sub_f32_e32 v65, v69, v128
	v_exp_f32_e32 v65, v65
	v_sub_f32_e32 v66, v70, v128
	v_add_f32_e32 v57, v58, v56
	v_exp_f32_e32 v66, v66
	v_sub_f32_e32 v67, v71, v128
	v_add_f32_e32 v57, v59, v57
	v_exp_f32_e32 v67, v67
	v_add_f32_e32 v57, v63, v57
	v_add_f32_e32 v57, v64, v57
	v_add_f32_e32 v57, v65, v57
	v_add_f32_e32 v57, v66, v57
	v_add_f32_e32 v129, v67, v57
	v_fmac_f32_e32 v129, v130, v60
	v_max3_f32 v130, v131, v62, v61
	v_sub_f32_e32 v40, v40, v130
	v_exp_f32_e32 v40, v40
	v_sub_f32_e32 v41, v41, v130
	v_exp_f32_e32 v41, v41
	v_sub_f32_e32 v42, v42, v130
	v_exp_f32_e32 v42, v42
	v_sub_f32_e32 v43, v43, v130
	v_exp_f32_e32 v43, v43
	v_sub_f32_e32 v44, v44, v130
	v_sub_f32_e32 v61, v131, v130
	v_exp_f32_e32 v44, v44
	v_sub_f32_e32 v45, v45, v130
	v_exp_f32_e32 v62, v61
	v_exp_f32_e32 v45, v45
	v_sub_f32_e32 v46, v46, v130
	v_add_f32_e32 v61, v41, v40
	v_exp_f32_e32 v46, v46
	v_sub_f32_e32 v47, v47, v130
	v_add_f32_e32 v61, v42, v61
	v_exp_f32_e32 v47, v47
	v_add_f32_e32 v61, v43, v61
	v_add_f32_e32 v61, v44, v61
	v_add_f32_e32 v61, v45, v61
	v_add_f32_e32 v61, v46, v61
	v_cvt_pk_bf16_f32 v56, v56, v58
	v_cvt_pk_bf16_f32 v57, v59, v63
	v_cvt_pk_bf16_f32 v58, v64, v65
	v_cvt_pk_bf16_f32 v59, v66, v67
	v_add_f32_e32 v131, v47, v61
	v_cvt_pk_bf16_f32 v40, v40, v41
	v_cvt_pk_bf16_f32 v41, v42, v43
	v_cvt_pk_bf16_f32 v42, v44, v45
	v_cvt_pk_bf16_f32 v43, v46, v47
	v_pk_mul_f32 v[46:47], v[122:123], v[60:61] op_sel_hi:[1,0]
	v_pk_mul_f32 v[44:45], v[120:121], v[60:61] op_sel_hi:[1,0]
	v_fmac_f32_e32 v131, v132, v62
	s_waitcnt lgkmcnt(10)
	v_mfma_f32_16x16x32_bf16 v[64:67], v[134:137], v[56:59], v[44:47]
	s_nop 2
	v_mul_f32_e64 v46, v126, v62
	v_mul_f32_e64 v47, v127, v62
	v_pk_mul_f32 v[44:45], v[124:125], v[62:63] op_sel_hi:[1,0]
	s_nop 1
	v_mfma_f32_16x16x32_bf16 v[68:71], v[134:137], v[40:43], v[44:47]
	s_nop 2
	v_mul_f32_e64 v46, v106, v60
	v_mul_f32_e64 v47, v107, v60
	v_pk_mul_f32 v[44:45], v[104:105], v[60:61] op_sel_hi:[1,0]
	s_waitcnt lgkmcnt(8)
	s_nop 0
	v_mfma_f32_16x16x32_bf16 v[104:107], v[138:141], v[56:59], v[44:47]
	s_nop 2
	v_mul_f32_e64 v46, v110, v62
	v_mul_f32_e64 v47, v111, v62
	v_pk_mul_f32 v[44:45], v[108:109], v[62:63] op_sel_hi:[1,0]
	s_nop 1
	v_mfma_f32_16x16x32_bf16 v[108:111], v[138:141], v[40:43], v[44:47]
	s_nop 2
	v_mul_f32_e64 v46, v114, v60
	v_mul_f32_e64 v47, v115, v60
	v_pk_mul_f32 v[44:45], v[112:113], v[60:61] op_sel_hi:[1,0]
	s_waitcnt lgkmcnt(6)
	s_nop 0
	v_mfma_f32_16x16x32_bf16 v[112:115], v[176:179], v[56:59], v[44:47]
	s_nop 2
	v_mul_f32_e64 v46, v118, v62
	v_mul_f32_e64 v47, v119, v62
	v_pk_mul_f32 v[44:45], v[116:117], v[62:63] op_sel_hi:[1,0]
	s_nop 1
	v_mfma_f32_16x16x32_bf16 v[116:119], v[176:179], v[40:43], v[44:47]
	s_nop 2
	v_mul_f32_e64 v46, v98, v60
	v_mul_f32_e64 v47, v99, v60
	v_pk_mul_f32 v[44:45], v[96:97], v[60:61] op_sel_hi:[1,0]
	s_waitcnt lgkmcnt(4)
	s_nop 0
	v_mfma_f32_16x16x32_bf16 v[120:123], v[188:191], v[56:59], v[44:47]
	v_or_b32_e32 v56, 0x50, v166
	v_add_u32_e32 v56, s76, v56
	s_nop 0
	v_pk_mul_f32 v[46:47], v[90:91], v[62:63] op_sel_hi:[1,0]
	v_pk_mul_f32 v[44:45], v[88:89], v[62:63] op_sel_hi:[1,0]
	s_nop 1
	v_mfma_f32_16x16x32_bf16 v[124:127], v[188:191], v[40:43], v[44:47]
	v_add_u32_e32 v40, 64, v155
	v_add_u32_e32 v40, s76, v40
	v_med3_i32 v40, v40, 0, s75
	v_lshl_add_u32 v40, v40, 9, v152
	global_load_dwordx4 v[72:75], v40, s[98:99]
	v_add_u32_e32 v40, 64, v172
	v_add_u32_e32 v40, s76, v40
	v_med3_i32 v40, v40, 0, s75
	v_lshl_add_u32 v40, v40, 9, v152
	global_load_dwordx4 v[80:83], v40, s[98:99]
	v_add_u32_e32 v40, 64, v173
	v_add_u32_e32 v40, s76, v40
	v_med3_i32 v40, v40, 0, s75
	v_lshl_add_u32 v40, v40, 9, v152
	global_load_dwordx4 v[88:91], v40, s[98:99]
	v_add_u32_e32 v40, 64, v182
	v_add_u32_e32 v40, s76, v40
	v_med3_i32 v40, v40, 0, s75
	v_lshl_add_u32 v40, v40, 9, v152
	global_load_dwordx4 v[96:99], v40, s[98:99]
	v_or_b32_e32 v40, 64, v166
	v_add_u32_e32 v40, s76, v40
	v_med3_i32 v40, v40, 0, s75
	v_med3_i32 v56, v56, 0, s75
	v_lshl_add_u32 v44, v40, 9, v158
	v_lshl_add_u32 v60, v56, 9, v158
	global_load_dwordx4 v[40:43], v44, s[100:101]
	global_load_dwordx4 v[44:47], v44, s[100:101] offset:64
	global_load_dwordx4 v[56:59], v60, s[100:101]
	global_load_dwordx4 v[60:63], v60, s[100:101] offset:64
	ds_read_b64_tr_b16 v[136:137], v169 offset:2304
	ds_read_b64_tr_b16 v[134:135], v169
	ds_read_b64_tr_b16 v[138:139], v169 offset:32
	ds_read_b64_tr_b16 v[140:141], v169 offset:2336
	ds_read_b64_tr_b16 v[176:177], v169 offset:64
	ds_read_b64_tr_b16 v[178:179], v169 offset:2368
	ds_read_b64_tr_b16 v[188:189], v169 offset:96
	ds_read_b64_tr_b16 v[190:191], v169 offset:2400
	s_waitcnt vmcnt(15)
	ds_write_b128 v241, v[76:79] offset:4608
	s_waitcnt vmcnt(14)
	ds_write_b128 v242, v[84:87] offset:4608
	s_waitcnt vmcnt(13)
	ds_write_b128 v243, v[92:95] offset:4608
	s_waitcnt vmcnt(12)
	ds_write_b128 v244, v[100:103] offset:4608
	v_mfma_f32_16x16x32_bf16 v[76:79], v[16:19], v[4:7], 0
	v_mfma_f32_16x16x32_bf16 v[16:19], v[16:19], v[12:15], 0
	v_mfma_f32_16x16x32_bf16 v[76:79], v[20:23], v[8:11], v[76:79]
	v_mfma_f32_16x16x32_bf16 v[84:87], v[24:27], v[4:7], 0
	v_mfma_f32_16x16x32_bf16 v[16:19], v[20:23], v[0:3], v[16:19]
	v_mfma_f32_16x16x32_bf16 v[20:23], v[24:27], v[12:15], 0
	v_sub_u32_e32 v24, v192, v147
	v_add_u32_e32 v27, 1, v24
	s_nop 2
	v_cmp_gt_u32_e64 s[0:1], v27, v146
	v_cmp_gt_u32_e32 vcc, v24, v146
	s_nop 0
	v_cndmask_b32_e64 v77, v77, v246, s[0:1]
	s_nop 0
	v_cndmask_b32_e32 v76, v76, v246, vcc
	v_mfma_f32_16x16x32_bf16 v[84:87], v[28:31], v[8:11], v[84:87]
	v_max_f32_e32 v26, v76, v77
	v_add_u32_e32 v27, 2, v24
	v_cmp_gt_u32_e64 s[22:23], v27, v146
	v_mfma_f32_16x16x32_bf16 v[20:23], v[28:31], v[0:3], v[20:23]
	v_add_u32_e32 v28, 3, v24
	v_cmp_gt_u32_e64 s[24:25], v28, v146
	v_cndmask_b32_e64 v78, v78, v246, s[22:23]
	v_sub_u32_e32 v25, v192, v148
	v_cndmask_b32_e64 v79, v79, v246, s[24:25]
	v_max3_f32 v26, v26, v78, v79
	v_add_u32_e32 v27, 16, v24
	v_add_u32_e32 v28, 17, v24
	v_cmp_gt_u32_e64 s[26:27], v27, v146
	v_cmp_gt_u32_e64 s[28:29], v28, v146
	v_cmp_gt_u32_e64 s[38:39], v25, v145
	v_cndmask_b32_e64 v84, v84, v246, s[26:27]
	v_cndmask_b32_e64 v85, v85, v246, s[28:29]
	v_max3_f32 v26, v26, v84, v85
	v_add_u32_e32 v27, 18, v24
	v_add_u32_e32 v24, 19, v24
	v_cmp_gt_u32_e64 s[30:31], v27, v146
	v_cmp_gt_u32_e64 s[34:35], v24, v146
	v_add_u32_e32 v28, 3, v25
	v_cndmask_b32_e64 v86, v86, v246, s[30:31]
	v_cndmask_b32_e64 v87, v87, v246, s[34:35]
	v_max3_f32 v24, v26, v86, v87
	v_add_u32_e32 v27, 1, v25
	v_cmp_gt_u32_e64 s[40:41], v27, v145
	v_cndmask_b32_e64 v16, v16, v246, s[38:39]
	s_nop 0
	v_cndmask_b32_e64 v17, v17, v246, s[40:41]
	v_max_f32_e32 v26, v16, v17
	v_add_u32_e32 v27, 2, v25
	v_cmp_gt_u32_e64 s[42:43], v27, v145
	v_cmp_gt_u32_e64 s[44:45], v28, v145
	s_nop 0
	v_cndmask_b32_e64 v18, v18, v246, s[42:43]
	v_cndmask_b32_e64 v19, v19, v246, s[44:45]
	v_max3_f32 v26, v26, v18, v19
	v_add_u32_e32 v27, 16, v25
	v_add_u32_e32 v28, 17, v25
	v_cmp_gt_u32_e64 s[46:47], v27, v145
	v_cmp_gt_u32_e64 s[48:49], v28, v145
	s_nop 0
	v_cndmask_b32_e64 v20, v20, v246, s[46:47]
	v_cndmask_b32_e64 v21, v21, v246, s[48:49]
	v_max3_f32 v26, v26, v20, v21
	v_add_u32_e32 v27, 18, v25
	v_add_u32_e32 v25, 19, v25
	v_cmp_gt_u32_e64 s[50:51], v27, v145
	v_cmp_gt_u32_e64 s[52:53], v25, v145
	s_nop 0
	v_cndmask_b32_e64 v22, v22, v246, s[50:51]
	v_cndmask_b32_e64 v23, v23, v246, s[52:53]
	v_max3_f32 v25, v26, v22, v23
	v_mov_b32_e32 v26, v24
	s_nop 1
	v_permlane32_swap_b32_e32 v26, v24
	v_max_f32_e32 v24, v24, v26
	v_mov_b32_e32 v26, v25
	s_nop 1
	v_permlane32_swap_b32_e32 v26, v25
	v_max_f32_e32 v25, v25, v26
	v_mov_b32_e32 v26, v24
	s_nop 1
	v_permlane16_swap_b32_e32 v26, v24
	v_max_f32_e32 v24, v24, v26
	v_mov_b32_e32 v26, v25
	v_mov_b32_e32 v28, v25
	v_max_f32_e32 v132, v128, v24
	s_nop 0
	v_permlane16_swap_b32_e32 v26, v28
	v_sub_f32_e32 v24, v128, v132
	v_exp_f32_e32 v92, v24
	v_sub_f32_e32 v24, v76, v132
	v_max_f32_e32 v29, v25, v26
	v_exp_f32_e32 v24, v24
	v_sub_f32_e32 v26, v77, v132
	v_exp_f32_e32 v26, v26
	v_sub_f32_e32 v27, v78, v132
	v_exp_f32_e32 v27, v27
	v_sub_f32_e32 v30, v79, v132
	v_exp_f32_e32 v30, v30
	v_sub_f32_e32 v31, v84, v132
	v_exp_f32_e32 v31, v31
	v_sub_f32_e32 v76, v85, v132
	v_exp_f32_e32 v76, v76
	v_sub_f32_e32 v77, v86, v132
	v_add_f32_e32 v25, v26, v24
	v_exp_f32_e32 v77, v77
	v_sub_f32_e32 v78, v87, v132
	v_add_f32_e32 v25, v27, v25
	v_exp_f32_e32 v78, v78
	v_add_f32_e32 v25, v30, v25
	v_add_f32_e32 v25, v31, v25
	v_add_f32_e32 v25, v76, v25
	v_add_f32_e32 v25, v77, v25
	v_add_f32_e32 v128, v78, v25
	v_fmac_f32_e32 v128, v129, v92
	v_max3_f32 v129, v130, v29, v28
	v_sub_f32_e32 v16, v16, v129
	v_exp_f32_e32 v16, v16
	v_sub_f32_e32 v17, v17, v129
	v_exp_f32_e32 v17, v17
	v_sub_f32_e32 v18, v18, v129
	v_exp_f32_e32 v18, v18
	v_sub_f32_e32 v19, v19, v129
	v_exp_f32_e32 v19, v19
	v_sub_f32_e32 v20, v20, v129
	v_sub_f32_e32 v28, v130, v129
	v_exp_f32_e32 v20, v20
	v_sub_f32_e32 v21, v21, v129
	v_cvt_pk_bf16_f32 v24, v24, v26
	v_cvt_pk_bf16_f32 v26, v31, v76
	v_exp_f32_e32 v76, v28
	v_exp_f32_e32 v21, v21
	v_sub_f32_e32 v22, v22, v129
	v_add_f32_e32 v28, v17, v16
	v_exp_f32_e32 v22, v22
	v_sub_f32_e32 v23, v23, v129
	v_add_f32_e32 v28, v18, v28
	v_exp_f32_e32 v23, v23
	v_add_f32_e32 v28, v19, v28
	v_add_f32_e32 v28, v20, v28
	v_add_f32_e32 v28, v21, v28
	v_add_f32_e32 v28, v22, v28
	v_cvt_pk_bf16_f32 v25, v27, v30
	v_cvt_pk_bf16_f32 v27, v77, v78
	v_add_f32_e32 v130, v23, v28
	v_cvt_pk_bf16_f32 v28, v16, v17
	v_cvt_pk_bf16_f32 v29, v18, v19
	v_pk_mul_f32 v[18:19], v[66:67], v[92:93] op_sel_hi:[1,0]
	v_pk_mul_f32 v[16:17], v[64:65], v[92:93] op_sel_hi:[1,0]
	v_pk_mul_f32 v[66:67], v[106:107], v[92:93] op_sel_hi:[1,0]
	v_pk_mul_f32 v[64:65], v[104:105], v[92:93] op_sel_hi:[1,0]
	v_cvt_pk_bf16_f32 v30, v20, v21
	v_cvt_pk_bf16_f32 v31, v22, v23
	s_waitcnt lgkmcnt(8)
	v_mfma_f32_16x16x32_bf16 v[104:107], v[138:141], v[24:27], v[64:67]
	v_fmac_f32_e32 v130, v131, v76
	v_pk_mul_f32 v[22:23], v[70:71], v[76:77] op_sel_hi:[1,0]
	v_pk_mul_f32 v[20:21], v[68:69], v[76:77] op_sel_hi:[1,0]
	v_pk_mul_f32 v[66:67], v[110:111], v[76:77] op_sel_hi:[1,0]
	v_pk_mul_f32 v[64:65], v[108:109], v[76:77] op_sel_hi:[1,0]
	v_mfma_f32_16x16x32_bf16 v[16:19], v[134:137], v[24:27], v[16:19]
	s_nop 0
	v_mfma_f32_16x16x32_bf16 v[108:111], v[138:141], v[28:31], v[64:67]
	s_nop 2
	v_mul_f32_e64 v66, v114, v92
	v_mul_f32_e64 v67, v115, v92
	v_pk_mul_f32 v[64:65], v[112:113], v[92:93] op_sel_hi:[1,0]
	v_mfma_f32_16x16x32_bf16 v[20:23], v[134:137], v[28:31], v[20:23]
	s_waitcnt lgkmcnt(6)
	v_mfma_f32_16x16x32_bf16 v[112:115], v[176:179], v[24:27], v[64:67]
	s_nop 2
	v_mul_f32_e64 v66, v118, v76
	v_mul_f32_e64 v67, v119, v76
	v_pk_mul_f32 v[64:65], v[116:117], v[76:77] op_sel_hi:[1,0]
	s_nop 1
	v_mfma_f32_16x16x32_bf16 v[116:119], v[176:179], v[28:31], v[64:67]
	s_nop 2
	v_mul_f32_e64 v66, v122, v92
	v_mul_f32_e64 v67, v123, v92
	v_pk_mul_f32 v[64:65], v[120:121], v[92:93] op_sel_hi:[1,0]
	s_waitcnt lgkmcnt(4)
	s_nop 0
	v_mfma_f32_16x16x32_bf16 v[120:123], v[188:191], v[24:27], v[64:67]
	v_mul_f32_e64 v26, v126, v76
	v_mul_f32_e64 v27, v127, v76
	v_pk_mul_f32 v[24:25], v[124:125], v[76:77] op_sel_hi:[1,0]
	v_or_b32_e32 v64, 0x70, v166
	s_nop 0
	v_mfma_f32_16x16x32_bf16 v[124:127], v[188:191], v[28:31], v[24:27]
	v_add_u32_e32 v64, s76, v64
	s_nop 0
	s_nop 0
	v_add_u32_e32 v24, s76, v196
	v_med3_i32 v24, v24, 0, s75
	v_lshl_add_u32 v24, v24, 9, v152
	global_load_dwordx4 v[76:79], v24, s[98:99]
	v_add_u32_e32 v24, s76, v168
	v_med3_i32 v24, v24, 0, s75
	v_lshl_add_u32 v24, v24, 9, v152
	global_load_dwordx4 v[84:87], v24, s[98:99]
	v_add_u32_e32 v24, s76, v193
	v_med3_i32 v24, v24, 0, s75
	v_lshl_add_u32 v24, v24, 9, v152
	global_load_dwordx4 v[92:95], v24, s[98:99]
	v_add_u32_e32 v24, s76, v194
	v_med3_i32 v24, v24, 0, s75
	v_lshl_add_u32 v24, v24, 9, v152
	global_load_dwordx4 v[100:103], v24, s[98:99]
	v_or_b32_e32 v24, 0x60, v166
	v_add_u32_e32 v24, s76, v24
	v_med3_i32 v24, v24, 0, s75
	v_med3_i32 v64, v64, 0, s75
	v_lshl_add_u32 v28, v24, 9, v158
	v_lshl_add_u32 v68, v64, 9, v158
	global_load_dwordx4 v[24:27], v28, s[100:101]
	global_load_dwordx4 v[28:31], v28, s[100:101] offset:64
	global_load_dwordx4 v[64:67], v68, s[100:101]
	global_load_dwordx4 v[68:71], v68, s[100:101] offset:64
	ds_read_b64_tr_b16 v[136:137], v169 offset:6912
	ds_read_b64_tr_b16 v[134:135], v169 offset:4608
	ds_read_b64_tr_b16 v[138:139], v169 offset:4640
	ds_read_b64_tr_b16 v[140:141], v169 offset:6944
	ds_read_b64_tr_b16 v[176:177], v169 offset:4672
	ds_read_b64_tr_b16 v[178:179], v169 offset:6976
	ds_read_b64_tr_b16 v[188:189], v169 offset:4704
	ds_read_b64_tr_b16 v[190:191], v169 offset:7008
	s_waitcnt vmcnt(15)
	ds_write_b128 v241, v[72:75]
	s_waitcnt vmcnt(14)
	ds_write_b128 v242, v[80:83]
	s_waitcnt vmcnt(13)
	ds_write_b128 v243, v[88:91]
	s_waitcnt vmcnt(12)
	ds_write_b128 v244, v[96:99]
	v_mfma_f32_16x16x32_bf16 v[72:75], v[32:35], v[4:7], 0
	v_mfma_f32_16x16x32_bf16 v[32:35], v[32:35], v[12:15], 0
	v_mfma_f32_16x16x32_bf16 v[72:75], v[36:39], v[8:11], v[72:75]
	v_mfma_f32_16x16x32_bf16 v[80:83], v[48:51], v[4:7], 0
	v_mfma_f32_16x16x32_bf16 v[32:35], v[36:39], v[0:3], v[32:35]
	v_mfma_f32_16x16x32_bf16 v[36:39], v[48:51], v[12:15], 0
	v_sub_u32_e32 v48, v197, v147
	v_add_u32_e32 v51, 1, v48
	s_nop 2
	v_cmp_gt_u32_e64 s[0:1], v51, v146
	v_cmp_gt_u32_e32 vcc, v48, v146
	s_nop 0
	v_cndmask_b32_e64 v73, v73, v246, s[0:1]
	s_nop 0
	v_cndmask_b32_e32 v72, v72, v246, vcc
	v_mfma_f32_16x16x32_bf16 v[80:83], v[52:55], v[8:11], v[80:83]
	v_max_f32_e32 v50, v72, v73
	v_add_u32_e32 v51, 2, v48
	v_cmp_gt_u32_e64 s[22:23], v51, v146
	v_mfma_f32_16x16x32_bf16 v[36:39], v[52:55], v[0:3], v[36:39]
	v_add_u32_e32 v52, 3, v48
	v_cmp_gt_u32_e64 s[24:25], v52, v146
	v_cndmask_b32_e64 v74, v74, v246, s[22:23]
	v_sub_u32_e32 v49, v197, v148
	v_cndmask_b32_e64 v75, v75, v246, s[24:25]
	v_max3_f32 v50, v50, v74, v75
	v_add_u32_e32 v51, 16, v48
	v_add_u32_e32 v52, 17, v48
	v_cmp_gt_u32_e64 s[26:27], v51, v146
	v_cmp_gt_u32_e64 s[28:29], v52, v146
	v_cmp_gt_u32_e64 s[38:39], v49, v145
	v_cndmask_b32_e64 v80, v80, v246, s[26:27]
	v_cndmask_b32_e64 v81, v81, v246, s[28:29]
	v_max3_f32 v50, v50, v80, v81
	v_add_u32_e32 v51, 18, v48
	v_add_u32_e32 v48, 19, v48
	v_cmp_gt_u32_e64 s[30:31], v51, v146
	v_cmp_gt_u32_e64 s[34:35], v48, v146
	v_add_u32_e32 v52, 3, v49
	v_cndmask_b32_e64 v82, v82, v246, s[30:31]
	v_cndmask_b32_e64 v83, v83, v246, s[34:35]
	v_max3_f32 v48, v50, v82, v83
	v_add_u32_e32 v51, 1, v49
	v_cmp_gt_u32_e64 s[40:41], v51, v145
	v_cndmask_b32_e64 v32, v32, v246, s[38:39]
	s_nop 0
	v_cndmask_b32_e64 v33, v33, v246, s[40:41]
	v_max_f32_e32 v50, v32, v33
	v_add_u32_e32 v51, 2, v49
	v_cmp_gt_u32_e64 s[42:43], v51, v145
	v_cmp_gt_u32_e64 s[44:45], v52, v145
	s_nop 0
	v_cndmask_b32_e64 v34, v34, v246, s[42:43]
	v_cndmask_b32_e64 v35, v35, v246, s[44:45]
	v_max3_f32 v50, v50, v34, v35
	v_add_u32_e32 v51, 16, v49
	v_add_u32_e32 v52, 17, v49
	v_cmp_gt_u32_e64 s[46:47], v51, v145
	v_cmp_gt_u32_e64 s[48:49], v52, v145
	s_nop 0
	v_cndmask_b32_e64 v36, v36, v246, s[46:47]
	v_cndmask_b32_e64 v37, v37, v246, s[48:49]
	v_max3_f32 v50, v50, v36, v37
	v_add_u32_e32 v51, 18, v49
	v_add_u32_e32 v49, 19, v49
	v_cmp_gt_u32_e64 s[50:51], v51, v145
	v_cmp_gt_u32_e64 s[52:53], v49, v145
	s_nop 0
	v_cndmask_b32_e64 v38, v38, v246, s[50:51]
	v_cndmask_b32_e64 v39, v39, v246, s[52:53]
	v_max3_f32 v49, v50, v38, v39
	v_mov_b32_e32 v50, v48
	s_nop 1
	v_permlane32_swap_b32_e32 v50, v48
	v_max_f32_e32 v48, v48, v50
	v_mov_b32_e32 v50, v49
	s_nop 1
	v_permlane32_swap_b32_e32 v50, v49
	v_max_f32_e32 v49, v49, v50
	v_mov_b32_e32 v50, v48
	s_nop 1
	v_permlane16_swap_b32_e32 v50, v48
	v_max_f32_e32 v48, v48, v50
	v_mov_b32_e32 v50, v49
	v_mov_b32_e32 v53, v49
	v_max_f32_e32 v131, v132, v48
	s_nop 0
	v_permlane16_swap_b32_e32 v50, v53
	v_sub_f32_e32 v48, v132, v131
	v_exp_f32_e32 v52, v48
	v_sub_f32_e32 v48, v72, v131
	v_max_f32_e32 v54, v49, v50
	v_exp_f32_e32 v48, v48
	v_sub_f32_e32 v50, v73, v131
	v_exp_f32_e32 v50, v50
	v_sub_f32_e32 v51, v74, v131
	v_exp_f32_e32 v51, v51
	v_sub_f32_e32 v55, v75, v131
	v_exp_f32_e32 v55, v55
	v_sub_f32_e32 v72, v80, v131
	v_exp_f32_e32 v72, v72
	v_sub_f32_e32 v73, v81, v131
	v_exp_f32_e32 v73, v73
	v_sub_f32_e32 v74, v82, v131
	v_add_f32_e32 v49, v50, v48
	v_exp_f32_e32 v74, v74
	v_sub_f32_e32 v75, v83, v131
	v_add_f32_e32 v49, v51, v49
	v_exp_f32_e32 v75, v75
	v_add_f32_e32 v49, v55, v49
	v_add_f32_e32 v49, v72, v49
	v_add_f32_e32 v49, v73, v49
	v_add_f32_e32 v49, v74, v49
	v_add_f32_e32 v132, v75, v49
	v_fmac_f32_e32 v132, v128, v52
	v_max3_f32 v128, v129, v54, v53
	v_sub_f32_e32 v32, v32, v128
	v_exp_f32_e32 v32, v32
	v_sub_f32_e32 v33, v33, v128
	v_exp_f32_e32 v33, v33
	v_sub_f32_e32 v34, v34, v128
	v_exp_f32_e32 v34, v34
	v_sub_f32_e32 v35, v35, v128
	v_exp_f32_e32 v35, v35
	v_sub_f32_e32 v36, v36, v128
	v_sub_f32_e32 v53, v129, v128
	v_exp_f32_e32 v36, v36
	v_sub_f32_e32 v37, v37, v128
	v_exp_f32_e32 v54, v53
	v_exp_f32_e32 v37, v37
	v_add_f32_e32 v53, v33, v32
	v_add_f32_e32 v53, v34, v53
	v_cvt_pk_bf16_f32 v49, v51, v55
	v_add_f32_e32 v53, v35, v53
	v_cndmask_b32_e64 v55, v36, 0, s[46:47]
	v_add_f32_e32 v36, v55, v53
	v_cndmask_b32_e64 v53, v37, 0, s[48:49]
	v_sub_f32_e32 v37, v38, v128
	v_exp_f32_e32 v37, v37
	v_cvt_pk_bf16_f32 v48, v48, v50
	v_cvt_pk_bf16_f32 v50, v72, v73
	v_add_f32_e32 v36, v53, v36
	v_cndmask_b32_e64 v72, v37, 0, s[50:51]
	v_sub_f32_e32 v37, v39, v128
	v_exp_f32_e32 v37, v37
	v_cvt_pk_bf16_f32 v51, v74, v75
	v_add_f32_e32 v36, v72, v36
	v_pk_mul_f32 v[18:19], v[18:19], v[52:53] op_sel_hi:[1,0]
	v_cndmask_b32_e64 v39, v37, 0, s[52:53]
	v_pk_mul_f32 v[16:17], v[16:17], v[52:53] op_sel_hi:[1,0]
	v_add_f32_e32 v129, v39, v36
	v_cvt_pk_bf16_f32 v36, v32, v33
	v_cvt_pk_bf16_f32 v37, v34, v35
	v_cvt_pk_bf16_f32 v38, v55, v53
	v_cvt_pk_bf16_f32 v39, v72, v39
	s_waitcnt lgkmcnt(10)
	v_mfma_f32_16x16x32_bf16 v[32:35], v[134:137], v[48:51], v[16:19]
	v_fmac_f32_e32 v129, v130, v54
	s_nop 1
	v_pk_mul_f32 v[18:19], v[22:23], v[54:55] op_sel_hi:[1,0]
	v_pk_mul_f32 v[16:17], v[20:21], v[54:55] op_sel_hi:[1,0]
	s_nop 1
	v_mfma_f32_16x16x32_bf16 v[96:99], v[134:137], v[36:39], v[16:19]
	s_nop 2
	v_mul_f32_e64 v18, v106, v52
	v_mul_f32_e64 v19, v107, v52
	v_pk_mul_f32 v[16:17], v[104:105], v[52:53] op_sel_hi:[1,0]
	s_waitcnt lgkmcnt(8)
	s_nop 0
	v_mfma_f32_16x16x32_bf16 v[104:107], v[138:141], v[48:51], v[16:19]
	s_nop 2
	v_mul_f32_e64 v18, v110, v54
	v_mul_f32_e64 v19, v111, v54
	v_pk_mul_f32 v[16:17], v[108:109], v[54:55] op_sel_hi:[1,0]
	s_nop 1
	v_mfma_f32_16x16x32_bf16 v[108:111], v[138:141], v[36:39], v[16:19]
	s_nop 2
	v_mul_f32_e64 v18, v114, v52
	v_mul_f32_e64 v19, v115, v52
	v_pk_mul_f32 v[16:17], v[112:113], v[52:53] op_sel_hi:[1,0]
	s_waitcnt lgkmcnt(6)
	s_nop 0
	v_mfma_f32_16x16x32_bf16 v[112:115], v[176:179], v[48:51], v[16:19]
	s_nop 2
	v_mul_f32_e64 v18, v118, v54
	v_mul_f32_e64 v19, v119, v54
	v_pk_mul_f32 v[16:17], v[116:117], v[54:55] op_sel_hi:[1,0]
	s_nop 1
	v_mfma_f32_16x16x32_bf16 v[116:119], v[176:179], v[36:39], v[16:19]
	s_nop 2
	v_mul_f32_e64 v18, v122, v52
	v_mul_f32_e64 v19, v123, v52
	v_pk_mul_f32 v[16:17], v[120:121], v[52:53] op_sel_hi:[1,0]
	s_waitcnt lgkmcnt(4)
	s_nop 0
	v_mfma_f32_16x16x32_bf16 v[120:123], v[188:191], v[48:51], v[16:19]
	v_or_b32_e32 v48, 0x90, v166
	v_add_u32_e32 v48, s76, v48
	s_nop 0
	v_pk_mul_f32 v[18:19], v[126:127], v[54:55] op_sel_hi:[1,0]
	v_pk_mul_f32 v[16:17], v[124:125], v[54:55] op_sel_hi:[1,0]
	s_nop 1
	v_mfma_f32_16x16x32_bf16 v[124:127], v[188:191], v[36:39], v[16:19]
	s_nop 2
	v_add_u32_e32 v16, 0x80, v149
	v_med3_i32 v16, v16, 0, s75
	v_lshl_add_u32 v16, v16, 9, v152
	global_load_dwordx4 v[36:39], v16, s[98:99]
	v_add_u32_e32 v16, 0x80, v150
	v_med3_i32 v16, v16, 0, s75
	v_lshl_add_u32 v16, v16, 9, v152
	global_load_dwordx4 v[72:75], v16, s[98:99]
	v_add_u32_e32 v16, 0x80, v151
	v_med3_i32 v16, v16, 0, s75
	v_lshl_add_u32 v16, v16, 9, v152
	global_load_dwordx4 v[80:83], v16, s[98:99]
	v_add_u32_e32 v16, 0x80, v252
	v_med3_i32 v16, v16, 0, s75
	v_lshl_add_u32 v16, v16, 9, v152
	global_load_dwordx4 v[88:91], v16, s[98:99]
	v_or_b32_e32 v16, 0x80, v166
	v_add_u32_e32 v16, s76, v16
	v_med3_i32 v16, v16, 0, s75
	v_med3_i32 v48, v48, 0, s75
	v_lshl_add_u32 v20, v16, 9, v158
	v_lshl_add_u32 v52, v48, 9, v158
	global_load_dwordx4 v[16:19], v20, s[100:101]
	global_load_dwordx4 v[20:23], v20, s[100:101] offset:64
	global_load_dwordx4 v[48:51], v52, s[100:101]
	global_load_dwordx4 v[52:55], v52, s[100:101] offset:64
	ds_read_b64_tr_b16 v[136:137], v169 offset:2304
	ds_read_b64_tr_b16 v[134:135], v169
	ds_read_b64_tr_b16 v[138:139], v169 offset:32
	ds_read_b64_tr_b16 v[140:141], v169 offset:2336
	ds_read_b64_tr_b16 v[188:189], v169 offset:64
	ds_read_b64_tr_b16 v[190:191], v169 offset:2368
	ds_read_b64_tr_b16 v[200:201], v169 offset:96
	ds_read_b64_tr_b16 v[202:203], v169 offset:2400
	s_waitcnt vmcnt(15)
	ds_write_b128 v241, v[76:79] offset:4608
	s_waitcnt vmcnt(14)
	ds_write_b128 v242, v[84:87] offset:4608
	s_waitcnt vmcnt(13)
	ds_write_b128 v243, v[92:95] offset:4608
	s_waitcnt vmcnt(12)
	ds_write_b128 v244, v[100:103] offset:4608
	v_mfma_f32_16x16x32_bf16 v[76:79], v[40:43], v[4:7], 0
	v_mfma_f32_16x16x32_bf16 v[40:43], v[40:43], v[12:15], 0
	v_mfma_f32_16x16x32_bf16 v[76:79], v[44:47], v[8:11], v[76:79]
	v_mfma_f32_16x16x32_bf16 v[84:87], v[56:59], v[4:7], 0
	v_mfma_f32_16x16x32_bf16 v[40:43], v[44:47], v[0:3], v[40:43]
	v_mfma_f32_16x16x32_bf16 v[44:47], v[56:59], v[12:15], 0
	v_sub_u32_e32 v56, v198, v147
	v_add_u32_e32 v59, 1, v56
	s_nop 2
	v_cmp_gt_u32_e64 s[0:1], v59, v146
	v_cmp_gt_u32_e32 vcc, v56, v146
	s_nop 0
	v_cndmask_b32_e64 v77, v77, v246, s[0:1]
	s_nop 0
	v_cndmask_b32_e32 v76, v76, v246, vcc
	v_mfma_f32_16x16x32_bf16 v[84:87], v[60:63], v[8:11], v[84:87]
	v_max_f32_e32 v58, v76, v77
	v_add_u32_e32 v59, 2, v56
	v_cmp_gt_u32_e64 s[22:23], v59, v146
	v_mfma_f32_16x16x32_bf16 v[44:47], v[60:63], v[0:3], v[44:47]
	v_add_u32_e32 v60, 3, v56
	v_cmp_gt_u32_e64 s[24:25], v60, v146
	v_cndmask_b32_e64 v78, v78, v246, s[22:23]
	v_sub_u32_e32 v57, v198, v148
	v_cndmask_b32_e64 v79, v79, v246, s[24:25]
	v_max3_f32 v58, v58, v78, v79
	v_add_u32_e32 v59, 16, v56
	v_add_u32_e32 v60, 17, v56
	v_cmp_gt_u32_e64 s[26:27], v59, v146
	v_cmp_gt_u32_e64 s[28:29], v60, v146
	v_cmp_gt_u32_e64 s[38:39], v57, v145
	v_cndmask_b32_e64 v84, v84, v246, s[26:27]
	v_cndmask_b32_e64 v85, v85, v246, s[28:29]
	v_max3_f32 v58, v58, v84, v85
	v_add_u32_e32 v59, 18, v56
	v_add_u32_e32 v56, 19, v56
	v_cmp_gt_u32_e64 s[30:31], v59, v146
	v_cmp_gt_u32_e64 s[34:35], v56, v146
	v_add_u32_e32 v60, 3, v57
	v_cndmask_b32_e64 v86, v86, v246, s[30:31]
	v_cndmask_b32_e64 v87, v87, v246, s[34:35]
	v_max3_f32 v56, v58, v86, v87
	v_add_u32_e32 v59, 1, v57
	v_cmp_gt_u32_e64 s[40:41], v59, v145
	v_cndmask_b32_e64 v40, v40, v246, s[38:39]
	s_nop 0
	v_cndmask_b32_e64 v41, v41, v246, s[40:41]
	v_max_f32_e32 v58, v40, v41
	v_add_u32_e32 v59, 2, v57
	v_cmp_gt_u32_e64 s[42:43], v59, v145
	v_cmp_gt_u32_e64 s[44:45], v60, v145
	s_nop 0
	v_cndmask_b32_e64 v42, v42, v246, s[42:43]
	v_cndmask_b32_e64 v43, v43, v246, s[44:45]
	v_max3_f32 v58, v58, v42, v43
	v_add_u32_e32 v59, 16, v57
	v_add_u32_e32 v60, 17, v57
	v_cmp_gt_u32_e64 s[46:47], v59, v145
	v_cmp_gt_u32_e64 s[48:49], v60, v145
	s_nop 0
	v_cndmask_b32_e64 v44, v44, v246, s[46:47]
	v_cndmask_b32_e64 v45, v45, v246, s[48:49]
	v_max3_f32 v58, v58, v44, v45
	v_add_u32_e32 v59, 18, v57
	v_add_u32_e32 v57, 19, v57
	v_cmp_gt_u32_e64 s[50:51], v59, v145
	v_cmp_gt_u32_e64 s[52:53], v57, v145
	s_nop 0
	v_cndmask_b32_e64 v46, v46, v246, s[50:51]
	v_cndmask_b32_e64 v47, v47, v246, s[52:53]
	v_max3_f32 v57, v58, v46, v47
	v_mov_b32_e32 v58, v56
	s_nop 1
	v_permlane32_swap_b32_e32 v58, v56
	v_max_f32_e32 v56, v56, v58
	v_mov_b32_e32 v58, v57
	s_nop 1
	v_permlane32_swap_b32_e32 v58, v57
	v_max_f32_e32 v57, v57, v58
	v_mov_b32_e32 v58, v56
	s_nop 1
	v_permlane16_swap_b32_e32 v58, v56
	v_max_f32_e32 v56, v56, v58
	v_mov_b32_e32 v58, v57
	s_nop 1
	v_permlane16_swap_b32_e32 v58, v57
	v_max_f32_e32 v175, v131, v56
	v_sub_f32_e32 v56, v131, v175
	v_max3_f32 v177, v128, v57, v58
	v_exp_f32_e32 v60, v56
	v_sub_f32_e32 v56, v76, v175
	v_sub_f32_e32 v40, v40, v177
	v_exp_f32_e32 v56, v56
	v_sub_f32_e32 v58, v77, v175
	v_exp_f32_e32 v40, v40
	v_sub_f32_e32 v41, v41, v177
	v_exp_f32_e32 v58, v58
	v_sub_f32_e32 v59, v78, v175
	v_exp_f32_e32 v41, v41
	v_sub_f32_e32 v42, v42, v177
	v_exp_f32_e32 v59, v59
	v_sub_f32_e32 v63, v79, v175
	v_exp_f32_e32 v42, v42
	v_sub_f32_e32 v43, v43, v177
	v_exp_f32_e32 v63, v63
	v_sub_f32_e32 v76, v84, v175
	v_exp_f32_e32 v43, v43
	v_sub_f32_e32 v44, v44, v177
	v_exp_f32_e32 v76, v76
	v_sub_f32_e32 v77, v85, v175
	v_sub_f32_e32 v61, v128, v177
	v_exp_f32_e32 v44, v44
	v_sub_f32_e32 v45, v45, v177
	v_exp_f32_e32 v77, v77
	v_sub_f32_e32 v78, v86, v175
	v_exp_f32_e32 v62, v61
	v_exp_f32_e32 v45, v45
	v_sub_f32_e32 v46, v46, v177
	v_add_f32_e32 v57, v58, v56
	v_exp_f32_e32 v78, v78
	v_sub_f32_e32 v79, v87, v175
	v_add_f32_e32 v61, v41, v40
	v_exp_f32_e32 v46, v46
	v_add_f32_e32 v57, v59, v57
	v_exp_f32_e32 v79, v79
	v_add_f32_e32 v61, v42, v61
	v_sub_f32_e32 v47, v47, v177
	v_add_f32_e32 v57, v63, v57
	v_add_f32_e32 v61, v43, v61
	v_exp_f32_e32 v47, v47
	v_add_f32_e32 v57, v76, v57
	v_add_f32_e32 v61, v44, v61
	v_add_f32_e32 v57, v77, v57
	v_add_f32_e32 v61, v45, v61
	v_add_f32_e32 v57, v78, v57
	v_add_f32_e32 v61, v46, v61
	v_add_f32_e32 v176, v79, v57
	v_cvt_pk_bf16_f32 v56, v56, v58
	v_cvt_pk_bf16_f32 v57, v59, v63
	v_cvt_pk_bf16_f32 v58, v76, v77
	v_cvt_pk_bf16_f32 v59, v78, v79
	v_pk_mul_f32 v[34:35], v[34:35], v[60:61] op_sel_hi:[1,0]
	v_pk_mul_f32 v[32:33], v[32:33], v[60:61] op_sel_hi:[1,0]
	v_add_f32_e32 v178, v47, v61
	v_cvt_pk_bf16_f32 v40, v40, v41
	v_cvt_pk_bf16_f32 v41, v42, v43
	v_cvt_pk_bf16_f32 v42, v44, v45
	v_cvt_pk_bf16_f32 v43, v46, v47
	s_waitcnt lgkmcnt(10)
	v_mfma_f32_16x16x32_bf16 v[44:47], v[134:137], v[56:59], v[32:35]
	v_fmac_f32_e32 v176, v132, v60
	v_fmac_f32_e32 v178, v129, v62
	s_nop 0
	v_pk_mul_f32 v[34:35], v[98:99], v[62:63] op_sel_hi:[1,0]
	v_pk_mul_f32 v[32:33], v[96:97], v[62:63] op_sel_hi:[1,0]
	s_nop 1
	v_mfma_f32_16x16x32_bf16 v[100:103], v[134:137], v[40:43], v[32:35]
	s_nop 2
	v_mul_f32_e64 v34, v106, v60
	v_mul_f32_e64 v35, v107, v60
	v_pk_mul_f32 v[32:33], v[104:105], v[60:61] op_sel_hi:[1,0]
	s_waitcnt lgkmcnt(8)
	s_nop 0
	v_mfma_f32_16x16x32_bf16 v[104:107], v[138:141], v[56:59], v[32:35]
	s_nop 2
	v_mul_f32_e64 v34, v110, v62
	v_mul_f32_e64 v35, v111, v62
	v_pk_mul_f32 v[32:33], v[108:109], v[62:63] op_sel_hi:[1,0]
	s_nop 1
	v_mfma_f32_16x16x32_bf16 v[108:111], v[138:141], v[40:43], v[32:35]
	s_nop 2
	v_mul_f32_e64 v34, v114, v60
	v_mul_f32_e64 v35, v115, v60
	v_pk_mul_f32 v[32:33], v[112:113], v[60:61] op_sel_hi:[1,0]
	s_waitcnt lgkmcnt(6)
	s_nop 0
	v_mfma_f32_16x16x32_bf16 v[112:115], v[188:191], v[56:59], v[32:35]
	s_nop 2
	v_mul_f32_e64 v34, v118, v62
	v_mul_f32_e64 v35, v119, v62
	v_pk_mul_f32 v[32:33], v[116:117], v[62:63] op_sel_hi:[1,0]
	s_nop 1
	v_mfma_f32_16x16x32_bf16 v[116:119], v[188:191], v[40:43], v[32:35]
	v_add_u32_e32 v188, s76, v207
	s_nop 1
	v_pk_mul_f32 v[34:35], v[122:123], v[60:61] op_sel_hi:[1,0]
	v_pk_mul_f32 v[32:33], v[120:121], v[60:61] op_sel_hi:[1,0]
	s_waitcnt lgkmcnt(4)
	s_nop 0
	v_mfma_f32_16x16x32_bf16 v[120:123], v[200:203], v[56:59], v[32:35]
	v_or_b32_e32 v56, 0xb0, v166
	v_add_u32_e32 v56, s76, v56
	s_nop 0
	v_pk_mul_f32 v[34:35], v[126:127], v[62:63] op_sel_hi:[1,0]
	v_pk_mul_f32 v[32:33], v[124:125], v[62:63] op_sel_hi:[1,0]
	s_nop 1
	v_mfma_f32_16x16x32_bf16 v[124:127], v[200:203], v[40:43], v[32:35]
	s_nop 2
	v_add_u32_e32 v32, 0xa0, v149
	v_med3_i32 v32, v32, 0, s75
	v_lshl_add_u32 v32, v32, 9, v152
	global_load_dwordx4 v[76:79], v32, s[98:99]
	v_add_u32_e32 v32, 0xa0, v150
	v_med3_i32 v32, v32, 0, s75
	v_lshl_add_u32 v32, v32, 9, v152
	global_load_dwordx4 v[84:87], v32, s[98:99]
	v_add_u32_e32 v32, 0xa0, v151
	v_med3_i32 v32, v32, 0, s75
	v_lshl_add_u32 v32, v32, 9, v152
	global_load_dwordx4 v[92:95], v32, s[98:99]
	v_add_u32_e32 v32, 0xa0, v252
	v_med3_i32 v32, v32, 0, s75
	v_lshl_add_u32 v32, v32, 9, v152
	global_load_dwordx4 v[96:99], v32, s[98:99]
	v_or_b32_e32 v32, 0xa0, v166
	v_add_u32_e32 v32, s76, v32
	v_med3_i32 v32, v32, 0, s75
	v_med3_i32 v56, v56, 0, s75
	v_lshl_add_u32 v40, v32, 9, v158
	v_lshl_add_u32 v60, v56, 9, v158
	global_load_dwordx4 v[32:35], v40, s[100:101]
	global_load_dwordx4 v[40:43], v40, s[100:101] offset:64
	global_load_dwordx4 v[56:59], v60, s[100:101]
	global_load_dwordx4 v[60:63], v60, s[100:101] offset:64
	ds_read_b64_tr_b16 v[142:143], v169 offset:6912
	ds_read_b64_tr_b16 v[140:141], v169 offset:4608
	ds_read_b64_tr_b16 v[136:137], v169 offset:4640
	ds_read_b64_tr_b16 v[138:139], v169 offset:6944
	ds_read_b64_tr_b16 v[132:133], v169 offset:4672
	ds_read_b64_tr_b16 v[134:135], v169 offset:6976
	ds_read_b64_tr_b16 v[128:129], v169 offset:4704
	ds_read_b64_tr_b16 v[130:131], v169 offset:7008
	s_waitcnt vmcnt(15)
	ds_write_b128 v241, v[36:39]
	s_waitcnt vmcnt(14)
	ds_write_b128 v242, v[72:75]
	s_waitcnt vmcnt(13)
	ds_write_b128 v243, v[80:83]
	s_waitcnt vmcnt(12)
	ds_write_b128 v244, v[88:91]
	v_mfma_f32_16x16x32_bf16 v[36:39], v[24:27], v[4:7], 0
	v_mfma_f32_16x16x32_bf16 v[24:27], v[24:27], v[12:15], 0
	v_mfma_f32_16x16x32_bf16 v[36:39], v[28:31], v[8:11], v[36:39]
	v_mfma_f32_16x16x32_bf16 v[72:75], v[64:67], v[4:7], 0
	v_mfma_f32_16x16x32_bf16 v[24:27], v[28:31], v[0:3], v[24:27]
	v_mfma_f32_16x16x32_bf16 v[28:31], v[64:67], v[12:15], 0
	v_sub_u32_e32 v64, v199, v147
	v_add_u32_e32 v67, 1, v64
	s_nop 2
	v_cmp_gt_u32_e64 s[0:1], v67, v146
	v_cmp_gt_u32_e32 vcc, v64, v146
	s_nop 0
	v_cndmask_b32_e64 v37, v37, v246, s[0:1]
	s_nop 0
	v_cndmask_b32_e32 v36, v36, v246, vcc
	v_mfma_f32_16x16x32_bf16 v[72:75], v[68:71], v[8:11], v[72:75]
	v_max_f32_e32 v66, v36, v37
	v_add_u32_e32 v67, 2, v64
	v_cmp_gt_u32_e64 s[22:23], v67, v146
	v_mfma_f32_16x16x32_bf16 v[28:31], v[68:71], v[0:3], v[28:31]
	v_add_u32_e32 v68, 3, v64
	v_cmp_gt_u32_e64 s[24:25], v68, v146
	v_cndmask_b32_e64 v38, v38, v246, s[22:23]
	v_sub_u32_e32 v65, v199, v148
	v_cndmask_b32_e64 v39, v39, v246, s[24:25]
	v_max3_f32 v66, v66, v38, v39
	v_add_u32_e32 v67, 16, v64
	v_add_u32_e32 v68, 17, v64
	v_cmp_gt_u32_e64 s[26:27], v67, v146
	v_cmp_gt_u32_e64 s[28:29], v68, v146
	v_cmp_gt_u32_e64 s[38:39], v65, v145
	v_cndmask_b32_e64 v72, v72, v246, s[26:27]
	v_cndmask_b32_e64 v73, v73, v246, s[28:29]
	v_max3_f32 v66, v66, v72, v73
	v_add_u32_e32 v67, 18, v64
	v_add_u32_e32 v64, 19, v64
	v_cmp_gt_u32_e64 s[30:31], v67, v146
	v_cmp_gt_u32_e64 s[34:35], v64, v146
	v_add_u32_e32 v68, 3, v65
	v_cndmask_b32_e64 v74, v74, v246, s[30:31]
	v_cndmask_b32_e64 v75, v75, v246, s[34:35]
	v_max3_f32 v64, v66, v74, v75
	v_add_u32_e32 v67, 1, v65
	v_cmp_gt_u32_e64 s[40:41], v67, v145
	v_cndmask_b32_e64 v24, v24, v246, s[38:39]
	s_nop 0
	v_cndmask_b32_e64 v25, v25, v246, s[40:41]
	v_max_f32_e32 v66, v24, v25
	v_add_u32_e32 v67, 2, v65
	v_cmp_gt_u32_e64 s[42:43], v67, v145
	v_cmp_gt_u32_e64 s[44:45], v68, v145
	s_nop 0
	v_cndmask_b32_e64 v26, v26, v246, s[42:43]
	v_cndmask_b32_e64 v27, v27, v246, s[44:45]
	v_max3_f32 v66, v66, v26, v27
	v_add_u32_e32 v67, 16, v65
	v_add_u32_e32 v68, 17, v65
	v_cmp_gt_u32_e64 s[46:47], v67, v145
	v_cmp_gt_u32_e64 s[48:49], v68, v145
	s_nop 0
	v_cndmask_b32_e64 v28, v28, v246, s[46:47]
	v_cndmask_b32_e64 v29, v29, v246, s[48:49]
	v_max3_f32 v66, v66, v28, v29
	v_add_u32_e32 v67, 18, v65
	v_add_u32_e32 v65, 19, v65
	v_cmp_gt_u32_e64 s[50:51], v67, v145
	v_cmp_gt_u32_e64 s[52:53], v65, v145
	s_nop 0
	v_cndmask_b32_e64 v30, v30, v246, s[50:51]
	v_cndmask_b32_e64 v31, v31, v246, s[52:53]
	v_max3_f32 v65, v66, v30, v31
	v_mov_b32_e32 v66, v64
	s_nop 1
	v_permlane32_swap_b32_e32 v66, v64
	v_max_f32_e32 v64, v64, v66
	v_mov_b32_e32 v66, v65
	s_nop 1
	v_permlane32_swap_b32_e32 v66, v65
	v_max_f32_e32 v65, v65, v66
	v_mov_b32_e32 v66, v64
	s_nop 1
	v_permlane16_swap_b32_e32 v66, v64
	v_max3_f32 v179, v175, v64, v66
	v_sub_f32_e32 v36, v36, v179
	v_exp_f32_e32 v36, v36
	v_sub_f32_e32 v37, v37, v179
	v_mov_b32_e32 v66, v65
	v_exp_f32_e32 v37, v37
	v_sub_f32_e32 v38, v38, v179
	v_permlane16_swap_b32_e32 v66, v65
	v_exp_f32_e32 v38, v38
	v_sub_f32_e32 v39, v39, v179
	v_exp_f32_e32 v39, v39
	v_sub_f32_e32 v67, v72, v179
	v_max_f32_e32 v65, v65, v66
	v_exp_f32_e32 v67, v67
	v_sub_f32_e32 v69, v73, v179
	v_exp_f32_e32 v69, v69
	v_sub_f32_e32 v70, v74, v179
	v_max_f32_e32 v181, v177, v65
	v_add_f32_e32 v66, v37, v36
	v_exp_f32_e32 v70, v70
	v_sub_f32_e32 v71, v75, v179
	v_sub_f32_e32 v24, v24, v181
	v_add_f32_e32 v66, v38, v66
	v_exp_f32_e32 v71, v71
	v_exp_f32_e32 v24, v24
	v_sub_f32_e32 v25, v25, v181
	v_add_f32_e32 v66, v39, v66
	v_exp_f32_e32 v25, v25
	v_sub_f32_e32 v26, v26, v181
	v_add_f32_e32 v66, v67, v66
	v_exp_f32_e32 v26, v26
	v_sub_f32_e32 v27, v27, v181
	v_add_f32_e32 v66, v69, v66
	v_exp_f32_e32 v27, v27
	v_sub_f32_e32 v28, v28, v181
	v_add_f32_e32 v66, v70, v66
	v_sub_f32_e32 v65, v177, v181
	v_exp_f32_e32 v28, v28
	v_sub_f32_e32 v29, v29, v181
	v_add_f32_e32 v180, v71, v66
	v_exp_f32_e32 v66, v65
	v_exp_f32_e32 v29, v29
	v_sub_f32_e32 v30, v30, v181
	v_add_f32_e32 v65, v25, v24
	v_exp_f32_e32 v30, v30
	v_sub_f32_e32 v31, v31, v181
	v_sub_f32_e32 v64, v175, v179
	v_add_f32_e32 v65, v26, v65
	v_exp_f32_e32 v31, v31
	v_exp_f32_e32 v64, v64
	v_add_f32_e32 v65, v27, v65
	v_add_f32_e32 v65, v28, v65
	v_add_f32_e32 v65, v29, v65
	v_add_f32_e32 v65, v30, v65
	v_cvt_pk_bf16_f32 v36, v36, v37
	v_cvt_pk_bf16_f32 v37, v38, v39
	v_cvt_pk_bf16_f32 v38, v67, v69
	v_cvt_pk_bf16_f32 v39, v70, v71
	v_add_f32_e32 v183, v31, v65
	v_cvt_pk_bf16_f32 v24, v24, v25
	v_cvt_pk_bf16_f32 v25, v26, v27
	v_cvt_pk_bf16_f32 v26, v28, v29
	v_cvt_pk_bf16_f32 v27, v30, v31
	v_pk_mul_f32 v[30:31], v[46:47], v[64:65] op_sel_hi:[1,0]
	v_pk_mul_f32 v[28:29], v[44:45], v[64:65] op_sel_hi:[1,0]
	v_fmac_f32_e32 v180, v176, v64
	v_fmac_f32_e32 v183, v178, v66
	s_waitcnt lgkmcnt(10)
	v_mfma_f32_16x16x32_bf16 v[68:71], v[140:143], v[36:39], v[28:31]
	s_nop 2
	v_mul_f32_e64 v30, v102, v66
	v_mul_f32_e64 v31, v103, v66
	v_pk_mul_f32 v[28:29], v[100:101], v[66:67] op_sel_hi:[1,0]
	s_nop 1
	v_mfma_f32_16x16x32_bf16 v[72:75], v[140:143], v[24:27], v[28:31]
	s_nop 2
	v_mul_f32_e64 v30, v106, v64
	v_mul_f32_e64 v31, v107, v64
	v_pk_mul_f32 v[28:29], v[104:105], v[64:65] op_sel_hi:[1,0]
	s_waitcnt lgkmcnt(8)
	s_nop 0
	v_mfma_f32_16x16x32_bf16 v[80:83], v[136:139], v[36:39], v[28:31]
	s_nop 2
	v_mul_f32_e64 v30, v110, v66
	v_mul_f32_e64 v31, v111, v66
	v_pk_mul_f32 v[28:29], v[108:109], v[66:67] op_sel_hi:[1,0]
	s_nop 1
	v_mfma_f32_16x16x32_bf16 v[108:111], v[136:139], v[24:27], v[28:31]
	s_nop 2
	v_mul_f32_e64 v30, v114, v64
	v_mul_f32_e64 v31, v115, v64
	v_pk_mul_f32 v[28:29], v[112:113], v[64:65] op_sel_hi:[1,0]
	s_waitcnt lgkmcnt(6)
	s_nop 0
	v_mfma_f32_16x16x32_bf16 v[112:115], v[132:135], v[36:39], v[28:31]
	s_nop 2
	v_mul_f32_e64 v30, v118, v66
	v_mul_f32_e64 v31, v119, v66
	v_pk_mul_f32 v[28:29], v[116:117], v[66:67] op_sel_hi:[1,0]
	s_nop 1
	v_mfma_f32_16x16x32_bf16 v[116:119], v[132:135], v[24:27], v[28:31]
	s_nop 2
	v_mul_f32_e64 v30, v122, v64
	v_mul_f32_e64 v31, v123, v64
	v_pk_mul_f32 v[28:29], v[120:121], v[64:65] op_sel_hi:[1,0]
	s_waitcnt lgkmcnt(4)
	s_nop 0
	v_mfma_f32_16x16x32_bf16 v[120:123], v[128:131], v[36:39], v[28:31]
	s_nop 2
	v_mul_f32_e64 v30, v126, v66
	v_mul_f32_e64 v31, v127, v66
	v_pk_mul_f32 v[28:29], v[124:125], v[66:67] op_sel_hi:[1,0]
	s_nop 1
	v_mfma_f32_16x16x32_bf16 v[124:127], v[128:131], v[24:27], v[28:31]
	v_add_u32_e32 v24, 0xc0, v149
	v_med3_i32 v24, v24, 0, s75
	v_lshl_add_u32 v24, v24, 9, v152
	global_load_dwordx4 v[64:67], v24, s[98:99]
	v_add_u32_e32 v24, 0xc0, v150
	v_med3_i32 v24, v24, 0, s75
	v_lshl_add_u32 v24, v24, 9, v152
	global_load_dwordx4 v[88:91], v24, s[98:99]
	v_add_u32_e32 v24, 0xc0, v151
	v_med3_i32 v24, v24, 0, s75
	v_lshl_add_u32 v24, v24, 9, v152
	global_load_dwordx4 v[100:103], v24, s[98:99]
	v_add_u32_e32 v24, 0xc0, v252
	v_med3_i32 v24, v24, 0, s75
	v_lshl_add_u32 v24, v24, 9, v152
	global_load_dwordx4 v[104:107], v24, s[98:99]
	v_or_b32_e32 v24, 0xc0, v166
	v_add_u32_e32 v24, s76, v24
	v_med3_i32 v24, v24, 0, s75
	v_lshl_add_u32 v24, v24, 9, v158
	global_load_dwordx4 v[36:39], v24, s[100:101]
	global_load_dwordx4 v[44:47], v24, s[100:101] offset:64
	v_or_b32_e32 v24, 0xd0, v166
	v_add_u32_e32 v24, s76, v24
	v_med3_i32 v24, v24, 0, s75
	v_lshl_add_u32 v28, v24, 9, v158
	global_load_dwordx4 v[24:27], v28, s[100:101]
	global_load_dwordx4 v[28:31], v28, s[100:101] offset:64
	ds_read_b64_tr_b16 v[142:143], v169 offset:2304
	ds_read_b64_tr_b16 v[140:141], v169
	ds_read_b64_tr_b16 v[136:137], v169 offset:32
	ds_read_b64_tr_b16 v[138:139], v169 offset:2336
	ds_read_b64_tr_b16 v[132:133], v169 offset:64
	ds_read_b64_tr_b16 v[134:135], v169 offset:2368
	ds_read_b64_tr_b16 v[128:129], v169 offset:96
	ds_read_b64_tr_b16 v[130:131], v169 offset:2400
	s_waitcnt vmcnt(15)
	ds_write_b128 v241, v[76:79] offset:4608
	s_waitcnt vmcnt(14)
	ds_write_b128 v242, v[84:87] offset:4608
	s_waitcnt vmcnt(13)
	ds_write_b128 v243, v[92:95] offset:4608
	s_waitcnt vmcnt(12)
	ds_write_b128 v244, v[96:99] offset:4608
	v_mfma_f32_16x16x32_bf16 v[76:79], v[16:19], v[4:7], 0
	v_mfma_f32_16x16x32_bf16 v[16:19], v[16:19], v[12:15], 0
	v_mfma_f32_16x16x32_bf16 v[76:79], v[20:23], v[8:11], v[76:79]
	v_mfma_f32_16x16x32_bf16 v[84:87], v[48:51], v[4:7], 0
	v_mfma_f32_16x16x32_bf16 v[16:19], v[20:23], v[0:3], v[16:19]
	v_mfma_f32_16x16x32_bf16 v[20:23], v[48:51], v[12:15], 0
	v_add_u32_e32 v49, 0xc0, v154
	v_sub_u32_e32 v48, v49, v147
	v_add_u32_e32 v51, 1, v48
	s_nop 1
	v_cmp_gt_u32_e64 s[0:1], v51, v146
	v_cmp_gt_u32_e32 vcc, v48, v146
	s_nop 0
	v_cndmask_b32_e64 v77, v77, v246, s[0:1]
	s_nop 0
	v_cndmask_b32_e32 v76, v76, v246, vcc
	v_mfma_f32_16x16x32_bf16 v[84:87], v[52:55], v[8:11], v[84:87]
	v_max_f32_e32 v50, v76, v77
	v_add_u32_e32 v51, 2, v48
	v_cmp_gt_u32_e64 s[22:23], v51, v146
	v_mfma_f32_16x16x32_bf16 v[20:23], v[52:55], v[0:3], v[20:23]
	v_add_u32_e32 v52, 3, v48
	v_cmp_gt_u32_e64 s[24:25], v52, v146
	v_cndmask_b32_e64 v78, v78, v246, s[22:23]
	v_sub_u32_e32 v49, v49, v148
	v_cndmask_b32_e64 v79, v79, v246, s[24:25]
	v_max3_f32 v50, v50, v78, v79
	v_add_u32_e32 v51, 16, v48
	v_add_u32_e32 v52, 17, v48
	v_cmp_gt_u32_e64 s[26:27], v51, v146
	v_cmp_gt_u32_e64 s[28:29], v52, v146
	v_cmp_gt_u32_e64 s[38:39], v49, v145
	v_cndmask_b32_e64 v84, v84, v246, s[26:27]
	v_cndmask_b32_e64 v85, v85, v246, s[28:29]
	v_max3_f32 v50, v50, v84, v85
	v_add_u32_e32 v51, 18, v48
	v_add_u32_e32 v48, 19, v48
	v_cmp_gt_u32_e64 s[30:31], v51, v146
	v_cmp_gt_u32_e64 s[34:35], v48, v146
	v_add_u32_e32 v52, 3, v49
	v_cndmask_b32_e64 v86, v86, v246, s[30:31]
	v_cndmask_b32_e64 v87, v87, v246, s[34:35]
	v_max3_f32 v48, v50, v86, v87
	v_add_u32_e32 v51, 1, v49
	v_cmp_gt_u32_e64 s[40:41], v51, v145
	v_cndmask_b32_e64 v16, v16, v246, s[38:39]
	s_nop 0
	v_cndmask_b32_e64 v17, v17, v246, s[40:41]
	v_max_f32_e32 v50, v16, v17
	v_add_u32_e32 v51, 2, v49
	v_cmp_gt_u32_e64 s[42:43], v51, v145
	v_cmp_gt_u32_e64 s[44:45], v52, v145
	s_nop 0
	v_cndmask_b32_e64 v18, v18, v246, s[42:43]
	v_cndmask_b32_e64 v19, v19, v246, s[44:45]
	v_max3_f32 v50, v50, v18, v19
	v_add_u32_e32 v51, 16, v49
	v_add_u32_e32 v52, 17, v49
	v_cmp_gt_u32_e64 s[46:47], v51, v145
	v_cmp_gt_u32_e64 s[48:49], v52, v145
	s_nop 0
	v_cndmask_b32_e64 v20, v20, v246, s[46:47]
	v_cndmask_b32_e64 v21, v21, v246, s[48:49]
	v_max3_f32 v50, v50, v20, v21
	v_add_u32_e32 v51, 18, v49
	v_add_u32_e32 v49, 19, v49
	v_cmp_gt_u32_e64 s[50:51], v51, v145
	v_cmp_gt_u32_e64 s[52:53], v49, v145
	s_nop 0
	v_cndmask_b32_e64 v22, v22, v246, s[50:51]
	v_cndmask_b32_e64 v23, v23, v246, s[52:53]
	v_max3_f32 v49, v50, v22, v23
	v_mov_b32_e32 v50, v48
	s_nop 1
	v_permlane32_swap_b32_e32 v50, v48
	v_max_f32_e32 v48, v48, v50
	v_mov_b32_e32 v50, v49
	s_nop 1
	v_permlane32_swap_b32_e32 v50, v49
	v_max_f32_e32 v49, v49, v50
	v_mov_b32_e32 v50, v48
	s_nop 1
	v_permlane16_swap_b32_e32 v50, v48
	v_max_f32_e32 v48, v48, v50
	v_mov_b32_e32 v50, v49
	s_nop 1
	v_permlane16_swap_b32_e32 v50, v49
	v_max_f32_e32 v175, v179, v48
	v_sub_f32_e32 v48, v179, v175
	v_max3_f32 v177, v181, v49, v50
	v_exp_f32_e32 v52, v48
	v_sub_f32_e32 v48, v76, v175
	v_sub_f32_e32 v16, v16, v177
	v_exp_f32_e32 v48, v48
	v_sub_f32_e32 v50, v77, v175
	v_exp_f32_e32 v16, v16
	v_sub_f32_e32 v17, v17, v177
	v_exp_f32_e32 v50, v50
	v_sub_f32_e32 v51, v78, v175
	v_exp_f32_e32 v17, v17
	v_sub_f32_e32 v18, v18, v177
	v_exp_f32_e32 v51, v51
	v_sub_f32_e32 v55, v79, v175
	v_exp_f32_e32 v18, v18
	v_sub_f32_e32 v19, v19, v177
	v_exp_f32_e32 v55, v55
	v_sub_f32_e32 v76, v84, v175
	v_exp_f32_e32 v19, v19
	v_sub_f32_e32 v20, v20, v177
	v_exp_f32_e32 v76, v76
	v_sub_f32_e32 v77, v85, v175
	v_sub_f32_e32 v53, v181, v177
	v_exp_f32_e32 v20, v20
	v_sub_f32_e32 v21, v21, v177
	v_exp_f32_e32 v77, v77
	v_sub_f32_e32 v78, v86, v175
	v_exp_f32_e32 v54, v53
	v_exp_f32_e32 v21, v21
	v_sub_f32_e32 v22, v22, v177
	v_add_f32_e32 v49, v50, v48
	v_exp_f32_e32 v78, v78
	v_sub_f32_e32 v79, v87, v175
	v_add_f32_e32 v53, v17, v16
	v_exp_f32_e32 v22, v22
	v_sub_f32_e32 v23, v23, v177
	v_add_f32_e32 v49, v51, v49
	v_exp_f32_e32 v79, v79
	v_add_f32_e32 v53, v18, v53
	v_exp_f32_e32 v23, v23
	v_add_f32_e32 v49, v55, v49
	v_add_f32_e32 v53, v19, v53
	v_add_f32_e32 v49, v76, v49
	v_add_f32_e32 v53, v20, v53
	v_add_f32_e32 v49, v77, v49
	v_add_f32_e32 v53, v21, v53
	v_add_f32_e32 v49, v78, v49
	v_add_f32_e32 v53, v22, v53
	v_add_f32_e32 v176, v79, v49
	v_cvt_pk_bf16_f32 v48, v48, v50
	v_cvt_pk_bf16_f32 v49, v51, v55
	v_cvt_pk_bf16_f32 v50, v76, v77
	v_cvt_pk_bf16_f32 v51, v78, v79
	v_add_f32_e32 v178, v23, v53
	v_cvt_pk_bf16_f32 v16, v16, v17
	v_cvt_pk_bf16_f32 v17, v18, v19
	v_cvt_pk_bf16_f32 v18, v20, v21
	v_cvt_pk_bf16_f32 v19, v22, v23
	v_pk_mul_f32 v[22:23], v[70:71], v[52:53] op_sel_hi:[1,0]
	v_pk_mul_f32 v[20:21], v[68:69], v[52:53] op_sel_hi:[1,0]
	v_fmac_f32_e32 v176, v180, v52
	v_fmac_f32_e32 v178, v183, v54
	s_waitcnt lgkmcnt(10)
	v_mfma_f32_16x16x32_bf16 v[76:79], v[140:143], v[48:51], v[20:23]
	v_add_u32_e32 v180, 0x100, v149
	v_add_u32_e32 v179, 0x100, v150
	s_nop 0
	v_pk_mul_f32 v[22:23], v[74:75], v[54:55] op_sel_hi:[1,0]
	v_pk_mul_f32 v[20:21], v[72:73], v[54:55] op_sel_hi:[1,0]
	s_nop 1
	v_mfma_f32_16x16x32_bf16 v[92:95], v[140:143], v[16:19], v[20:23]
	s_nop 2
	v_mul_f32_e64 v22, v82, v52
	v_mul_f32_e64 v23, v83, v52
	v_pk_mul_f32 v[20:21], v[80:81], v[52:53] op_sel_hi:[1,0]
	s_waitcnt lgkmcnt(8)
	s_nop 0
	v_mfma_f32_16x16x32_bf16 v[96:99], v[136:139], v[48:51], v[20:23]
	s_nop 2
	v_mul_f32_e64 v22, v110, v54
	v_mul_f32_e64 v23, v111, v54
	v_pk_mul_f32 v[20:21], v[108:109], v[54:55] op_sel_hi:[1,0]
	s_nop 1
	v_mfma_f32_16x16x32_bf16 v[108:111], v[136:139], v[16:19], v[20:23]
	s_nop 2
	v_mul_f32_e64 v22, v114, v52
	v_mul_f32_e64 v23, v115, v52
	v_pk_mul_f32 v[20:21], v[112:113], v[52:53] op_sel_hi:[1,0]
	s_waitcnt lgkmcnt(6)
	s_nop 0
	v_mfma_f32_16x16x32_bf16 v[112:115], v[132:135], v[48:51], v[20:23]
	s_nop 2
	v_mul_f32_e64 v22, v118, v54
	v_mul_f32_e64 v23, v119, v54
	v_pk_mul_f32 v[20:21], v[116:117], v[54:55] op_sel_hi:[1,0]
	s_nop 1
	v_mfma_f32_16x16x32_bf16 v[116:119], v[132:135], v[16:19], v[20:23]
	s_nop 2
	v_mul_f32_e64 v22, v122, v52
	v_mul_f32_e64 v23, v123, v52
	v_pk_mul_f32 v[20:21], v[120:121], v[52:53] op_sel_hi:[1,0]
	s_waitcnt lgkmcnt(4)
	s_nop 0
	v_mfma_f32_16x16x32_bf16 v[120:123], v[128:131], v[48:51], v[20:23]
	s_nop 2
	v_mul_f32_e64 v22, v126, v54
	v_mul_f32_e64 v23, v127, v54
	v_pk_mul_f32 v[20:21], v[124:125], v[54:55] op_sel_hi:[1,0]
	s_nop 1
	v_mfma_f32_16x16x32_bf16 v[124:127], v[128:131], v[16:19], v[20:23]
	v_add_u32_e32 v16, 0xe0, v149
	v_med3_i32 v16, v16, 0, s75
	v_lshl_add_u32 v16, v16, 9, v152
	global_load_dwordx4 v[68:71], v16, s[98:99]
	v_add_u32_e32 v16, 0xe0, v150
	v_med3_i32 v16, v16, 0, s75
	v_lshl_add_u32 v16, v16, 9, v152
	global_load_dwordx4 v[72:75], v16, s[98:99]
	v_add_u32_e32 v16, 0xe0, v151
	v_med3_i32 v16, v16, 0, s75
	v_lshl_add_u32 v16, v16, 9, v152
	global_load_dwordx4 v[80:83], v16, s[98:99]
	v_add_u32_e32 v16, 0xe0, v252
	v_med3_i32 v16, v16, 0, s75
	v_lshl_add_u32 v16, v16, 9, v152
	global_load_dwordx4 v[84:87], v16, s[98:99]
	v_or_b32_e32 v16, 0xe0, v166
	v_add_u32_e32 v16, s76, v16
	v_med3_i32 v16, v16, 0, s75
	v_lshl_add_u32 v16, v16, 9, v158
	global_load_dwordx4 v[48:51], v16, s[100:101]
	global_load_dwordx4 v[52:55], v16, s[100:101] offset:64
	v_or_b32_e32 v16, 0xf0, v166
	v_add_u32_e32 v16, s76, v16
	v_med3_i32 v16, v16, 0, s75
	v_lshl_add_u32 v20, v16, 9, v158
	global_load_dwordx4 v[16:19], v20, s[100:101]
	global_load_dwordx4 v[20:23], v20, s[100:101] offset:64
	ds_read_b64_tr_b16 v[142:143], v169 offset:6912
	ds_read_b64_tr_b16 v[140:141], v169 offset:4608
	ds_read_b64_tr_b16 v[136:137], v169 offset:4640
	ds_read_b64_tr_b16 v[138:139], v169 offset:6944
	ds_read_b64_tr_b16 v[132:133], v169 offset:4672
	ds_read_b64_tr_b16 v[134:135], v169 offset:6976
	ds_read_b64_tr_b16 v[128:129], v169 offset:4704
	ds_read_b64_tr_b16 v[130:131], v169 offset:7008
	s_waitcnt vmcnt(15)
	ds_write_b128 v241, v[64:67]
	s_waitcnt vmcnt(14)
	ds_write_b128 v242, v[88:91]
	s_waitcnt vmcnt(13)
	ds_write_b128 v243, v[100:103]
	s_waitcnt vmcnt(12)
	ds_write_b128 v244, v[104:107]
	v_mfma_f32_16x16x32_bf16 v[64:67], v[32:35], v[4:7], 0
	v_mfma_f32_16x16x32_bf16 v[32:35], v[32:35], v[12:15], 0
	v_mfma_f32_16x16x32_bf16 v[64:67], v[40:43], v[8:11], v[64:67]
	v_mfma_f32_16x16x32_bf16 v[88:91], v[56:59], v[4:7], 0
	v_mfma_f32_16x16x32_bf16 v[32:35], v[40:43], v[0:3], v[32:35]
	v_mfma_f32_16x16x32_bf16 v[40:43], v[56:59], v[12:15], 0
	v_add_u32_e32 v57, 0xe0, v154
	v_sub_u32_e32 v56, v57, v147
	v_add_u32_e32 v59, 1, v56
	s_nop 1
	v_cmp_gt_u32_e64 s[0:1], v59, v146
	v_cmp_gt_u32_e32 vcc, v56, v146
	s_nop 0
	v_cndmask_b32_e64 v65, v65, v246, s[0:1]
	s_nop 0
	v_cndmask_b32_e32 v64, v64, v246, vcc
	v_mfma_f32_16x16x32_bf16 v[88:91], v[60:63], v[8:11], v[88:91]
	v_max_f32_e32 v58, v64, v65
	v_add_u32_e32 v59, 2, v56
	v_cmp_gt_u32_e64 s[22:23], v59, v146
	v_mfma_f32_16x16x32_bf16 v[40:43], v[60:63], v[0:3], v[40:43]
	v_add_u32_e32 v60, 3, v56
	v_cmp_gt_u32_e64 s[24:25], v60, v146
	v_cndmask_b32_e64 v66, v66, v246, s[22:23]
	v_sub_u32_e32 v57, v57, v148
	v_cndmask_b32_e64 v67, v67, v246, s[24:25]
	v_max3_f32 v58, v58, v66, v67
	v_add_u32_e32 v59, 16, v56
	v_add_u32_e32 v60, 17, v56
	v_cmp_gt_u32_e64 s[26:27], v59, v146
	v_cmp_gt_u32_e64 s[28:29], v60, v146
	v_cmp_gt_u32_e64 s[38:39], v57, v145
	v_cndmask_b32_e64 v88, v88, v246, s[26:27]
	v_cndmask_b32_e64 v89, v89, v246, s[28:29]
	v_max3_f32 v58, v58, v88, v89
	v_add_u32_e32 v59, 18, v56
	v_add_u32_e32 v56, 19, v56
	v_cmp_gt_u32_e64 s[30:31], v59, v146
	v_cmp_gt_u32_e64 s[34:35], v56, v146
	v_add_u32_e32 v60, 3, v57
	v_cndmask_b32_e64 v90, v90, v246, s[30:31]
	v_cndmask_b32_e64 v91, v91, v246, s[34:35]
	v_max3_f32 v56, v58, v90, v91
	v_add_u32_e32 v59, 1, v57
	v_cmp_gt_u32_e64 s[40:41], v59, v145
	v_cndmask_b32_e64 v32, v32, v246, s[38:39]
	s_nop 0
	v_cndmask_b32_e64 v33, v33, v246, s[40:41]
	v_max_f32_e32 v58, v32, v33
	v_add_u32_e32 v59, 2, v57
	v_cmp_gt_u32_e64 s[42:43], v59, v145
	v_cmp_gt_u32_e64 s[44:45], v60, v145
	s_nop 0
	v_cndmask_b32_e64 v34, v34, v246, s[42:43]
	v_cndmask_b32_e64 v35, v35, v246, s[44:45]
	v_max3_f32 v58, v58, v34, v35
	v_add_u32_e32 v59, 16, v57
	v_add_u32_e32 v60, 17, v57
	v_cmp_gt_u32_e64 s[46:47], v59, v145
	v_cmp_gt_u32_e64 s[48:49], v60, v145
	s_nop 0
	v_cndmask_b32_e64 v40, v40, v246, s[46:47]
	v_cndmask_b32_e64 v41, v41, v246, s[48:49]
	v_max3_f32 v58, v58, v40, v41
	v_add_u32_e32 v59, 18, v57
	v_add_u32_e32 v57, 19, v57
	v_cmp_gt_u32_e64 s[50:51], v59, v145
	v_cmp_gt_u32_e64 s[52:53], v57, v145
	s_nop 0
	v_cndmask_b32_e64 v42, v42, v246, s[50:51]
	v_cndmask_b32_e64 v43, v43, v246, s[52:53]
	v_max3_f32 v57, v58, v42, v43
	v_mov_b32_e32 v58, v56
	s_nop 1
	v_permlane32_swap_b32_e32 v58, v56
	v_max_f32_e32 v56, v56, v58
	v_mov_b32_e32 v58, v57
	s_nop 1
	v_permlane32_swap_b32_e32 v58, v57
	v_max_f32_e32 v57, v57, v58
	v_mov_b32_e32 v58, v56
	s_nop 1
	v_permlane16_swap_b32_e32 v58, v56
	v_max_f32_e32 v56, v56, v58
	v_mov_b32_e32 v58, v57
	s_nop 1
	v_permlane16_swap_b32_e32 v58, v57
	v_max_f32_e32 v181, v175, v56
	v_sub_f32_e32 v56, v175, v181
	v_max3_f32 v184, v177, v57, v58
	v_exp_f32_e32 v60, v56
	v_sub_f32_e32 v56, v64, v181
	v_sub_f32_e32 v32, v32, v184
	v_exp_f32_e32 v56, v56
	v_sub_f32_e32 v58, v65, v181
	v_exp_f32_e32 v32, v32
	v_sub_f32_e32 v33, v33, v184
	v_exp_f32_e32 v58, v58
	v_sub_f32_e32 v59, v66, v181
	v_exp_f32_e32 v33, v33
	v_sub_f32_e32 v34, v34, v184
	v_exp_f32_e32 v59, v59
	v_sub_f32_e32 v63, v67, v181
	v_exp_f32_e32 v34, v34
	v_sub_f32_e32 v35, v35, v184
	v_exp_f32_e32 v63, v63
	v_sub_f32_e32 v64, v88, v181
	v_exp_f32_e32 v35, v35
	v_sub_f32_e32 v40, v40, v184
	v_exp_f32_e32 v64, v64
	v_sub_f32_e32 v65, v89, v181
	v_sub_f32_e32 v61, v177, v184
	v_exp_f32_e32 v40, v40
	v_sub_f32_e32 v41, v41, v184
	v_exp_f32_e32 v65, v65
	v_sub_f32_e32 v66, v90, v181
	v_exp_f32_e32 v62, v61
	v_exp_f32_e32 v41, v41
	v_sub_f32_e32 v42, v42, v184
	v_add_f32_e32 v57, v58, v56
	v_exp_f32_e32 v66, v66
	v_sub_f32_e32 v67, v91, v181
	v_add_f32_e32 v61, v33, v32
	v_exp_f32_e32 v42, v42
	v_sub_f32_e32 v43, v43, v184
	v_add_f32_e32 v57, v59, v57
	v_exp_f32_e32 v67, v67
	v_add_f32_e32 v61, v34, v61
	v_exp_f32_e32 v43, v43
	v_add_f32_e32 v57, v63, v57
	v_add_f32_e32 v61, v35, v61
	v_add_f32_e32 v57, v64, v57
	v_add_f32_e32 v61, v40, v61
	v_add_f32_e32 v57, v65, v57
	v_add_f32_e32 v61, v41, v61
	v_add_f32_e32 v57, v66, v57
	v_add_f32_e32 v61, v42, v61
	v_add_f32_e32 v183, v67, v57
	v_cvt_pk_bf16_f32 v56, v56, v58
	v_cvt_pk_bf16_f32 v57, v59, v63
	v_cvt_pk_bf16_f32 v58, v64, v65
	v_cvt_pk_bf16_f32 v59, v66, v67
	v_add_f32_e32 v185, v43, v61
	v_cvt_pk_bf16_f32 v32, v32, v33
	v_cvt_pk_bf16_f32 v33, v34, v35
	v_cvt_pk_bf16_f32 v34, v40, v41
	v_cvt_pk_bf16_f32 v35, v42, v43
	v_pk_mul_f32 v[42:43], v[78:79], v[60:61] op_sel_hi:[1,0]
	v_pk_mul_f32 v[40:41], v[76:77], v[60:61] op_sel_hi:[1,0]
	v_fmac_f32_e32 v185, v178, v62
	s_waitcnt lgkmcnt(10)
	v_mfma_f32_16x16x32_bf16 v[100:103], v[140:143], v[56:59], v[40:43]
	v_add_u32_e32 v178, 0x100, v151
	v_fmac_f32_e32 v183, v176, v60
	v_add_u32_e32 v177, 0x100, v252
	v_pk_mul_f32 v[42:43], v[94:95], v[62:63] op_sel_hi:[1,0]
	v_pk_mul_f32 v[40:41], v[92:93], v[62:63] op_sel_hi:[1,0]
	s_nop 1
	v_mfma_f32_16x16x32_bf16 v[92:95], v[140:143], v[32:35], v[40:43]
	s_nop 2
	v_mul_f32_e64 v42, v98, v60
	v_mul_f32_e64 v43, v99, v60
	v_pk_mul_f32 v[40:41], v[96:97], v[60:61] op_sel_hi:[1,0]
	s_waitcnt lgkmcnt(8)
	s_nop 0
	v_mfma_f32_16x16x32_bf16 v[104:107], v[136:139], v[56:59], v[40:43]
	s_nop 2
	v_mul_f32_e64 v42, v110, v62
	v_mul_f32_e64 v43, v111, v62
	v_pk_mul_f32 v[40:41], v[108:109], v[62:63] op_sel_hi:[1,0]
	s_nop 1
	v_mfma_f32_16x16x32_bf16 v[108:111], v[136:139], v[32:35], v[40:43]
	s_nop 2
	v_mul_f32_e64 v42, v114, v60
	v_mul_f32_e64 v43, v115, v60
	v_pk_mul_f32 v[40:41], v[112:113], v[60:61] op_sel_hi:[1,0]
	s_waitcnt lgkmcnt(6)
	s_nop 0
	v_mfma_f32_16x16x32_bf16 v[112:115], v[132:135], v[56:59], v[40:43]
	s_nop 2
	v_mul_f32_e64 v42, v118, v62
	v_mul_f32_e64 v43, v119, v62
	v_pk_mul_f32 v[40:41], v[116:117], v[62:63] op_sel_hi:[1,0]
	s_nop 1
	v_mfma_f32_16x16x32_bf16 v[116:119], v[132:135], v[32:35], v[40:43]
	s_nop 2
	v_mul_f32_e64 v42, v122, v60
	v_mul_f32_e64 v43, v123, v60
	v_pk_mul_f32 v[40:41], v[120:121], v[60:61] op_sel_hi:[1,0]
	s_waitcnt lgkmcnt(4)
	s_nop 0
	v_mfma_f32_16x16x32_bf16 v[120:123], v[128:131], v[56:59], v[40:43]
	s_nop 2
	v_mul_f32_e64 v42, v126, v62
	v_mul_f32_e64 v43, v127, v62
	v_pk_mul_f32 v[40:41], v[124:125], v[62:63] op_sel_hi:[1,0]
	s_nop 1
	v_mfma_f32_16x16x32_bf16 v[124:127], v[128:131], v[32:35], v[40:43]
	v_med3_i32 v32, v180, 0, s75
	v_lshl_add_u32 v32, v32, 9, v152
	global_load_dwordx4 v[56:59], v32, s[98:99]
	v_med3_i32 v32, v179, 0, s75
	v_lshl_add_u32 v32, v32, 9, v152
	global_load_dwordx4 v[60:63], v32, s[98:99]
	v_med3_i32 v32, v178, 0, s75
	v_lshl_add_u32 v32, v32, 9, v152
	global_load_dwordx4 v[88:91], v32, s[98:99]
	v_med3_i32 v32, v177, 0, s75
	v_lshl_add_u32 v32, v32, 9, v152
	global_load_dwordx4 v[96:99], v32, s[98:99]
	v_or_b32_e32 v32, 0x100, v166
	v_add_u32_e32 v32, s76, v32
	v_med3_i32 v32, v32, 0, s75
	v_lshl_add_u32 v32, v32, 9, v158
	global_load_dwordx4 v[76:79], v32, s[100:101]
	global_load_dwordx4 v[64:67], v32, s[100:101] offset:64
	v_or_b32_e32 v32, 0x110, v166
	v_add_u32_e32 v32, s76, v32
	v_med3_i32 v32, v32, 0, s75
	v_lshl_add_u32 v32, v32, 9, v158
	global_load_dwordx4 v[40:43], v32, s[100:101]
	global_load_dwordx4 v[32:35], v32, s[100:101] offset:64
	ds_read_b64_tr_b16 v[142:143], v169 offset:2304
	ds_read_b64_tr_b16 v[140:141], v169
	ds_read_b64_tr_b16 v[136:137], v169 offset:32
	ds_read_b64_tr_b16 v[138:139], v169 offset:2336
	ds_read_b64_tr_b16 v[132:133], v169 offset:64
	ds_read_b64_tr_b16 v[134:135], v169 offset:2368
	ds_read_b64_tr_b16 v[128:129], v169 offset:96
	ds_read_b64_tr_b16 v[130:131], v169 offset:2400
	s_waitcnt vmcnt(15)
	ds_write_b128 v241, v[68:71] offset:4608
	s_waitcnt vmcnt(14)
	ds_write_b128 v242, v[72:75] offset:4608
	s_waitcnt vmcnt(13)
	ds_write_b128 v243, v[80:83] offset:4608
	s_waitcnt vmcnt(12)
	ds_write_b128 v244, v[84:87] offset:4608
	v_mfma_f32_16x16x32_bf16 v[68:71], v[36:39], v[4:7], 0
	v_mfma_f32_16x16x32_bf16 v[72:75], v[24:27], v[4:7], 0
	v_mfma_f32_16x16x32_bf16 v[24:27], v[24:27], v[12:15], 0
	v_mfma_f32_16x16x32_bf16 v[68:71], v[44:47], v[8:11], v[68:71]
	v_mfma_f32_16x16x32_bf16 v[72:75], v[28:31], v[8:11], v[72:75]
	v_mfma_f32_16x16x32_bf16 v[24:27], v[28:31], v[0:3], v[24:27]
	v_add_u32_e32 v29, 0x100, v154
	v_sub_u32_e32 v28, v29, v147
	v_add_u32_e32 v31, 1, v28
	v_mfma_f32_16x16x32_bf16 v[36:39], v[36:39], v[12:15], 0
	s_nop 1
	v_cmp_gt_u32_e64 s[0:1], v31, v146
	v_cmp_gt_u32_e32 vcc, v28, v146
	s_nop 0
	v_cndmask_b32_e64 v69, v69, v246, s[0:1]
	s_nop 0
	v_cndmask_b32_e32 v68, v68, v246, vcc
	v_mfma_f32_16x16x32_bf16 v[36:39], v[44:47], v[0:3], v[36:39]
	v_max_f32_e32 v30, v68, v69
	v_add_u32_e32 v31, 2, v28
	v_add_u32_e32 v44, 3, v28
	v_cmp_gt_u32_e64 s[22:23], v31, v146
	v_cmp_gt_u32_e64 s[24:25], v44, v146
	v_sub_u32_e32 v29, v29, v148
	v_cndmask_b32_e64 v70, v70, v246, s[22:23]
	v_cndmask_b32_e64 v71, v71, v246, s[24:25]
	v_max3_f32 v30, v30, v70, v71
	v_add_u32_e32 v31, 16, v28
	v_add_u32_e32 v44, 17, v28
	v_cmp_gt_u32_e64 s[26:27], v31, v146
	v_cmp_gt_u32_e64 s[28:29], v44, v146
	v_cmp_gt_u32_e64 s[38:39], v29, v145
	v_cndmask_b32_e64 v72, v72, v246, s[26:27]
	v_cndmask_b32_e64 v73, v73, v246, s[28:29]
	v_max3_f32 v30, v30, v72, v73
	v_add_u32_e32 v31, 18, v28
	v_add_u32_e32 v28, 19, v28
	v_cmp_gt_u32_e64 s[30:31], v31, v146
	v_cmp_gt_u32_e64 s[34:35], v28, v146
	v_add_u32_e32 v44, 3, v29
	v_cndmask_b32_e64 v74, v74, v246, s[30:31]
	v_cndmask_b32_e64 v75, v75, v246, s[34:35]
	v_max3_f32 v28, v30, v74, v75
	v_add_u32_e32 v31, 1, v29
	v_cmp_gt_u32_e64 s[40:41], v31, v145
	v_cndmask_b32_e64 v36, v36, v246, s[38:39]
	s_nop 0
	v_cndmask_b32_e64 v37, v37, v246, s[40:41]
	v_max_f32_e32 v30, v36, v37
	v_add_u32_e32 v31, 2, v29
	v_cmp_gt_u32_e64 s[42:43], v31, v145
	v_cmp_gt_u32_e64 s[44:45], v44, v145
	s_nop 0
	v_cndmask_b32_e64 v38, v38, v246, s[42:43]
	v_cndmask_b32_e64 v39, v39, v246, s[44:45]
	v_max3_f32 v30, v30, v38, v39
	v_add_u32_e32 v31, 16, v29
	v_add_u32_e32 v44, 17, v29
	v_cmp_gt_u32_e64 s[46:47], v31, v145
	v_cmp_gt_u32_e64 s[48:49], v44, v145
	s_nop 0
	v_cndmask_b32_e64 v24, v24, v246, s[46:47]
	v_cndmask_b32_e64 v25, v25, v246, s[48:49]
	v_max3_f32 v30, v30, v24, v25
	v_add_u32_e32 v31, 18, v29
	v_add_u32_e32 v29, 19, v29
	v_cmp_gt_u32_e64 s[50:51], v31, v145
	v_cmp_gt_u32_e64 s[52:53], v29, v145
	s_nop 0
	v_cndmask_b32_e64 v26, v26, v246, s[50:51]
	v_cndmask_b32_e64 v27, v27, v246, s[52:53]
	v_max3_f32 v29, v30, v26, v27
	v_mov_b32_e32 v30, v28
	s_nop 1
	v_permlane32_swap_b32_e32 v30, v28
	v_max_f32_e32 v28, v28, v30
	v_mov_b32_e32 v30, v29
	s_nop 1
	v_permlane32_swap_b32_e32 v30, v29
	v_max_f32_e32 v29, v29, v30
	v_mov_b32_e32 v30, v28
	s_nop 1
	v_permlane16_swap_b32_e32 v30, v28
	v_max_f32_e32 v28, v28, v30
	v_mov_b32_e32 v30, v29
	v_max_f32_e32 v175, v181, v28
	s_nop 0
	v_permlane16_swap_b32_e32 v30, v29
	v_sub_f32_e32 v28, v181, v175
	v_exp_f32_e32 v44, v28
	v_sub_f32_e32 v28, v68, v175
	v_max_f32_e32 v46, v29, v30
	v_exp_f32_e32 v28, v28
	v_sub_f32_e32 v30, v69, v175
	v_exp_f32_e32 v30, v30
	v_sub_f32_e32 v31, v70, v175
	v_exp_f32_e32 v31, v31
	v_sub_f32_e32 v47, v71, v175
	v_max_f32_e32 v181, v184, v46
	v_exp_f32_e32 v47, v47
	v_sub_f32_e32 v68, v72, v175
	v_sub_f32_e32 v36, v36, v181
	v_exp_f32_e32 v68, v68
	v_sub_f32_e32 v69, v73, v175
	v_exp_f32_e32 v36, v36
	v_sub_f32_e32 v37, v37, v181
	v_exp_f32_e32 v69, v69
	v_sub_f32_e32 v70, v74, v175
	v_exp_f32_e32 v37, v37
	v_sub_f32_e32 v38, v38, v181
	v_add_f32_e32 v29, v30, v28
	v_exp_f32_e32 v70, v70
	v_sub_f32_e32 v71, v75, v175
	v_exp_f32_e32 v38, v38
	v_sub_f32_e32 v39, v39, v181
	v_add_f32_e32 v29, v31, v29
	v_exp_f32_e32 v71, v71
	v_exp_f32_e32 v39, v39
	v_sub_f32_e32 v24, v24, v181
	v_add_f32_e32 v29, v47, v29
	v_sub_f32_e32 v45, v184, v181
	v_exp_f32_e32 v24, v24
	v_sub_f32_e32 v25, v25, v181
	v_add_f32_e32 v29, v68, v29
	v_exp_f32_e32 v46, v45
	v_exp_f32_e32 v25, v25
	v_add_f32_e32 v29, v69, v29
	v_add_f32_e32 v45, v37, v36
	v_add_f32_e32 v29, v70, v29
	v_add_f32_e32 v45, v38, v45
	v_add_f32_e32 v176, v71, v29
	v_cvt_pk_bf16_f32 v29, v31, v47
	v_add_f32_e32 v45, v39, v45
	v_cndmask_b32_e64 v47, v24, 0, s[46:47]
	v_add_f32_e32 v24, v47, v45
	v_cndmask_b32_e64 v45, v25, 0, s[48:49]
	v_sub_f32_e32 v25, v26, v181
	v_exp_f32_e32 v25, v25
	v_cvt_pk_bf16_f32 v28, v28, v30
	v_cvt_pk_bf16_f32 v30, v68, v69
	v_add_f32_e32 v24, v45, v24
	v_cndmask_b32_e64 v68, v25, 0, s[50:51]
	v_sub_f32_e32 v25, v27, v181
	v_exp_f32_e32 v25, v25
	v_add_f32_e32 v24, v68, v24
	v_fmac_f32_e32 v176, v183, v44
	v_cvt_pk_bf16_f32 v31, v70, v71
	v_cndmask_b32_e64 v27, v25, 0, s[52:53]
	v_add_f32_e32 v183, v27, v24
	v_cvt_pk_bf16_f32 v24, v36, v37
	v_cvt_pk_bf16_f32 v25, v38, v39
	v_pk_mul_f32 v[38:39], v[102:103], v[44:45] op_sel_hi:[1,0]
	v_pk_mul_f32 v[36:37], v[100:101], v[44:45] op_sel_hi:[1,0]
	v_cvt_pk_bf16_f32 v26, v47, v45
	v_cvt_pk_bf16_f32 v27, v68, v27
	s_waitcnt lgkmcnt(10)
	v_mfma_f32_16x16x32_bf16 v[80:83], v[140:143], v[28:31], v[36:39]
	v_fmac_f32_e32 v183, v185, v46
	v_add_u32_e32 v184, s76, v204
	v_add_u32_e32 v185, s76, v205
	v_pk_mul_f32 v[38:39], v[94:95], v[46:47] op_sel_hi:[1,0]
	v_pk_mul_f32 v[36:37], v[92:93], v[46:47] op_sel_hi:[1,0]
	s_nop 1
	v_mfma_f32_16x16x32_bf16 v[84:87], v[140:143], v[24:27], v[36:39]
	s_nop 2
	v_mul_f32_e64 v38, v106, v44
	v_mul_f32_e64 v39, v107, v44
	v_pk_mul_f32 v[36:37], v[104:105], v[44:45] op_sel_hi:[1,0]
	s_waitcnt lgkmcnt(8)
	s_nop 0
	v_mfma_f32_16x16x32_bf16 v[104:107], v[136:139], v[28:31], v[36:39]
	s_nop 2
	v_mul_f32_e64 v38, v110, v46
	v_mul_f32_e64 v39, v111, v46
	v_pk_mul_f32 v[36:37], v[108:109], v[46:47] op_sel_hi:[1,0]
	s_nop 1
	v_mfma_f32_16x16x32_bf16 v[108:111], v[136:139], v[24:27], v[36:39]
	s_nop 2
	v_mul_f32_e64 v38, v114, v44
	v_mul_f32_e64 v39, v115, v44
	v_pk_mul_f32 v[36:37], v[112:113], v[44:45] op_sel_hi:[1,0]
	s_waitcnt lgkmcnt(6)
	s_nop 0
	v_mfma_f32_16x16x32_bf16 v[112:115], v[132:135], v[28:31], v[36:39]
	s_nop 2
	v_mul_f32_e64 v38, v118, v46
	v_mul_f32_e64 v39, v119, v46
	v_pk_mul_f32 v[36:37], v[116:117], v[46:47] op_sel_hi:[1,0]
	s_nop 1
	v_mfma_f32_16x16x32_bf16 v[116:119], v[132:135], v[24:27], v[36:39]
	s_nop 2
	v_mul_f32_e64 v38, v122, v44
	v_mul_f32_e64 v39, v123, v44
	v_pk_mul_f32 v[36:37], v[120:121], v[44:45] op_sel_hi:[1,0]
	s_waitcnt lgkmcnt(4)
	s_nop 0
	v_mfma_f32_16x16x32_bf16 v[120:123], v[128:131], v[28:31], v[36:39]
	v_mul_f32_e64 v30, v126, v46
	v_mul_f32_e64 v31, v127, v46
	v_pk_mul_f32 v[28:29], v[124:125], v[46:47] op_sel_hi:[1,0]
	s_nop 1
	v_mfma_f32_16x16x32_bf16 v[124:127], v[128:131], v[24:27], v[28:31]
	v_add_u32_e32 v24, 0x120, v149
	v_med3_i32 v24, v24, 0, s75
	v_lshl_add_u32 v24, v24, 9, v152
	global_load_dwordx4 v[28:31], v24, s[98:99]
	v_add_u32_e32 v24, 0x120, v150
	v_med3_i32 v24, v24, 0, s75
	v_lshl_add_u32 v24, v24, 9, v152
	global_load_dwordx4 v[44:47], v24, s[98:99]
	v_add_u32_e32 v24, 0x120, v151
	v_med3_i32 v24, v24, 0, s75
	v_lshl_add_u32 v24, v24, 9, v152
	global_load_dwordx4 v[92:95], v24, s[98:99]
	v_add_u32_e32 v24, 0x120, v252
	v_med3_i32 v24, v24, 0, s75
	v_lshl_add_u32 v24, v24, 9, v152
	global_load_dwordx4 v[100:103], v24, s[98:99]
	v_or_b32_e32 v24, 0x120, v166
	v_add_u32_e32 v24, s76, v24
	v_med3_i32 v24, v24, 0, s75
	v_lshl_add_u32 v24, v24, 9, v158
	global_load_dwordx4 v[72:75], v24, s[100:101]
	global_load_dwordx4 v[68:71], v24, s[100:101] offset:64
	v_or_b32_e32 v24, 0x130, v166
	v_add_u32_e32 v24, s76, v24
	v_med3_i32 v24, v24, 0, s75
	v_lshl_add_u32 v24, v24, 9, v158
	global_load_dwordx4 v[36:39], v24, s[100:101]
	global_load_dwordx4 v[24:27], v24, s[100:101] offset:64
	ds_read_b64_tr_b16 v[142:143], v169 offset:6912
	ds_read_b64_tr_b16 v[140:141], v169 offset:4608
	ds_read_b64_tr_b16 v[136:137], v169 offset:4640
	ds_read_b64_tr_b16 v[138:139], v169 offset:6944
	ds_read_b64_tr_b16 v[132:133], v169 offset:4672
	ds_read_b64_tr_b16 v[134:135], v169 offset:6976
	ds_read_b64_tr_b16 v[128:129], v169 offset:4704
	ds_read_b64_tr_b16 v[130:131], v169 offset:7008
	s_waitcnt vmcnt(15)
	ds_write_b128 v241, v[56:59]
	s_waitcnt vmcnt(14)
	ds_write_b128 v242, v[60:63]
	s_waitcnt vmcnt(13)
	ds_write_b128 v243, v[88:91]
	s_waitcnt vmcnt(12)
	ds_write_b128 v244, v[96:99]
	v_mfma_f32_16x16x32_bf16 v[56:59], v[48:51], v[4:7], 0
	v_mfma_f32_16x16x32_bf16 v[60:63], v[16:19], v[4:7], 0
	v_mfma_f32_16x16x32_bf16 v[16:19], v[16:19], v[12:15], 0
	v_mfma_f32_16x16x32_bf16 v[56:59], v[52:55], v[8:11], v[56:59]
	v_mfma_f32_16x16x32_bf16 v[60:63], v[20:23], v[8:11], v[60:63]
	v_mfma_f32_16x16x32_bf16 v[16:19], v[20:23], v[0:3], v[16:19]
	v_sub_u32_e32 v20, v195, v147
	v_add_u32_e32 v23, 1, v20
	s_nop 3
	v_mfma_f32_16x16x32_bf16 v[48:51], v[48:51], v[12:15], 0
	v_cmp_gt_u32_e64 s[0:1], v23, v146
	v_cmp_gt_u32_e32 vcc, v20, v146
	s_nop 0
	v_cndmask_b32_e64 v57, v57, v246, s[0:1]
	s_nop 0
	v_cndmask_b32_e32 v56, v56, v246, vcc
	v_mfma_f32_16x16x32_bf16 v[48:51], v[52:55], v[0:3], v[48:51]
	v_max_f32_e32 v22, v56, v57
	v_add_u32_e32 v23, 2, v20
	v_add_u32_e32 v52, 3, v20
	v_cmp_gt_u32_e64 s[22:23], v23, v146
	v_cmp_gt_u32_e64 s[24:25], v52, v146
	v_sub_u32_e32 v21, v195, v148
	v_cndmask_b32_e64 v58, v58, v246, s[22:23]
	v_cndmask_b32_e64 v59, v59, v246, s[24:25]
	v_max3_f32 v22, v22, v58, v59
	v_add_u32_e32 v23, 16, v20
	v_add_u32_e32 v52, 17, v20
	v_cmp_gt_u32_e64 s[26:27], v23, v146
	v_cmp_gt_u32_e64 s[28:29], v52, v146
	v_cmp_gt_u32_e64 s[38:39], v21, v145
	v_cndmask_b32_e64 v60, v60, v246, s[26:27]
	v_cndmask_b32_e64 v61, v61, v246, s[28:29]
	v_max3_f32 v22, v22, v60, v61
	v_add_u32_e32 v23, 18, v20
	v_add_u32_e32 v20, 19, v20
	v_cmp_gt_u32_e64 s[30:31], v23, v146
	v_cmp_gt_u32_e64 s[34:35], v20, v146
	v_add_u32_e32 v52, 3, v21
	v_cndmask_b32_e64 v62, v62, v246, s[30:31]
	v_cndmask_b32_e64 v63, v63, v246, s[34:35]
	v_max3_f32 v20, v22, v62, v63
	v_add_u32_e32 v23, 1, v21
	v_cmp_gt_u32_e64 s[40:41], v23, v145
	v_cndmask_b32_e64 v48, v48, v246, s[38:39]
	s_nop 0
	v_cndmask_b32_e64 v49, v49, v246, s[40:41]
	v_max_f32_e32 v22, v48, v49
	v_add_u32_e32 v23, 2, v21
	v_cmp_gt_u32_e64 s[42:43], v23, v145
	v_cmp_gt_u32_e64 s[44:45], v52, v145
	s_nop 0
	v_cndmask_b32_e64 v50, v50, v246, s[42:43]
	v_cndmask_b32_e64 v51, v51, v246, s[44:45]
	v_max3_f32 v22, v22, v50, v51
	v_add_u32_e32 v23, 16, v21
	v_add_u32_e32 v52, 17, v21
	v_cmp_gt_u32_e64 s[46:47], v23, v145
	v_cmp_gt_u32_e64 s[48:49], v52, v145
	s_nop 0
	v_cndmask_b32_e64 v16, v16, v246, s[46:47]
	v_cndmask_b32_e64 v17, v17, v246, s[48:49]
	v_max3_f32 v22, v22, v16, v17
	v_add_u32_e32 v23, 18, v21
	v_add_u32_e32 v21, 19, v21
	v_cmp_gt_u32_e64 s[50:51], v23, v145
	v_cmp_gt_u32_e64 s[52:53], v21, v145
	s_nop 0
	v_cndmask_b32_e64 v18, v18, v246, s[50:51]
	v_cndmask_b32_e64 v19, v19, v246, s[52:53]
	v_max3_f32 v21, v22, v18, v19
	v_mov_b32_e32 v22, v20
	s_nop 1
	v_permlane32_swap_b32_e32 v22, v20
	v_max_f32_e32 v20, v20, v22
	v_mov_b32_e32 v22, v21
	s_nop 1
	v_permlane32_swap_b32_e32 v22, v21
	v_max_f32_e32 v21, v21, v22
	v_mov_b32_e32 v22, v20
	s_nop 1
	v_permlane16_swap_b32_e32 v22, v20
	v_max3_f32 v149, v175, v20, v22
	v_sub_f32_e32 v20, v175, v149
	v_exp_f32_e32 v88, v20
	v_sub_f32_e32 v20, v56, v149
	v_sub_f32_e32 v56, v61, v149
	v_exp_f32_e32 v56, v56
	v_exp_f32_e32 v20, v20
	v_sub_f32_e32 v23, v57, v149
	v_exp_f32_e32 v23, v23
	v_sub_f32_e32 v53, v58, v149
	v_cndmask_b32_e64 v58, v56, 0, s[28:29]
	v_sub_f32_e32 v56, v62, v149
	v_mov_b32_e32 v22, v21
	v_exp_f32_e32 v53, v53
	v_sub_f32_e32 v54, v59, v149
	v_exp_f32_e32 v56, v56
	v_permlane16_swap_b32_e32 v22, v21
	v_exp_f32_e32 v54, v54
	v_sub_f32_e32 v55, v60, v149
	v_exp_f32_e32 v55, v55
	v_max_f32_e32 v21, v21, v22
	v_add_f32_e32 v22, v23, v20
	v_cndmask_b32_e64 v59, v56, 0, s[30:31]
	v_sub_f32_e32 v56, v63, v149
	v_add_f32_e32 v22, v53, v22
	v_exp_f32_e32 v56, v56
	v_add_f32_e32 v22, v54, v22
	v_add_f32_e32 v22, v55, v22
	v_add_f32_e32 v22, v58, v22
	v_max_f32_e32 v151, v181, v21
	v_add_f32_e32 v22, v59, v22
	v_cndmask_b32_e64 v60, v56, 0, s[34:35]
	v_cvt_pk_bf16_f32 v56, v20, v23
	v_sub_f32_e32 v20, v181, v151
	v_add_f32_e32 v150, v60, v22
	v_cvt_pk_bf16_f32 v59, v59, v60
	v_exp_f32_e32 v60, v20
	v_sub_f32_e32 v20, v48, v151
	v_exp_f32_e32 v20, v20
	v_sub_f32_e32 v22, v49, v151
	v_exp_f32_e32 v22, v22
	v_sub_f32_e32 v23, v50, v151
	v_exp_f32_e32 v23, v23
	v_sub_f32_e32 v48, v51, v151
	v_exp_f32_e32 v48, v48
	v_sub_f32_e32 v16, v16, v151
	v_exp_f32_e32 v16, v16
	v_sub_f32_e32 v17, v17, v151
	v_exp_f32_e32 v17, v17
	v_add_f32_e32 v21, v22, v20
	v_add_f32_e32 v21, v23, v21
	v_add_f32_e32 v21, v48, v21
	v_cndmask_b32_e64 v49, v16, 0, s[46:47]
	v_add_f32_e32 v16, v49, v21
	v_cndmask_b32_e64 v21, v17, 0, s[48:49]
	v_sub_f32_e32 v17, v18, v151
	v_exp_f32_e32 v17, v17
	v_add_f32_e32 v16, v21, v16
	v_cvt_pk_bf16_f32 v18, v49, v21
	v_cvt_pk_bf16_f32 v57, v53, v54
	v_cndmask_b32_e64 v50, v17, 0, s[50:51]
	v_sub_f32_e32 v17, v19, v151
	v_exp_f32_e32 v17, v17
	v_add_f32_e32 v16, v50, v16
	v_cvt_pk_bf16_f32 v58, v55, v58
	v_fmac_f32_e32 v150, v176, v88
	v_cndmask_b32_e64 v19, v17, 0, s[52:53]
	v_add_f32_e32 v175, v19, v16
	v_cvt_pk_bf16_f32 v16, v20, v22
	v_cvt_pk_bf16_f32 v17, v23, v48
	v_cvt_pk_bf16_f32 v19, v50, v19
	v_pk_mul_f32 v[50:51], v[86:87], v[60:61] op_sel_hi:[1,0]
	v_pk_mul_f32 v[48:49], v[84:85], v[60:61] op_sel_hi:[1,0]
	v_pk_mul_f32 v[22:23], v[82:83], v[88:89] op_sel_hi:[1,0]
	v_pk_mul_f32 v[20:21], v[80:81], v[88:89] op_sel_hi:[1,0]
	s_waitcnt lgkmcnt(10)
	v_mfma_f32_16x16x32_bf16 v[52:55], v[140:143], v[16:19], v[48:51]
	v_fmac_f32_e32 v175, v183, v60
	s_nop 1
	v_pk_mul_f32 v[50:51], v[106:107], v[88:89] op_sel_hi:[1,0]
	v_pk_mul_f32 v[48:49], v[104:105], v[88:89] op_sel_hi:[1,0]
	v_mfma_f32_16x16x32_bf16 v[20:23], v[140:143], v[56:59], v[20:23]
	s_waitcnt lgkmcnt(8)
	v_mfma_f32_16x16x32_bf16 v[104:107], v[136:139], v[56:59], v[48:51]
	s_nop 2
	v_mul_f32_e64 v50, v110, v60
	v_mul_f32_e64 v51, v111, v60
	v_pk_mul_f32 v[48:49], v[108:109], v[60:61] op_sel_hi:[1,0]
	s_nop 1
	v_mfma_f32_16x16x32_bf16 v[108:111], v[136:139], v[16:19], v[48:51]
	s_nop 2
	v_mul_f32_e64 v50, v114, v88
	v_mul_f32_e64 v51, v115, v88
	v_pk_mul_f32 v[48:49], v[112:113], v[88:89] op_sel_hi:[1,0]
	s_waitcnt lgkmcnt(6)
	s_nop 0
	v_mfma_f32_16x16x32_bf16 v[112:115], v[132:135], v[56:59], v[48:51]
	s_nop 2
	v_mul_f32_e64 v50, v118, v60
	v_mul_f32_e64 v51, v119, v60
	v_pk_mul_f32 v[48:49], v[116:117], v[60:61] op_sel_hi:[1,0]
	s_nop 1
	v_mfma_f32_16x16x32_bf16 v[116:119], v[132:135], v[16:19], v[48:51]
	s_nop 2
	v_mul_f32_e64 v50, v122, v88
	v_mul_f32_e64 v51, v123, v88
	v_pk_mul_f32 v[48:49], v[120:121], v[88:89] op_sel_hi:[1,0]
	s_waitcnt lgkmcnt(4)
	s_nop 0
	v_mfma_f32_16x16x32_bf16 v[120:123], v[128:131], v[56:59], v[48:51]
	v_add_u32_e32 v56, 0xffffff00, v206
	v_add_u32_e32 v56, s76, v56
	s_nop 0
	v_pk_mul_f32 v[50:51], v[126:127], v[60:61] op_sel_hi:[1,0]
	v_pk_mul_f32 v[48:49], v[124:125], v[60:61] op_sel_hi:[1,0]
	s_nop 1
	v_mfma_f32_16x16x32_bf16 v[124:127], v[128:131], v[16:19], v[48:51]
	v_add_u32_e32 v16, 0xffffff00, v204
	v_add_u32_e32 v16, s76, v16
	s_nop 0
	v_add_u32_e32 v48, 0xffffff00, v205
	v_add_u32_e32 v48, s76, v48
	v_med3_i32 v16, v16, 0, s75
	v_med3_i32 v48, v48, 0, s75
	v_med3_i32 v56, v56, 0, s75
	v_lshl_add_u32 v56, v56, 9, v152
	global_load_dwordx4 v[88:91], v56, s[98:99]
	v_add_u32_e32 v56, 0xffffff00, v207
	v_add_u32_e32 v56, s76, v56
	v_med3_i32 v56, v56, 0, s75
	v_lshl_add_u32 v56, v56, 9, v152
	global_load_dwordx4 v[96:99], v56, s[98:99]
	v_add_u32_e32 v56, s76, v208
	v_lshl_add_u32 v16, v16, 9, v152
	v_lshl_add_u32 v48, v48, 9, v152
	v_med3_i32 v56, v56, 0, s75
	v_lshl_add_u32 v56, v56, 9, v158
	global_load_dwordx4 v[16:19], v16, s[98:99]
	global_load_dwordx4 v[48:51], v48, s[98:99]
	global_load_dwordx4 v[84:87], v56, s[100:101]
	global_load_dwordx4 v[80:83], v56, s[100:101] offset:64
	v_or_b32_e32 v56, 0xffffff40, v209
	v_add_u32_e32 v56, s76, v56
	v_med3_i32 v56, v56, 0, s75
	v_lshl_add_u32 v56, v56, 9, v158
	global_load_dwordx4 v[60:63], v56, s[100:101]
	global_load_dwordx4 v[56:59], v56, s[100:101] offset:64
	ds_read_b64_tr_b16 v[142:143], v169 offset:2304
	ds_read_b64_tr_b16 v[140:141], v169
	ds_read_b64_tr_b16 v[136:137], v169 offset:32
	ds_read_b64_tr_b16 v[138:139], v169 offset:2336
	ds_read_b64_tr_b16 v[132:133], v169 offset:64
	ds_read_b64_tr_b16 v[134:135], v169 offset:2368
	ds_read_b64_tr_b16 v[128:129], v169 offset:96
	ds_read_b64_tr_b16 v[130:131], v169 offset:2400
	s_waitcnt vmcnt(15)
	ds_write_b128 v241, v[28:31] offset:4608
	s_waitcnt vmcnt(14)
	ds_write_b128 v242, v[44:47] offset:4608
	s_waitcnt vmcnt(13)
	ds_write_b128 v243, v[92:95] offset:4608
	s_waitcnt vmcnt(12)
	ds_write_b128 v244, v[100:103] offset:4608
	v_mfma_f32_16x16x32_bf16 v[28:31], v[76:79], v[4:7], 0
	v_mfma_f32_16x16x32_bf16 v[44:47], v[40:43], v[4:7], 0
	v_mfma_f32_16x16x32_bf16 v[40:43], v[40:43], v[12:15], 0
	v_mfma_f32_16x16x32_bf16 v[28:31], v[64:67], v[8:11], v[28:31]
	v_mfma_f32_16x16x32_bf16 v[44:47], v[32:35], v[8:11], v[44:47]
	v_mfma_f32_16x16x32_bf16 v[32:35], v[32:35], v[0:3], v[40:43]
	s_nop 4
	v_sub_u32_e32 v40, v210, v147
	v_mfma_f32_16x16x32_bf16 v[76:79], v[76:79], v[12:15], 0
	v_add_u32_e32 v43, 1, v40
	v_cmp_gt_u32_e64 s[0:1], v43, v146
	v_cmp_gt_u32_e32 vcc, v40, v146
	s_nop 0
	v_cndmask_b32_e64 v29, v29, v246, s[0:1]
	s_nop 0
	v_cndmask_b32_e32 v28, v28, v246, vcc
	v_mfma_f32_16x16x32_bf16 v[64:67], v[64:67], v[0:3], v[76:79]
	v_max_f32_e32 v42, v28, v29
	v_add_u32_e32 v43, 2, v40
	v_cmp_gt_u32_e64 s[22:23], v43, v146
	v_add_u32_e32 v76, 3, v40
	v_cmp_gt_u32_e64 s[24:25], v76, v146
	v_cndmask_b32_e64 v30, v30, v246, s[22:23]
	v_sub_u32_e32 v41, v210, v148
	v_cndmask_b32_e64 v31, v31, v246, s[24:25]
	v_max3_f32 v42, v42, v30, v31
	v_add_u32_e32 v43, 16, v40
	v_add_u32_e32 v76, 17, v40
	v_cmp_gt_u32_e64 s[26:27], v43, v146
	v_cmp_gt_u32_e64 s[28:29], v76, v146
	v_cmp_gt_u32_e64 s[38:39], v41, v145
	v_cndmask_b32_e64 v44, v44, v246, s[26:27]
	v_cndmask_b32_e64 v45, v45, v246, s[28:29]
	v_max3_f32 v42, v42, v44, v45
	v_add_u32_e32 v43, 18, v40
	v_add_u32_e32 v40, 19, v40
	v_cmp_gt_u32_e64 s[30:31], v43, v146
	v_cmp_gt_u32_e64 s[34:35], v40, v146
	v_add_u32_e32 v76, 3, v41
	v_cndmask_b32_e64 v46, v46, v246, s[30:31]
	v_cndmask_b32_e64 v47, v47, v246, s[34:35]
	v_max3_f32 v40, v42, v46, v47
	v_add_u32_e32 v43, 1, v41
	v_cmp_gt_u32_e64 s[40:41], v43, v145
	v_cndmask_b32_e64 v64, v64, v246, s[38:39]
	s_nop 0
	v_cndmask_b32_e64 v65, v65, v246, s[40:41]
	v_max_f32_e32 v42, v64, v65
	v_add_u32_e32 v43, 2, v41
	v_cmp_gt_u32_e64 s[42:43], v43, v145
	v_cmp_gt_u32_e64 s[44:45], v76, v145
	s_nop 0
	v_cndmask_b32_e64 v66, v66, v246, s[42:43]
	v_cndmask_b32_e64 v67, v67, v246, s[44:45]
	v_max3_f32 v42, v42, v66, v67
	v_add_u32_e32 v43, 16, v41
	v_add_u32_e32 v76, 17, v41
	v_cmp_gt_u32_e64 s[46:47], v43, v145
	v_cmp_gt_u32_e64 s[48:49], v76, v145
	s_nop 0
	v_cndmask_b32_e64 v32, v32, v246, s[46:47]
	v_cndmask_b32_e64 v33, v33, v246, s[48:49]
	v_max3_f32 v42, v42, v32, v33
	v_add_u32_e32 v43, 18, v41
	v_add_u32_e32 v41, 19, v41
	v_cmp_gt_u32_e64 s[50:51], v43, v145
	v_cmp_gt_u32_e64 s[52:53], v41, v145
	s_nop 0
	v_cndmask_b32_e64 v34, v34, v246, s[50:51]
	v_cndmask_b32_e64 v35, v35, v246, s[52:53]
	v_max3_f32 v41, v42, v34, v35
	v_mov_b32_e32 v42, v40
	s_nop 1
	v_permlane32_swap_b32_e32 v42, v40
	v_max_f32_e32 v40, v40, v42
	v_mov_b32_e32 v42, v41
	s_nop 1
	v_permlane32_swap_b32_e32 v42, v41
	v_max_f32_e32 v41, v41, v42
	v_mov_b32_e32 v42, v40
	s_nop 1
	v_permlane16_swap_b32_e32 v42, v40
	v_max3_f32 v176, v149, v40, v42
	v_sub_f32_e32 v28, v28, v176
	v_mov_b32_e32 v42, v41
	v_exp_f32_e32 v28, v28
	v_sub_f32_e32 v29, v29, v176
	v_permlane16_swap_b32_e32 v42, v41
	v_exp_f32_e32 v29, v29
	v_sub_f32_e32 v30, v30, v176
	v_exp_f32_e32 v30, v30
	v_sub_f32_e32 v31, v31, v176
	v_max_f32_e32 v41, v41, v42
	v_exp_f32_e32 v31, v31
	v_sub_f32_e32 v42, v44, v176
	v_sub_f32_e32 v40, v149, v176
	v_exp_f32_e32 v42, v42
	v_sub_f32_e32 v43, v45, v176
	v_exp_f32_e32 v76, v40
	v_exp_f32_e32 v43, v43
	v_sub_f32_e32 v44, v46, v176
	v_add_f32_e32 v40, v29, v28
	v_exp_f32_e32 v44, v44
	v_sub_f32_e32 v45, v47, v176
	v_add_f32_e32 v40, v30, v40
	v_exp_f32_e32 v45, v45
	v_add_f32_e32 v40, v31, v40
	v_add_f32_e32 v40, v42, v40
	v_add_f32_e32 v40, v43, v40
	v_add_f32_e32 v40, v44, v40
	v_add_f32_e32 v149, v45, v40
	v_fmac_f32_e32 v149, v150, v76
	v_max_f32_e32 v150, v151, v41
	v_sub_f32_e32 v40, v151, v150
	v_cvt_pk_bf16_f32 v28, v28, v29
	v_cvt_pk_bf16_f32 v29, v30, v31
	v_cvt_pk_bf16_f32 v31, v44, v45
	v_exp_f32_e32 v44, v40
	v_sub_f32_e32 v40, v64, v150
	v_cvt_pk_bf16_f32 v30, v42, v43
	v_exp_f32_e32 v40, v40
	v_sub_f32_e32 v42, v65, v150
	v_exp_f32_e32 v42, v42
	v_sub_f32_e32 v43, v66, v150
	v_exp_f32_e32 v43, v43
	v_sub_f32_e32 v45, v67, v150
	v_exp_f32_e32 v45, v45
	v_sub_f32_e32 v32, v32, v150
	v_exp_f32_e32 v32, v32
	v_sub_f32_e32 v33, v33, v150
	v_exp_f32_e32 v33, v33
	v_add_f32_e32 v41, v42, v40
	v_add_f32_e32 v41, v43, v41
	v_add_f32_e32 v41, v45, v41
	v_cndmask_b32_e64 v46, v32, 0, s[46:47]
	v_add_f32_e32 v32, v46, v41
	v_cndmask_b32_e64 v41, v33, 0, s[48:49]
	v_sub_f32_e32 v33, v34, v150
	v_exp_f32_e32 v33, v33
	v_add_f32_e32 v32, v41, v32
	v_pk_mul_f32 v[22:23], v[22:23], v[76:77] op_sel_hi:[1,0]
	v_pk_mul_f32 v[20:21], v[20:21], v[76:77] op_sel_hi:[1,0]
	v_cndmask_b32_e64 v47, v33, 0, s[50:51]
	v_sub_f32_e32 v33, v35, v150
	v_exp_f32_e32 v33, v33
	v_add_f32_e32 v32, v47, v32
	v_cvt_pk_bf16_f32 v34, v46, v41
	v_cndmask_b32_e64 v35, v33, 0, s[52:53]
	v_add_f32_e32 v151, v35, v32
	v_cvt_pk_bf16_f32 v32, v40, v42
	v_cvt_pk_bf16_f32 v33, v43, v45
	v_cvt_pk_bf16_f32 v35, v47, v35
	s_waitcnt lgkmcnt(10)
	v_mfma_f32_16x16x32_bf16 v[40:43], v[140:143], v[28:31], v[20:23]
	v_fmac_f32_e32 v151, v175, v44
	s_nop 1
	v_pk_mul_f32 v[22:23], v[54:55], v[44:45] op_sel_hi:[1,0]
	v_pk_mul_f32 v[20:21], v[52:53], v[44:45] op_sel_hi:[1,0]
	s_nop 1
	v_mfma_f32_16x16x32_bf16 v[92:95], v[140:143], v[32:35], v[20:23]
	s_nop 2
	v_mul_f32_e64 v22, v106, v76
	v_mul_f32_e64 v23, v107, v76
	v_pk_mul_f32 v[20:21], v[104:105], v[76:77] op_sel_hi:[1,0]
	s_waitcnt lgkmcnt(8)
	s_nop 0
	v_mfma_f32_16x16x32_bf16 v[104:107], v[136:139], v[28:31], v[20:23]
	s_nop 2
	v_mul_f32_e64 v22, v110, v44
	v_mul_f32_e64 v23, v111, v44
	v_pk_mul_f32 v[20:21], v[108:109], v[44:45] op_sel_hi:[1,0]
	s_nop 1
	v_mfma_f32_16x16x32_bf16 v[108:111], v[136:139], v[32:35], v[20:23]
	s_nop 2
	v_mul_f32_e64 v22, v114, v76
	v_mul_f32_e64 v23, v115, v76
	v_pk_mul_f32 v[20:21], v[112:113], v[76:77] op_sel_hi:[1,0]
	s_waitcnt lgkmcnt(6)
	s_nop 0
	v_mfma_f32_16x16x32_bf16 v[112:115], v[132:135], v[28:31], v[20:23]
	s_nop 2
	v_mul_f32_e64 v22, v118, v44
	v_mul_f32_e64 v23, v119, v44
	v_pk_mul_f32 v[20:21], v[116:117], v[44:45] op_sel_hi:[1,0]
	s_nop 1
	v_mfma_f32_16x16x32_bf16 v[116:119], v[132:135], v[32:35], v[20:23]
	s_nop 2
	v_mul_f32_e64 v22, v122, v76
	v_mul_f32_e64 v23, v123, v76
	v_pk_mul_f32 v[20:21], v[120:121], v[76:77] op_sel_hi:[1,0]
	s_waitcnt lgkmcnt(4)
	s_nop 0
	v_mfma_f32_16x16x32_bf16 v[120:123], v[128:131], v[28:31], v[20:23]
	s_nop 2
	v_mul_f32_e64 v22, v126, v44
	v_mul_f32_e64 v23, v127, v44
	v_pk_mul_f32 v[20:21], v[124:125], v[44:45] op_sel_hi:[1,0]
	s_nop 1
	v_mfma_f32_16x16x32_bf16 v[124:127], v[128:131], v[32:35], v[20:23]
	s_nop 2
	v_add_u32_e32 v20, 0xffffff80, v204
	v_add_u32_e32 v20, s76, v20
	v_med3_i32 v20, v20, 0, s75
	v_lshl_add_u32 v20, v20, 9, v152
	global_load_dwordx4 v[32:35], v20, s[98:99]
	v_add_u32_e32 v20, 0xffffff80, v205
	v_add_u32_e32 v20, s76, v20
	v_med3_i32 v20, v20, 0, s75
	v_lshl_add_u32 v20, v20, 9, v152
	global_load_dwordx4 v[64:67], v20, s[98:99]
	v_add_u32_e32 v20, 0xffffff80, v206
	v_add_u32_e32 v20, s76, v20
	v_med3_i32 v20, v20, 0, s75
	v_lshl_add_u32 v20, v20, 9, v152
	global_load_dwordx4 v[76:79], v20, s[98:99]
	v_add_u32_e32 v20, 0xffffff80, v207
	v_add_u32_e32 v20, s76, v20
	v_med3_i32 v20, v20, 0, s75
	v_lshl_add_u32 v20, v20, 9, v152
	global_load_dwordx4 v[100:103], v20, s[98:99]
	v_or_b32_e32 v20, 0xffffff80, v209
	v_add_u32_e32 v20, s76, v20
	v_med3_i32 v20, v20, 0, s75
	v_lshl_add_u32 v20, v20, 9, v158
	global_load_dwordx4 v[52:55], v20, s[100:101]
	global_load_dwordx4 v[44:47], v20, s[100:101] offset:64
	v_add_u32_e32 v20, s76, v211
	v_med3_i32 v20, v20, 0, s75
	v_lshl_add_u32 v20, v20, 9, v158
	global_load_dwordx4 v[28:31], v20, s[100:101]
	global_load_dwordx4 v[20:23], v20, s[100:101] offset:64
	ds_read_b64_tr_b16 v[142:143], v169 offset:6912
	ds_read_b64_tr_b16 v[140:141], v169 offset:4608
	ds_read_b64_tr_b16 v[136:137], v169 offset:4640
	ds_read_b64_tr_b16 v[138:139], v169 offset:6944
	ds_read_b64_tr_b16 v[132:133], v169 offset:4672
	ds_read_b64_tr_b16 v[134:135], v169 offset:6976
	ds_read_b64_tr_b16 v[128:129], v169 offset:4704
	ds_read_b64_tr_b16 v[130:131], v169 offset:7008
	s_waitcnt vmcnt(13)
	ds_write_b128 v241, v[16:19]
	s_waitcnt vmcnt(12)
	ds_write_b128 v242, v[48:51]
	ds_write_b128 v243, v[88:91]
	ds_write_b128 v244, v[96:99]
	v_mfma_f32_16x16x32_bf16 v[16:19], v[72:75], v[4:7], 0
	v_mfma_f32_16x16x32_bf16 v[48:51], v[36:39], v[4:7], 0
	v_mfma_f32_16x16x32_bf16 v[36:39], v[36:39], v[12:15], 0
	v_mfma_f32_16x16x32_bf16 v[16:19], v[68:71], v[8:11], v[16:19]
	v_mfma_f32_16x16x32_bf16 v[48:51], v[24:27], v[8:11], v[48:51]
	v_mfma_f32_16x16x32_bf16 v[24:27], v[24:27], v[0:3], v[36:39]
	s_nop 4
	v_sub_u32_e32 v36, v212, v147
	v_mfma_f32_16x16x32_bf16 v[72:75], v[72:75], v[12:15], 0
	v_add_u32_e32 v39, 1, v36
	v_cmp_gt_u32_e64 s[0:1], v39, v146
	v_cmp_gt_u32_e32 vcc, v36, v146
	s_nop 0
	v_cndmask_b32_e64 v17, v17, v246, s[0:1]
	s_nop 0
	v_cndmask_b32_e32 v16, v16, v246, vcc
	v_mfma_f32_16x16x32_bf16 v[68:71], v[68:71], v[0:3], v[72:75]
	v_max_f32_e32 v38, v16, v17
	v_add_u32_e32 v39, 2, v36
	v_cmp_gt_u32_e64 s[22:23], v39, v146
	v_add_u32_e32 v72, 3, v36
	v_cmp_gt_u32_e64 s[24:25], v72, v146
	v_cndmask_b32_e64 v18, v18, v246, s[22:23]
	v_sub_u32_e32 v37, v212, v148
	v_cndmask_b32_e64 v19, v19, v246, s[24:25]
	v_max3_f32 v38, v38, v18, v19
	v_add_u32_e32 v39, 16, v36
	v_add_u32_e32 v72, 17, v36
	v_cmp_gt_u32_e64 s[26:27], v39, v146
	v_cmp_gt_u32_e64 s[28:29], v72, v146
	v_cmp_gt_u32_e64 s[38:39], v37, v145
	v_cndmask_b32_e64 v48, v48, v246, s[26:27]
	v_cndmask_b32_e64 v49, v49, v246, s[28:29]
	v_max3_f32 v38, v38, v48, v49
	v_add_u32_e32 v39, 18, v36
	v_add_u32_e32 v36, 19, v36
	v_cmp_gt_u32_e64 s[30:31], v39, v146
	v_cmp_gt_u32_e64 s[34:35], v36, v146
	v_add_u32_e32 v72, 3, v37
	v_cndmask_b32_e64 v50, v50, v246, s[30:31]
	v_cndmask_b32_e64 v51, v51, v246, s[34:35]
	v_max3_f32 v36, v38, v50, v51
	v_add_u32_e32 v39, 1, v37
	v_cmp_gt_u32_e64 s[40:41], v39, v145
	v_cndmask_b32_e64 v68, v68, v246, s[38:39]
	s_nop 0
	v_cndmask_b32_e64 v69, v69, v246, s[40:41]
	v_max_f32_e32 v38, v68, v69
	v_add_u32_e32 v39, 2, v37
	v_cmp_gt_u32_e64 s[42:43], v39, v145
	v_cmp_gt_u32_e64 s[44:45], v72, v145
	s_nop 0
	v_cndmask_b32_e64 v70, v70, v246, s[42:43]
	v_cndmask_b32_e64 v71, v71, v246, s[44:45]
	v_max3_f32 v38, v38, v70, v71
	v_add_u32_e32 v39, 16, v37
	v_add_u32_e32 v72, 17, v37
	v_cmp_gt_u32_e64 s[46:47], v39, v145
	v_cmp_gt_u32_e64 s[48:49], v72, v145
	s_nop 0
	v_cndmask_b32_e64 v24, v24, v246, s[46:47]
	v_cndmask_b32_e64 v25, v25, v246, s[48:49]
	v_max3_f32 v38, v38, v24, v25
	v_add_u32_e32 v39, 18, v37
	v_add_u32_e32 v37, 19, v37
	v_cmp_gt_u32_e64 s[50:51], v39, v145
	v_cmp_gt_u32_e64 s[52:53], v37, v145
	s_nop 0
	v_cndmask_b32_e64 v26, v26, v246, s[50:51]
	v_cndmask_b32_e64 v27, v27, v246, s[52:53]
	v_max3_f32 v37, v38, v26, v27
	v_mov_b32_e32 v38, v36
	s_nop 1
	v_permlane32_swap_b32_e32 v38, v36
	v_max_f32_e32 v36, v36, v38
	v_mov_b32_e32 v38, v37
	s_nop 1
	v_permlane32_swap_b32_e32 v38, v37
	v_max_f32_e32 v37, v37, v38
	v_mov_b32_e32 v38, v36
	s_nop 1
	v_permlane16_swap_b32_e32 v38, v36
	v_max3_f32 v145, v176, v36, v38
	v_sub_f32_e32 v16, v16, v145
	v_mov_b32_e32 v38, v37
	v_exp_f32_e32 v16, v16
	v_sub_f32_e32 v17, v17, v145
	v_permlane16_swap_b32_e32 v38, v37
	v_exp_f32_e32 v17, v17
	v_sub_f32_e32 v18, v18, v145
	v_exp_f32_e32 v18, v18
	v_sub_f32_e32 v19, v19, v145
	v_max_f32_e32 v37, v37, v38
	v_exp_f32_e32 v19, v19
	v_sub_f32_e32 v38, v48, v145
	v_sub_f32_e32 v36, v176, v145
	v_exp_f32_e32 v38, v38
	v_sub_f32_e32 v39, v49, v145
	v_exp_f32_e32 v88, v36
	v_exp_f32_e32 v39, v39
	v_sub_f32_e32 v48, v50, v145
	v_add_f32_e32 v36, v17, v16
	v_exp_f32_e32 v48, v48
	v_sub_f32_e32 v49, v51, v145
	v_add_f32_e32 v36, v18, v36
	v_exp_f32_e32 v49, v49
	v_add_f32_e32 v36, v19, v36
	v_add_f32_e32 v36, v38, v36
	v_add_f32_e32 v36, v39, v36
	v_add_f32_e32 v36, v48, v36
	v_max_f32_e32 v147, v150, v37
	v_add_f32_e32 v146, v49, v36
	v_sub_f32_e32 v36, v150, v147
	v_cvt_pk_bf16_f32 v16, v16, v17
	v_cvt_pk_bf16_f32 v17, v18, v19
	v_cvt_pk_bf16_f32 v19, v48, v49
	v_exp_f32_e32 v48, v36
	v_sub_f32_e32 v36, v68, v147
	v_cvt_pk_bf16_f32 v18, v38, v39
	v_exp_f32_e32 v36, v36
	v_sub_f32_e32 v38, v69, v147
	v_exp_f32_e32 v38, v38
	v_sub_f32_e32 v39, v70, v147
	v_exp_f32_e32 v39, v39
	v_sub_f32_e32 v49, v71, v147
	v_exp_f32_e32 v49, v49
	v_sub_f32_e32 v24, v24, v147
	v_exp_f32_e32 v24, v24
	v_sub_f32_e32 v25, v25, v147
	v_exp_f32_e32 v25, v25
	v_add_f32_e32 v37, v38, v36
	v_add_f32_e32 v37, v39, v37
	v_add_f32_e32 v37, v49, v37
	v_cndmask_b32_e64 v50, v24, 0, s[46:47]
	v_add_f32_e32 v24, v50, v37
	v_cndmask_b32_e64 v37, v25, 0, s[48:49]
	v_sub_f32_e32 v25, v26, v147
	v_exp_f32_e32 v25, v25
	v_add_f32_e32 v24, v37, v24
	v_cvt_pk_bf16_f32 v26, v50, v37
	v_cmp_lt_i32_e32 vcc, -1, v184
	v_cndmask_b32_e64 v51, v25, 0, s[50:51]
	v_sub_f32_e32 v25, v27, v147
	v_exp_f32_e32 v25, v25
	v_add_f32_e32 v24, v51, v24
	v_fmac_f32_e32 v146, v149, v88
	s_add_i32 s0, s76, 0xffffff00
	v_cndmask_b32_e64 v27, v25, 0, s[52:53]
	v_add_f32_e32 v183, v27, v24
	v_cvt_pk_bf16_f32 v24, v36, v38
	v_cvt_pk_bf16_f32 v25, v39, v49
	v_cvt_pk_bf16_f32 v27, v51, v27
	v_pk_mul_f32 v[38:39], v[42:43], v[88:89] op_sel_hi:[1,0]
	v_pk_mul_f32 v[36:37], v[40:41], v[88:89] op_sel_hi:[1,0]
	v_pk_mul_f32 v[42:43], v[94:95], v[48:49] op_sel_hi:[1,0]
	v_pk_mul_f32 v[40:41], v[92:93], v[48:49] op_sel_hi:[1,0]
	s_waitcnt lgkmcnt(10)
	v_mfma_f32_16x16x32_bf16 v[36:39], v[140:143], v[16:19], v[36:39]
	v_fmac_f32_e32 v183, v151, v48
	s_min_i32 s1, s0, 0
	s_sub_i32 s1, 3, s1
	v_mfma_f32_16x16x32_bf16 v[68:71], v[140:143], v[24:27], v[40:43]
	s_ashr_i32 s1, s1, 2
	s_sub_i32 s22, 0x200, s76
	s_sub_i32 s0, s75, s0
	v_pk_mul_f32 v[42:43], v[106:107], v[88:89] op_sel_hi:[1,0]
	v_pk_mul_f32 v[40:41], v[104:105], v[88:89] op_sel_hi:[1,0]
	s_ashr_i32 s0, s0, 2
	s_cmp_lt_i32 s76, 0
	s_waitcnt lgkmcnt(8)
	v_mfma_f32_16x16x32_bf16 v[72:75], v[136:139], v[16:19], v[40:43]
	s_nop 2
	v_mul_f32_e64 v42, v110, v48
	v_mul_f32_e64 v43, v111, v48
	v_pk_mul_f32 v[40:41], v[108:109], v[48:49] op_sel_hi:[1,0]
	s_nop 1
	v_mfma_f32_16x16x32_bf16 v[104:107], v[136:139], v[24:27], v[40:43]
	s_nop 2
	v_mul_f32_e64 v42, v114, v88
	v_mul_f32_e64 v43, v115, v88
	v_pk_mul_f32 v[40:41], v[112:113], v[88:89] op_sel_hi:[1,0]
	s_waitcnt lgkmcnt(6)
	s_nop 0
	v_mfma_f32_16x16x32_bf16 v[108:111], v[132:135], v[16:19], v[40:43]
	s_nop 2
	v_mul_f32_e64 v42, v118, v48
	v_mul_f32_e64 v43, v119, v48
	v_pk_mul_f32 v[40:41], v[116:117], v[48:49] op_sel_hi:[1,0]
	s_nop 1
	v_mfma_f32_16x16x32_bf16 v[112:115], v[132:135], v[24:27], v[40:43]
	s_nop 2
	v_mul_f32_e64 v42, v122, v88
	v_mul_f32_e64 v43, v123, v88
	v_pk_mul_f32 v[40:41], v[120:121], v[88:89] op_sel_hi:[1,0]
	s_waitcnt lgkmcnt(4)
	s_nop 0
	v_mfma_f32_16x16x32_bf16 v[116:119], v[128:131], v[16:19], v[40:43]
	v_mul_f32_e64 v18, v126, v48
	v_mul_f32_e64 v19, v127, v48
	v_pk_mul_f32 v[16:17], v[124:125], v[48:49] op_sel_hi:[1,0]
	s_nop 1
	v_mfma_f32_16x16x32_bf16 v[128:131], v[128:131], v[24:27], v[16:19]
	s_nop 2
	v_min_i32_e32 v16, s75, v184
	v_cndmask_b32_e32 v16, 0, v16, vcc
	v_lshl_add_u32 v16, v16, 9, v152
	global_load_dwordx4 v[88:91], v16, s[98:99]
	v_med3_i32 v16, v185, 0, s75
	v_lshl_add_u32 v16, v16, 9, v152
	global_load_dwordx4 v[92:95], v16, s[98:99]
	v_med3_i32 v16, v186, 0, s75
	v_lshl_add_u32 v16, v16, 9, v152
	global_load_dwordx4 v[120:123], v16, s[98:99]
	v_med3_i32 v16, v188, 0, s75
	v_lshl_add_u32 v16, v16, 9, v152
	global_load_dwordx4 v[124:127], v16, s[98:99]
	v_add_u32_e32 v16, s76, v209
	v_med3_i32 v16, v16, 0, s75
	v_lshl_add_u32 v16, v16, 9, v158
	global_load_dwordx4 v[48:51], v16, s[100:101]
	global_load_dwordx4 v[40:43], v16, s[100:101] offset:64
	v_or_b32_e32 v16, 64, v209
	v_add_u32_e32 v16, s76, v16
	v_med3_i32 v16, v16, 0, s75
	v_lshl_add_u32 v16, v16, 9, v158
	global_load_dwordx4 v[24:27], v16, s[100:101]
	global_load_dwordx4 v[16:19], v16, s[100:101] offset:64
	ds_read_b64_tr_b16 v[98:99], v169 offset:2304
	ds_read_b64_tr_b16 v[96:97], v169
	ds_read_b64_tr_b16 v[140:141], v169 offset:32
	ds_read_b64_tr_b16 v[142:143], v169 offset:2336
	ds_read_b64_tr_b16 v[136:137], v169 offset:64
	ds_read_b64_tr_b16 v[138:139], v169 offset:2368
	ds_read_b64_tr_b16 v[132:133], v169 offset:96
	ds_read_b64_tr_b16 v[134:135], v169 offset:2400
	s_waitcnt vmcnt(15)
	ds_write_b128 v241, v[32:35] offset:4608
	s_waitcnt vmcnt(14)
	ds_write_b128 v242, v[64:67] offset:4608
	s_waitcnt vmcnt(13)
	ds_write_b128 v243, v[76:79] offset:4608
	s_waitcnt vmcnt(12)
	ds_write_b128 v244, v[100:103] offset:4608
	v_mfma_f32_16x16x32_bf16 v[64:67], v[60:63], v[4:7], 0
	v_mfma_f32_16x16x32_bf16 v[60:63], v[60:63], v[12:15], 0
	v_mfma_f32_16x16x32_bf16 v[32:35], v[84:87], v[4:7], 0
	v_mfma_f32_16x16x32_bf16 v[64:67], v[56:59], v[8:11], v[64:67]
	v_mfma_f32_16x16x32_bf16 v[56:59], v[56:59], v[0:3], v[60:63]
	s_nop 4
	v_ashrrev_i32_e32 v60, 2, v250
	v_max_i32_e32 v176, s1, v60
	v_add_u32_e32 v60, s22, v251
	v_ashrrev_i32_e32 v60, 2, v60
	v_min3_i32 v60, v60, s0, v247
	v_mfma_f32_16x16x32_bf16 v[32:35], v[80:83], v[8:11], v[32:35]
	v_sub_u32_e32 v175, v60, v176
	v_ashrrev_i32_e32 v60, 2, v249
	v_max_i32_e32 v181, s1, v60
	v_add_u32_e32 v60, s22, v144
	v_sub_u32_e32 v61, v154, v176
	v_ashrrev_i32_e32 v60, 2, v60
	v_mfma_f32_16x16x32_bf16 v[76:79], v[84:87], v[12:15], 0
	v_min3_i32 v60, v60, s0, v247
	v_add_u32_e32 v63, 1, v61
	v_sub_u32_e32 v252, v60, v181
	v_cmp_gt_u32_e64 s[0:1], v63, v175
	v_cmp_gt_u32_e32 vcc, v61, v175
	s_nop 0
	v_cndmask_b32_e64 v33, v33, v246, s[0:1]
	s_nop 0
	v_cndmask_b32_e32 v32, v32, v246, vcc
	v_mfma_f32_16x16x32_bf16 v[76:79], v[80:83], v[0:3], v[76:79]
	v_max_f32_e32 v60, v32, v33
	v_add_u32_e32 v63, 2, v61
	v_add_u32_e32 v80, 3, v61
	v_cmp_gt_u32_e64 s[22:23], v63, v175
	v_cmp_gt_u32_e64 s[24:25], v80, v175
	v_sub_u32_e32 v62, v154, v181
	v_cndmask_b32_e64 v34, v34, v246, s[22:23]
	v_cndmask_b32_e64 v35, v35, v246, s[24:25]
	v_max3_f32 v60, v60, v34, v35
	v_add_u32_e32 v63, 16, v61
	v_add_u32_e32 v80, 17, v61
	v_cmp_gt_u32_e64 s[26:27], v63, v175
	v_cmp_gt_u32_e64 s[28:29], v80, v175
	v_cmp_gt_u32_e64 s[38:39], v62, v252
	v_cndmask_b32_e64 v64, v64, v246, s[26:27]
	v_cndmask_b32_e64 v65, v65, v246, s[28:29]
	v_max3_f32 v60, v60, v64, v65
	v_add_u32_e32 v63, 18, v61
	v_add_u32_e32 v61, 19, v61
	v_cmp_gt_u32_e64 s[30:31], v63, v175
	v_cmp_gt_u32_e64 s[34:35], v61, v175
	v_add_u32_e32 v80, 3, v62
	v_cndmask_b32_e64 v66, v66, v246, s[30:31]
	v_cndmask_b32_e64 v67, v67, v246, s[34:35]
	v_max3_f32 v60, v60, v66, v67
	v_add_u32_e32 v63, 1, v62
	v_cmp_gt_u32_e64 s[40:41], v63, v252
	v_cndmask_b32_e64 v76, v76, v246, s[38:39]
	s_nop 0
	v_cndmask_b32_e64 v77, v77, v246, s[40:41]
	v_max_f32_e32 v61, v76, v77
	v_add_u32_e32 v63, 2, v62
	v_cmp_gt_u32_e64 s[42:43], v63, v252
	v_cmp_gt_u32_e64 s[44:45], v80, v252
	s_nop 0
	v_cndmask_b32_e64 v78, v78, v246, s[42:43]
	v_cndmask_b32_e64 v79, v79, v246, s[44:45]
	v_max3_f32 v61, v61, v78, v79
	v_add_u32_e32 v63, 16, v62
	v_add_u32_e32 v80, 17, v62
	v_cmp_gt_u32_e64 s[46:47], v63, v252
	v_cmp_gt_u32_e64 s[48:49], v80, v252
	s_nop 0
	v_cndmask_b32_e64 v56, v56, v246, s[46:47]
	v_cndmask_b32_e64 v57, v57, v246, s[48:49]
	v_max3_f32 v61, v61, v56, v57
	v_add_u32_e32 v63, 18, v62
	v_add_u32_e32 v62, 19, v62
	v_cmp_gt_u32_e64 s[50:51], v63, v252
	v_cmp_gt_u32_e64 s[52:53], v62, v252
	s_nop 0
	v_cndmask_b32_e64 v58, v58, v246, s[50:51]
	v_cndmask_b32_e64 v59, v59, v246, s[52:53]
	v_max3_f32 v61, v61, v58, v59
	v_mov_b32_e32 v62, v60
	s_nop 1
	v_permlane32_swap_b32_e32 v62, v60
	v_max_f32_e32 v60, v60, v62
	v_mov_b32_e32 v62, v61
	s_nop 1
	v_permlane32_swap_b32_e32 v62, v61
	v_max_f32_e32 v61, v61, v62
	v_mov_b32_e32 v62, v60
	s_nop 1
	v_permlane16_swap_b32_e32 v62, v60
	v_max3_f32 v148, v145, v60, v62
	v_sub_f32_e32 v32, v32, v148
	v_exp_f32_e32 v32, v32
	v_sub_f32_e32 v33, v33, v148
	v_exp_f32_e32 v33, v33
	v_sub_f32_e32 v34, v34, v148
	v_mov_b32_e32 v62, v61
	v_exp_f32_e32 v34, v34
	v_sub_f32_e32 v35, v35, v148
	v_permlane16_swap_b32_e32 v62, v61
	v_exp_f32_e32 v35, v35
	v_sub_f32_e32 v63, v64, v148
	v_exp_f32_e32 v63, v63
	v_sub_f32_e32 v64, v65, v148
	v_max_f32_e32 v61, v61, v62
	v_exp_f32_e32 v64, v64
	v_sub_f32_e32 v65, v66, v148
	v_add_f32_e32 v62, v33, v32
	v_exp_f32_e32 v65, v65
	v_sub_f32_e32 v66, v67, v148
	v_add_f32_e32 v62, v34, v62
	v_exp_f32_e32 v66, v66
	v_add_f32_e32 v62, v35, v62
	v_add_f32_e32 v62, v63, v62
	v_add_f32_e32 v62, v64, v62
	v_max_f32_e32 v150, v147, v61
	v_add_f32_e32 v62, v65, v62
	v_sub_f32_e32 v61, v147, v150
	v_add_f32_e32 v149, v66, v62
	v_exp_f32_e32 v62, v61
	v_sub_f32_e32 v61, v76, v150
	v_cvt_pk_bf16_f32 v32, v32, v33
	v_cvt_pk_bf16_f32 v33, v34, v35
	v_cvt_pk_bf16_f32 v34, v63, v64
	v_exp_f32_e32 v61, v61
	v_sub_f32_e32 v64, v77, v150
	v_cvt_pk_bf16_f32 v35, v65, v66
	v_exp_f32_e32 v64, v64
	v_sub_f32_e32 v65, v78, v150
	v_exp_f32_e32 v65, v65
	v_sub_f32_e32 v66, v79, v150
	v_exp_f32_e32 v66, v66
	v_sub_f32_e32 v56, v56, v150
	v_exp_f32_e32 v56, v56
	v_sub_f32_e32 v57, v57, v150
	v_exp_f32_e32 v57, v57
	v_add_f32_e32 v63, v64, v61
	v_add_f32_e32 v63, v65, v63
	v_add_f32_e32 v63, v66, v63
	v_cndmask_b32_e64 v67, v56, 0, s[46:47]
	v_add_f32_e32 v56, v67, v63
	v_cndmask_b32_e64 v63, v57, 0, s[48:49]
	v_sub_f32_e32 v57, v58, v150
	v_exp_f32_e32 v57, v57
	v_sub_f32_e32 v60, v145, v148
	v_exp_f32_e32 v60, v60
	v_add_f32_e32 v56, v63, v56
	v_cndmask_b32_e64 v76, v57, 0, s[50:51]
	v_sub_f32_e32 v57, v59, v150
	v_exp_f32_e32 v57, v57
	v_add_f32_e32 v56, v76, v56
	v_pk_mul_f32 v[38:39], v[38:39], v[60:61] op_sel_hi:[1,0]
	v_pk_mul_f32 v[36:37], v[36:37], v[60:61] op_sel_hi:[1,0]
	v_cndmask_b32_e64 v59, v57, 0, s[52:53]
	v_add_f32_e32 v151, v59, v56
	v_cvt_pk_bf16_f32 v56, v61, v64
	v_cvt_pk_bf16_f32 v57, v65, v66
	v_cvt_pk_bf16_f32 v58, v67, v63
	v_cvt_pk_bf16_f32 v59, v76, v59
	s_waitcnt lgkmcnt(10)
	v_mfma_f32_16x16x32_bf16 v[80:83], v[96:99], v[32:35], v[36:39]
	v_fmac_f32_e32 v149, v146, v60
	v_fmac_f32_e32 v151, v183, v62
	s_nop 0
	v_pk_mul_f32 v[38:39], v[70:71], v[62:63] op_sel_hi:[1,0]
	v_pk_mul_f32 v[36:37], v[68:69], v[62:63] op_sel_hi:[1,0]
	s_nop 1
	v_mfma_f32_16x16x32_bf16 v[84:87], v[96:99], v[56:59], v[36:39]
	s_nop 2
	v_mul_f32_e64 v38, v74, v60
	v_mul_f32_e64 v39, v75, v60
	v_pk_mul_f32 v[36:37], v[72:73], v[60:61] op_sel_hi:[1,0]
	s_waitcnt lgkmcnt(8)
	s_nop 0
	v_mfma_f32_16x16x32_bf16 v[96:99], v[140:143], v[32:35], v[36:39]
	s_nop 2
	v_mul_f32_e64 v38, v106, v62
	v_mul_f32_e64 v39, v107, v62
	v_pk_mul_f32 v[36:37], v[104:105], v[62:63] op_sel_hi:[1,0]
	s_nop 1
	v_mfma_f32_16x16x32_bf16 v[100:103], v[140:143], v[56:59], v[36:39]
	s_nop 2
	v_mul_f32_e64 v38, v110, v60
	v_mul_f32_e64 v39, v111, v60
	v_pk_mul_f32 v[36:37], v[108:109], v[60:61] op_sel_hi:[1,0]
	s_waitcnt lgkmcnt(6)
	s_nop 0
	v_mfma_f32_16x16x32_bf16 v[104:107], v[136:139], v[32:35], v[36:39]
	s_nop 2
	v_mul_f32_e64 v38, v114, v62
	v_mul_f32_e64 v39, v115, v62
	v_pk_mul_f32 v[36:37], v[112:113], v[62:63] op_sel_hi:[1,0]
	s_nop 1
	v_mfma_f32_16x16x32_bf16 v[108:111], v[136:139], v[56:59], v[36:39]
	s_nop 2
	v_mul_f32_e64 v38, v118, v60
	v_mul_f32_e64 v39, v119, v60
	v_pk_mul_f32 v[36:37], v[116:117], v[60:61] op_sel_hi:[1,0]
	s_waitcnt lgkmcnt(4)
	s_nop 0
	v_mfma_f32_16x16x32_bf16 v[112:115], v[132:135], v[32:35], v[36:39]
	v_mul_f32_e64 v34, v130, v62
	v_mul_f32_e64 v35, v131, v62
	v_pk_mul_f32 v[32:33], v[128:129], v[62:63] op_sel_hi:[1,0]
	s_nop 1
	v_mfma_f32_16x16x32_bf16 v[116:119], v[132:135], v[56:59], v[32:35]
	s_nop 2
	v_add_u32_e32 v32, 0x80, v184
	v_med3_i32 v32, v32, 0, s75
	v_lshl_add_u32 v32, v32, 9, v152
	global_load_dwordx4 v[64:67], v32, s[98:99]
	v_add_u32_e32 v32, 0x80, v185
	v_med3_i32 v32, v32, 0, s75
	v_lshl_add_u32 v32, v32, 9, v152
	global_load_dwordx4 v[68:71], v32, s[98:99]
	v_add_u32_e32 v32, 0x80, v186
	v_med3_i32 v32, v32, 0, s75
	v_lshl_add_u32 v32, v32, 9, v152
	global_load_dwordx4 v[72:75], v32, s[98:99]
	v_add_u32_e32 v32, 0x80, v188
	v_med3_i32 v32, v32, 0, s75
	v_lshl_add_u32 v32, v32, 9, v152
	global_load_dwordx4 v[76:79], v32, s[98:99]
	v_or_b32_e32 v32, 0x80, v209
	v_add_u32_e32 v32, s76, v32
	v_med3_i32 v32, v32, 0, s75
	v_lshl_add_u32 v32, v32, 9, v158
	global_load_dwordx4 v[60:63], v32, s[100:101]
	global_load_dwordx4 v[56:59], v32, s[100:101] offset:64
	v_or_b32_e32 v32, 0xc0, v209
	v_add_u32_e32 v32, s76, v32
	v_med3_i32 v32, v32, 0, s75
	v_lshl_add_u32 v32, v32, 9, v158
	global_load_dwordx4 v[36:39], v32, s[100:101]
	global_load_dwordx4 v[32:35], v32, s[100:101] offset:64
	ds_read_b64_tr_b16 v[134:135], v169 offset:6912
	ds_read_b64_tr_b16 v[132:133], v169 offset:4608
	ds_read_b64_tr_b16 v[128:129], v169 offset:4640
	ds_read_b64_tr_b16 v[130:131], v169 offset:6944
	ds_read_b64_tr_b16 v[136:137], v169 offset:4672
	ds_read_b64_tr_b16 v[138:139], v169 offset:6976
	ds_read_b64_tr_b16 v[144:145], v169 offset:4704
	ds_read_b64_tr_b16 v[146:147], v169 offset:7008
	s_waitcnt vmcnt(15)
	ds_write_b128 v241, v[88:91]
	s_waitcnt vmcnt(14)
	ds_write_b128 v242, v[92:95]
	s_waitcnt vmcnt(13)
	ds_write_b128 v243, v[120:123]
	s_waitcnt vmcnt(12)
	ds_write_b128 v244, v[124:127]
	v_mfma_f32_16x16x32_bf16 v[88:91], v[52:55], v[4:7], 0
	v_mfma_f32_16x16x32_bf16 v[92:95], v[28:31], v[4:7], 0
	v_mfma_f32_16x16x32_bf16 v[28:31], v[28:31], v[12:15], 0
	v_mfma_f32_16x16x32_bf16 v[88:91], v[44:47], v[8:11], v[88:91]
	v_mfma_f32_16x16x32_bf16 v[92:95], v[20:23], v[8:11], v[92:95]
	v_mfma_f32_16x16x32_bf16 v[20:23], v[20:23], v[0:3], v[28:31]
	s_nop 4
	v_sub_u32_e32 v28, v187, v176
	v_mfma_f32_16x16x32_bf16 v[52:55], v[52:55], v[12:15], 0
	v_add_u32_e32 v31, 1, v28
	v_cmp_gt_u32_e64 s[0:1], v31, v175
	v_cmp_gt_u32_e32 vcc, v28, v175
	s_nop 0
	v_cndmask_b32_e64 v89, v89, v246, s[0:1]
	s_nop 0
	v_cndmask_b32_e32 v88, v88, v246, vcc
	v_mfma_f32_16x16x32_bf16 v[44:47], v[44:47], v[0:3], v[52:55]
	v_max_f32_e32 v30, v88, v89
	v_add_u32_e32 v31, 2, v28
	v_cmp_gt_u32_e64 s[22:23], v31, v175
	v_add_u32_e32 v52, 3, v28
	v_cmp_gt_u32_e64 s[24:25], v52, v175
	v_cndmask_b32_e64 v90, v90, v246, s[22:23]
	v_sub_u32_e32 v29, v187, v181
	v_cndmask_b32_e64 v91, v91, v246, s[24:25]
	v_max3_f32 v30, v30, v90, v91
	v_add_u32_e32 v31, 16, v28
	v_add_u32_e32 v52, 17, v28
	v_cmp_gt_u32_e64 s[26:27], v31, v175
	v_cmp_gt_u32_e64 s[28:29], v52, v175
	v_cmp_gt_u32_e64 s[38:39], v29, v252
	v_cndmask_b32_e64 v92, v92, v246, s[26:27]
	v_cndmask_b32_e64 v93, v93, v246, s[28:29]
	v_max3_f32 v30, v30, v92, v93
	v_add_u32_e32 v31, 18, v28
	v_add_u32_e32 v28, 19, v28
	v_cmp_gt_u32_e64 s[30:31], v31, v175
	v_cmp_gt_u32_e64 s[34:35], v28, v175
	v_add_u32_e32 v52, 3, v29
	v_cndmask_b32_e64 v94, v94, v246, s[30:31]
	v_cndmask_b32_e64 v95, v95, v246, s[34:35]
	v_max3_f32 v28, v30, v94, v95
	v_add_u32_e32 v31, 1, v29
	v_cmp_gt_u32_e64 s[40:41], v31, v252
	v_cndmask_b32_e64 v44, v44, v246, s[38:39]
	s_nop 0
	v_cndmask_b32_e64 v45, v45, v246, s[40:41]
	v_max_f32_e32 v30, v44, v45
	v_add_u32_e32 v31, 2, v29
	v_cmp_gt_u32_e64 s[42:43], v31, v252
	v_cmp_gt_u32_e64 s[44:45], v52, v252
	s_nop 0
	v_cndmask_b32_e64 v46, v46, v246, s[42:43]
	v_cndmask_b32_e64 v47, v47, v246, s[44:45]
	v_max3_f32 v30, v30, v46, v47
	v_add_u32_e32 v31, 16, v29
	v_add_u32_e32 v52, 17, v29
	v_cmp_gt_u32_e64 s[46:47], v31, v252
	v_cmp_gt_u32_e64 s[48:49], v52, v252
	s_nop 0
	v_cndmask_b32_e64 v20, v20, v246, s[46:47]
	v_cndmask_b32_e64 v21, v21, v246, s[48:49]
	v_max3_f32 v30, v30, v20, v21
	v_add_u32_e32 v31, 18, v29
	v_add_u32_e32 v29, 19, v29
	v_cmp_gt_u32_e64 s[50:51], v31, v252
	v_cmp_gt_u32_e64 s[52:53], v29, v252
	s_nop 0
	v_cndmask_b32_e64 v22, v22, v246, s[50:51]
	v_cndmask_b32_e64 v23, v23, v246, s[52:53]
	v_max3_f32 v29, v30, v22, v23
	v_mov_b32_e32 v30, v28
	s_nop 1
	v_permlane32_swap_b32_e32 v30, v28
	v_max_f32_e32 v28, v28, v30
	v_mov_b32_e32 v30, v29
	s_nop 1
	v_permlane32_swap_b32_e32 v30, v29
	v_max_f32_e32 v29, v29, v30
	v_mov_b32_e32 v30, v28
	s_nop 1
	v_permlane16_swap_b32_e32 v30, v28
	v_max_f32_e32 v28, v28, v30
	v_mov_b32_e32 v30, v29
	v_max_f32_e32 v183, v148, v28
	s_nop 0
	v_permlane16_swap_b32_e32 v30, v29
	v_sub_f32_e32 v28, v148, v183
	v_exp_f32_e32 v52, v28
	v_sub_f32_e32 v28, v88, v183
	v_max_f32_e32 v54, v29, v30
	v_exp_f32_e32 v28, v28
	v_sub_f32_e32 v30, v89, v183
	v_exp_f32_e32 v30, v30
	v_sub_f32_e32 v31, v90, v183
	v_exp_f32_e32 v31, v31
	v_sub_f32_e32 v55, v91, v183
	v_max_f32_e32 v185, v150, v54
	v_exp_f32_e32 v55, v55
	v_sub_f32_e32 v88, v92, v183
	v_sub_f32_e32 v44, v44, v185
	v_exp_f32_e32 v88, v88
	v_sub_f32_e32 v89, v93, v183
	v_exp_f32_e32 v44, v44
	v_sub_f32_e32 v45, v45, v185
	v_exp_f32_e32 v89, v89
	v_sub_f32_e32 v90, v94, v183
	v_exp_f32_e32 v45, v45
	v_sub_f32_e32 v46, v46, v185
	v_add_f32_e32 v29, v30, v28
	v_exp_f32_e32 v90, v90
	v_sub_f32_e32 v91, v95, v183
	v_exp_f32_e32 v46, v46
	v_sub_f32_e32 v47, v47, v185
	v_add_f32_e32 v29, v31, v29
	v_exp_f32_e32 v91, v91
	v_exp_f32_e32 v47, v47
	v_sub_f32_e32 v20, v20, v185
	v_add_f32_e32 v29, v55, v29
	v_sub_f32_e32 v53, v150, v185
	v_exp_f32_e32 v20, v20
	v_sub_f32_e32 v21, v21, v185
	v_add_f32_e32 v29, v88, v29
	v_exp_f32_e32 v54, v53
	v_exp_f32_e32 v21, v21
	v_add_f32_e32 v29, v89, v29
	v_add_f32_e32 v53, v45, v44
	v_add_f32_e32 v29, v90, v29
	v_add_f32_e32 v53, v46, v53
	v_add_f32_e32 v184, v91, v29
	v_cvt_pk_bf16_f32 v29, v31, v55
	v_add_f32_e32 v53, v47, v53
	v_cndmask_b32_e64 v55, v20, 0, s[46:47]
	v_add_f32_e32 v20, v55, v53
	v_cndmask_b32_e64 v53, v21, 0, s[48:49]
	v_sub_f32_e32 v21, v22, v185
	v_exp_f32_e32 v21, v21
	v_cvt_pk_bf16_f32 v28, v28, v30
	v_cvt_pk_bf16_f32 v30, v88, v89
	v_add_f32_e32 v20, v53, v20
	v_cndmask_b32_e64 v88, v21, 0, s[50:51]
	v_sub_f32_e32 v21, v23, v185
	v_exp_f32_e32 v21, v21
	v_add_f32_e32 v20, v88, v20
	v_cvt_pk_bf16_f32 v31, v90, v91
	v_cvt_pk_bf16_f32 v22, v55, v53
	v_cndmask_b32_e64 v23, v21, 0, s[52:53]
	v_add_f32_e32 v186, v23, v20
	v_cvt_pk_bf16_f32 v20, v44, v45
	v_cvt_pk_bf16_f32 v21, v46, v47
	v_pk_mul_f32 v[46:47], v[82:83], v[52:53] op_sel_hi:[1,0]
	v_pk_mul_f32 v[44:45], v[80:81], v[52:53] op_sel_hi:[1,0]
	v_cvt_pk_bf16_f32 v23, v88, v23
	v_fmac_f32_e32 v184, v149, v52
	s_waitcnt lgkmcnt(10)
	v_mfma_f32_16x16x32_bf16 v[120:123], v[132:135], v[28:31], v[44:47]
	v_fmac_f32_e32 v186, v151, v54
	s_nop 1
	v_pk_mul_f32 v[46:47], v[86:87], v[54:55] op_sel_hi:[1,0]
	v_pk_mul_f32 v[44:45], v[84:85], v[54:55] op_sel_hi:[1,0]
	s_nop 1
	v_mfma_f32_16x16x32_bf16 v[124:127], v[132:135], v[20:23], v[44:47]
	s_nop 2
	v_mul_f32_e64 v46, v98, v52
	v_mul_f32_e64 v47, v99, v52
	v_pk_mul_f32 v[44:45], v[96:97], v[52:53] op_sel_hi:[1,0]
	s_waitcnt lgkmcnt(8)
	s_nop 0
	v_mfma_f32_16x16x32_bf16 v[96:99], v[128:131], v[28:31], v[44:47]
	s_nop 2
	v_mul_f32_e64 v46, v102, v54
	v_mul_f32_e64 v47, v103, v54
	v_pk_mul_f32 v[44:45], v[100:101], v[54:55] op_sel_hi:[1,0]
	s_nop 1
	v_mfma_f32_16x16x32_bf16 v[128:131], v[128:131], v[20:23], v[44:47]
	s_nop 2
	v_mul_f32_e64 v46, v106, v52
	v_mul_f32_e64 v47, v107, v52
	v_pk_mul_f32 v[44:45], v[104:105], v[52:53] op_sel_hi:[1,0]
	s_waitcnt lgkmcnt(6)
	s_nop 0
	v_mfma_f32_16x16x32_bf16 v[132:135], v[136:139], v[28:31], v[44:47]
	s_nop 2
	v_mul_f32_e64 v46, v110, v54
	v_mul_f32_e64 v47, v111, v54
	v_pk_mul_f32 v[44:45], v[108:109], v[54:55] op_sel_hi:[1,0]
	s_nop 1
	v_mfma_f32_16x16x32_bf16 v[136:139], v[136:139], v[20:23], v[44:47]
	s_nop 2
	v_mul_f32_e64 v46, v114, v52
	v_mul_f32_e64 v47, v115, v52
	v_pk_mul_f32 v[44:45], v[112:113], v[52:53] op_sel_hi:[1,0]
	s_waitcnt lgkmcnt(4)
	s_nop 0
	v_mfma_f32_16x16x32_bf16 v[140:143], v[144:147], v[28:31], v[44:47]
	v_mul_f32_e64 v30, v118, v54
	v_mul_f32_e64 v31, v119, v54
	v_pk_mul_f32 v[28:29], v[116:117], v[54:55] op_sel_hi:[1,0]
	s_nop 1
	v_mfma_f32_16x16x32_bf16 v[144:147], v[144:147], v[20:23], v[28:31]
	v_lshl_add_u32 v20, v155, 1, v155
	v_add_u32_e32 v20, v180, v20
	v_med3_i32 v20, v20, 0, s75
	v_lshl_add_u32 v20, v20, 9, v152
	global_load_dwordx4 v[80:83], v20, s[98:99]
	v_lshl_add_u32 v20, v172, 1, v172
	v_add_u32_e32 v20, v179, v20
	v_med3_i32 v20, v20, 0, s75
	v_lshl_add_u32 v20, v20, 9, v152
	global_load_dwordx4 v[84:87], v20, s[98:99]
	v_lshl_add_u32 v20, v173, 1, v173
	v_add_u32_e32 v20, v178, v20
	v_med3_i32 v20, v20, 0, s75
	v_lshl_add_u32 v20, v20, 9, v152
	global_load_dwordx4 v[88:91], v20, s[98:99]
	v_lshl_add_u32 v20, v182, 1, v182
	v_add_u32_e32 v20, v177, v20
	v_med3_i32 v20, v20, 0, s75
	v_lshl_add_u32 v20, v20, 9, v152
	global_load_dwordx4 v[92:95], v20, s[98:99]
	v_or_b32_e32 v20, 0x100, v209
	v_add_u32_e32 v20, s76, v20
	v_med3_i32 v20, v20, 0, s75
	v_lshl_add_u32 v20, v20, 9, v158
	global_load_dwordx4 v[52:55], v20, s[100:101]
	global_load_dwordx4 v[44:47], v20, s[100:101] offset:64
	v_or_b32_e32 v20, 0x140, v209
	v_add_u32_e32 v20, s76, v20
	v_med3_i32 v20, v20, 0, s75
	v_lshl_add_u32 v20, v20, 9, v158
	global_load_dwordx4 v[28:31], v20, s[100:101]
	global_load_dwordx4 v[20:23], v20, s[100:101] offset:64
	ds_read_b64_tr_b16 v[102:103], v169 offset:2304
	ds_read_b64_tr_b16 v[100:101], v169
	ds_read_b64_tr_b16 v[108:109], v169 offset:32
	ds_read_b64_tr_b16 v[110:111], v169 offset:2336
	ds_read_b64_tr_b16 v[116:117], v169 offset:64
	ds_read_b64_tr_b16 v[118:119], v169 offset:2368
	ds_read_b64_tr_b16 v[148:149], v169 offset:96
	ds_read_b64_tr_b16 v[150:151], v169 offset:2400
	s_waitcnt vmcnt(15)
	ds_write_b128 v241, v[64:67] offset:4608
	s_waitcnt vmcnt(14)
	ds_write_b128 v242, v[68:71] offset:4608
	s_waitcnt vmcnt(13)
	ds_write_b128 v243, v[72:75] offset:4608
	s_waitcnt vmcnt(12)
	ds_write_b128 v244, v[76:79] offset:4608
	v_mfma_f32_16x16x32_bf16 v[64:67], v[48:51], v[4:7], 0
	v_mfma_f32_16x16x32_bf16 v[68:71], v[24:27], v[4:7], 0
	v_mfma_f32_16x16x32_bf16 v[24:27], v[24:27], v[12:15], 0
	v_mfma_f32_16x16x32_bf16 v[64:67], v[40:43], v[8:11], v[64:67]
	v_mfma_f32_16x16x32_bf16 v[68:71], v[16:19], v[8:11], v[68:71]
	v_mfma_f32_16x16x32_bf16 v[16:19], v[16:19], v[0:3], v[24:27]
	s_nop 4
	v_sub_u32_e32 v24, v192, v176
	v_mfma_f32_16x16x32_bf16 v[48:51], v[48:51], v[12:15], 0
	v_add_u32_e32 v27, 1, v24
	v_cmp_gt_u32_e64 s[0:1], v27, v175
	v_cmp_gt_u32_e32 vcc, v24, v175
	s_nop 0
	v_cndmask_b32_e64 v65, v65, v246, s[0:1]
	s_nop 0
	v_cndmask_b32_e32 v64, v64, v246, vcc
	v_mfma_f32_16x16x32_bf16 v[40:43], v[40:43], v[0:3], v[48:51]
	v_max_f32_e32 v26, v64, v65
	v_add_u32_e32 v27, 2, v24
	v_cmp_gt_u32_e64 s[22:23], v27, v175
	v_add_u32_e32 v48, 3, v24
	v_cmp_gt_u32_e64 s[24:25], v48, v175
	v_cndmask_b32_e64 v66, v66, v246, s[22:23]
	v_sub_u32_e32 v25, v192, v181
	v_cndmask_b32_e64 v67, v67, v246, s[24:25]
	v_max3_f32 v26, v26, v66, v67
	v_add_u32_e32 v27, 16, v24
	v_add_u32_e32 v48, 17, v24
	v_cmp_gt_u32_e64 s[26:27], v27, v175
	v_cmp_gt_u32_e64 s[28:29], v48, v175
	v_cmp_gt_u32_e64 s[38:39], v25, v252
	v_cndmask_b32_e64 v68, v68, v246, s[26:27]
	v_cndmask_b32_e64 v69, v69, v246, s[28:29]
	v_max3_f32 v26, v26, v68, v69
	v_add_u32_e32 v27, 18, v24
	v_add_u32_e32 v24, 19, v24
	v_cmp_gt_u32_e64 s[30:31], v27, v175
	v_cmp_gt_u32_e64 s[34:35], v24, v175
	v_add_u32_e32 v48, 3, v25
	v_cndmask_b32_e64 v70, v70, v246, s[30:31]
	v_cndmask_b32_e64 v71, v71, v246, s[34:35]
	v_max3_f32 v24, v26, v70, v71
	v_add_u32_e32 v27, 1, v25
	v_cmp_gt_u32_e64 s[40:41], v27, v252
	v_cndmask_b32_e64 v40, v40, v246, s[38:39]
	s_nop 0
	v_cndmask_b32_e64 v41, v41, v246, s[40:41]
	v_max_f32_e32 v26, v40, v41
	v_add_u32_e32 v27, 2, v25
	v_cmp_gt_u32_e64 s[42:43], v27, v252
	v_cmp_gt_u32_e64 s[44:45], v48, v252
	s_nop 0
	v_cndmask_b32_e64 v42, v42, v246, s[42:43]
	v_cndmask_b32_e64 v43, v43, v246, s[44:45]
	v_max3_f32 v26, v26, v42, v43
	v_add_u32_e32 v27, 16, v25
	v_add_u32_e32 v48, 17, v25
	v_cmp_gt_u32_e64 s[46:47], v27, v252
	v_cmp_gt_u32_e64 s[48:49], v48, v252
	s_nop 0
	v_cndmask_b32_e64 v16, v16, v246, s[46:47]
	v_cndmask_b32_e64 v17, v17, v246, s[48:49]
	v_max3_f32 v26, v26, v16, v17
	v_add_u32_e32 v27, 18, v25
	v_add_u32_e32 v25, 19, v25
	v_cmp_gt_u32_e64 s[50:51], v27, v252
	v_cmp_gt_u32_e64 s[52:53], v25, v252
	s_nop 0
	v_cndmask_b32_e64 v18, v18, v246, s[50:51]
	v_cndmask_b32_e64 v19, v19, v246, s[52:53]
	v_max3_f32 v25, v26, v18, v19
	v_mov_b32_e32 v26, v24
	s_nop 1
	v_permlane32_swap_b32_e32 v26, v24
	v_max_f32_e32 v24, v24, v26
	v_mov_b32_e32 v26, v25
	s_nop 1
	v_permlane32_swap_b32_e32 v26, v25
	v_max_f32_e32 v25, v25, v26
	v_mov_b32_e32 v26, v24
	s_nop 1
	v_permlane16_swap_b32_e32 v26, v24
	v_max3_f32 v177, v183, v24, v26
	v_sub_f32_e32 v48, v66, v177
	v_exp_f32_e32 v48, v48
	v_sub_f32_e32 v24, v183, v177
	v_exp_f32_e32 v72, v24
	v_sub_f32_e32 v24, v64, v177
	v_cndmask_b32_e64 v49, v48, 0, s[22:23]
	v_sub_f32_e32 v48, v67, v177
	v_exp_f32_e32 v48, v48
	v_exp_f32_e32 v24, v24
	v_sub_f32_e32 v27, v65, v177
	v_exp_f32_e32 v27, v27
	v_cndmask_b32_e64 v50, v48, 0, s[24:25]
	v_sub_f32_e32 v48, v68, v177
	v_exp_f32_e32 v48, v48
	v_mov_b32_e32 v26, v25
	s_nop 1
	v_permlane16_swap_b32_e32 v26, v25
	v_cndmask_b32_e64 v51, v48, 0, s[26:27]
	v_sub_f32_e32 v48, v69, v177
	v_exp_f32_e32 v48, v48
	v_max_f32_e32 v25, v25, v26
	v_cndmask_b32_e64 v64, v48, 0, s[28:29]
	v_sub_f32_e32 v48, v70, v177
	v_exp_f32_e32 v48, v48
	v_add_f32_e32 v26, v27, v24
	v_cndmask_b32_e64 v65, v48, 0, s[30:31]
	v_sub_f32_e32 v48, v71, v177
	v_exp_f32_e32 v48, v48
	v_add_f32_e32 v26, v49, v26
	v_add_f32_e32 v26, v50, v26
	v_add_f32_e32 v26, v51, v26
	v_max_f32_e32 v179, v185, v25
	v_add_f32_e32 v26, v64, v26
	v_cndmask_b32_e64 v66, v48, 0, s[34:35]
	v_cvt_pk_bf16_f32 v48, v24, v27
	v_sub_f32_e32 v24, v185, v179
	v_add_f32_e32 v26, v65, v26
	v_cvt_pk_bf16_f32 v49, v49, v50
	v_cvt_pk_bf16_f32 v50, v51, v64
	v_exp_f32_e32 v64, v24
	v_sub_f32_e32 v24, v40, v179
	v_add_f32_e32 v178, v66, v26
	v_exp_f32_e32 v24, v24
	v_sub_f32_e32 v26, v41, v179
	v_exp_f32_e32 v26, v26
	v_sub_f32_e32 v27, v42, v179
	v_exp_f32_e32 v27, v27
	v_sub_f32_e32 v40, v43, v179
	v_exp_f32_e32 v40, v40
	v_sub_f32_e32 v16, v16, v179
	v_exp_f32_e32 v16, v16
	v_sub_f32_e32 v17, v17, v179
	v_exp_f32_e32 v17, v17
	v_add_f32_e32 v25, v26, v24
	v_add_f32_e32 v25, v27, v25
	v_add_f32_e32 v25, v40, v25
	v_cndmask_b32_e64 v41, v16, 0, s[46:47]
	v_add_f32_e32 v16, v41, v25
	v_cndmask_b32_e64 v25, v17, 0, s[48:49]
	v_sub_f32_e32 v17, v18, v179
	v_exp_f32_e32 v17, v17
	v_add_f32_e32 v16, v25, v16
	v_cvt_pk_bf16_f32 v51, v65, v66
	v_cvt_pk_bf16_f32 v18, v41, v25
	v_cndmask_b32_e64 v42, v17, 0, s[50:51]
	v_sub_f32_e32 v17, v19, v179
	v_exp_f32_e32 v17, v17
	v_add_f32_e32 v16, v42, v16
	v_fmac_f32_e32 v178, v184, v72
	v_cndmask_b32_e64 v19, v17, 0, s[52:53]
	v_add_f32_e32 v180, v19, v16
	v_cvt_pk_bf16_f32 v16, v24, v26
	v_cvt_pk_bf16_f32 v17, v27, v40
	v_cvt_pk_bf16_f32 v19, v42, v19
	v_pk_mul_f32 v[26:27], v[122:123], v[72:73] op_sel_hi:[1,0]
	v_pk_mul_f32 v[24:25], v[120:121], v[72:73] op_sel_hi:[1,0]
	v_pk_mul_f32 v[42:43], v[126:127], v[64:65] op_sel_hi:[1,0]
	v_pk_mul_f32 v[40:41], v[124:125], v[64:65] op_sel_hi:[1,0]
	s_waitcnt lgkmcnt(10)
	v_mfma_f32_16x16x32_bf16 v[24:27], v[100:103], v[48:51], v[24:27]
	v_fmac_f32_e32 v180, v186, v64
	v_mfma_f32_16x16x32_bf16 v[100:103], v[100:103], v[16:19], v[40:43]
	s_nop 2
	v_mul_f32_e64 v42, v98, v72
	v_mul_f32_e64 v43, v99, v72
	v_pk_mul_f32 v[40:41], v[96:97], v[72:73] op_sel_hi:[1,0]
	s_waitcnt lgkmcnt(8)
	s_nop 0
	v_mfma_f32_16x16x32_bf16 v[104:107], v[108:111], v[48:51], v[40:43]
	s_nop 2
	v_mul_f32_e64 v42, v130, v64
	v_mul_f32_e64 v43, v131, v64
	v_pk_mul_f32 v[40:41], v[128:129], v[64:65] op_sel_hi:[1,0]
	s_nop 1
	v_mfma_f32_16x16x32_bf16 v[108:111], v[108:111], v[16:19], v[40:43]
	s_nop 2
	v_mul_f32_e64 v42, v134, v72
	v_mul_f32_e64 v43, v135, v72
	v_pk_mul_f32 v[40:41], v[132:133], v[72:73] op_sel_hi:[1,0]
	s_waitcnt lgkmcnt(6)
	s_nop 0
	v_mfma_f32_16x16x32_bf16 v[112:115], v[116:119], v[48:51], v[40:43]
	s_nop 2
	v_mul_f32_e64 v42, v138, v64
	v_mul_f32_e64 v43, v139, v64
	v_pk_mul_f32 v[40:41], v[136:137], v[64:65] op_sel_hi:[1,0]
	s_nop 1
	v_mfma_f32_16x16x32_bf16 v[116:119], v[116:119], v[16:19], v[40:43]
	s_nop 2
	v_mul_f32_e64 v42, v142, v72
	v_mul_f32_e64 v43, v143, v72
	v_pk_mul_f32 v[40:41], v[140:141], v[72:73] op_sel_hi:[1,0]
	s_waitcnt lgkmcnt(4)
	s_nop 0
	v_mfma_f32_16x16x32_bf16 v[120:123], v[148:151], v[48:51], v[40:43]
	s_nop 2
	v_mul_f32_e64 v42, v146, v64
	v_mul_f32_e64 v43, v147, v64
	v_pk_mul_f32 v[40:41], v[144:145], v[64:65] op_sel_hi:[1,0]
	s_nop 1
	v_mfma_f32_16x16x32_bf16 v[124:127], v[148:151], v[16:19], v[40:43]
	v_lshlrev_b32_e32 v16, 2, v196
	v_add_u32_e32 v16, s76, v16
	v_med3_i32 v16, v16, 0, s75
	v_lshl_add_u32 v16, v16, 9, v152
	global_load_dwordx4 v[68:71], v16, s[98:99]
	v_lshlrev_b32_e32 v16, 2, v168
	v_add_u32_e32 v16, s76, v16
	v_med3_i32 v16, v16, 0, s75
	v_lshl_add_u32 v16, v16, 9, v152
	global_load_dwordx4 v[72:75], v16, s[98:99]
	v_lshlrev_b32_e32 v16, 2, v193
	v_add_u32_e32 v16, s76, v16
	v_med3_i32 v16, v16, 0, s75
	v_lshl_add_u32 v16, v16, 9, v152
	global_load_dwordx4 v[76:79], v16, s[98:99]
	v_lshlrev_b32_e32 v16, 2, v194
	v_add_u32_e32 v16, s76, v16
	v_med3_i32 v16, v16, 0, s75
	v_lshl_add_u32 v16, v16, 9, v152
	global_load_dwordx4 v[96:99], v16, s[98:99]
	v_or_b32_e32 v16, 0x180, v209
	v_add_u32_e32 v16, s76, v16
	v_med3_i32 v16, v16, 0, s75
	v_lshl_add_u32 v16, v16, 9, v158
	global_load_dwordx4 v[64:67], v16, s[100:101]
	global_load_dwordx4 v[48:51], v16, s[100:101] offset:64
	v_or_b32_e32 v16, 0x1c0, v209
	v_add_u32_e32 v16, s76, v16
	v_med3_i32 v16, v16, 0, s75
	v_lshl_add_u32 v16, v16, 9, v158
	global_load_dwordx4 v[40:43], v16, s[100:101]
	global_load_dwordx4 v[16:19], v16, s[100:101] offset:64
	ds_read_b64_tr_b16 v[142:143], v169 offset:6912
	ds_read_b64_tr_b16 v[140:141], v169 offset:4608
	ds_read_b64_tr_b16 v[136:137], v169 offset:4640
	ds_read_b64_tr_b16 v[138:139], v169 offset:6944
	ds_read_b64_tr_b16 v[132:133], v169 offset:4672
	ds_read_b64_tr_b16 v[134:135], v169 offset:6976
	ds_read_b64_tr_b16 v[128:129], v169 offset:4704
	ds_read_b64_tr_b16 v[130:131], v169 offset:7008
	s_waitcnt vmcnt(15)
	ds_write_b128 v241, v[80:83]
	s_waitcnt vmcnt(14)
	ds_write_b128 v242, v[84:87]
	s_waitcnt vmcnt(13)
	ds_write_b128 v243, v[88:91]
	s_waitcnt vmcnt(12)
	ds_write_b128 v244, v[92:95]
	v_mfma_f32_16x16x32_bf16 v[80:83], v[60:63], v[4:7], 0
	v_mfma_f32_16x16x32_bf16 v[84:87], v[36:39], v[4:7], 0
	v_mfma_f32_16x16x32_bf16 v[36:39], v[36:39], v[12:15], 0
	v_mfma_f32_16x16x32_bf16 v[80:83], v[56:59], v[8:11], v[80:83]
	v_mfma_f32_16x16x32_bf16 v[84:87], v[32:35], v[8:11], v[84:87]
	v_mfma_f32_16x16x32_bf16 v[32:35], v[32:35], v[0:3], v[36:39]
	s_nop 4
	v_sub_u32_e32 v36, v197, v176
	v_mfma_f32_16x16x32_bf16 v[60:63], v[60:63], v[12:15], 0
	v_add_u32_e32 v39, 1, v36
	v_cmp_gt_u32_e64 s[0:1], v39, v175
	v_cmp_gt_u32_e32 vcc, v36, v175
	s_nop 0
	v_cndmask_b32_e64 v81, v81, v246, s[0:1]
	s_nop 0
	v_cndmask_b32_e32 v80, v80, v246, vcc
	v_mfma_f32_16x16x32_bf16 v[56:59], v[56:59], v[0:3], v[60:63]
	v_max_f32_e32 v38, v80, v81
	v_add_u32_e32 v39, 2, v36
	v_cmp_gt_u32_e64 s[22:23], v39, v175
	v_add_u32_e32 v60, 3, v36
	v_cmp_gt_u32_e64 s[24:25], v60, v175
	v_cndmask_b32_e64 v82, v82, v246, s[22:23]
	v_sub_u32_e32 v37, v197, v181
	v_cndmask_b32_e64 v83, v83, v246, s[24:25]
	v_max3_f32 v38, v38, v82, v83
	v_add_u32_e32 v39, 16, v36
	v_add_u32_e32 v60, 17, v36
	v_cmp_gt_u32_e64 s[26:27], v39, v175
	v_cmp_gt_u32_e64 s[28:29], v60, v175
	v_cmp_gt_u32_e64 s[38:39], v37, v252
	v_cndmask_b32_e64 v84, v84, v246, s[26:27]
	v_cndmask_b32_e64 v85, v85, v246, s[28:29]
	v_max3_f32 v38, v38, v84, v85
	v_add_u32_e32 v39, 18, v36
	v_add_u32_e32 v36, 19, v36
	v_cmp_gt_u32_e64 s[30:31], v39, v175
	v_cmp_gt_u32_e64 s[34:35], v36, v175
	v_add_u32_e32 v60, 3, v37
	v_cndmask_b32_e64 v86, v86, v246, s[30:31]
	v_cndmask_b32_e64 v87, v87, v246, s[34:35]
	v_max3_f32 v36, v38, v86, v87
	v_add_u32_e32 v39, 1, v37
	v_cmp_gt_u32_e64 s[40:41], v39, v252
	v_cndmask_b32_e64 v56, v56, v246, s[38:39]
	s_nop 0
	v_cndmask_b32_e64 v57, v57, v246, s[40:41]
	v_max_f32_e32 v38, v56, v57
	v_add_u32_e32 v39, 2, v37
	v_cmp_gt_u32_e64 s[42:43], v39, v252
	v_cmp_gt_u32_e64 s[44:45], v60, v252
	s_nop 0
	v_cndmask_b32_e64 v58, v58, v246, s[42:43]
	v_cndmask_b32_e64 v59, v59, v246, s[44:45]
	v_max3_f32 v38, v38, v58, v59
	v_add_u32_e32 v39, 16, v37
	v_add_u32_e32 v60, 17, v37
	v_cmp_gt_u32_e64 s[46:47], v39, v252
	v_cmp_gt_u32_e64 s[48:49], v60, v252
	s_nop 0
	v_cndmask_b32_e64 v32, v32, v246, s[46:47]
	v_cndmask_b32_e64 v33, v33, v246, s[48:49]
	v_max3_f32 v38, v38, v32, v33
	v_add_u32_e32 v39, 18, v37
	v_add_u32_e32 v37, 19, v37
	v_cmp_gt_u32_e64 s[50:51], v39, v252
	v_cmp_gt_u32_e64 s[52:53], v37, v252
	s_nop 0
	v_cndmask_b32_e64 v34, v34, v246, s[50:51]
	v_cndmask_b32_e64 v35, v35, v246, s[52:53]
	v_max3_f32 v37, v38, v34, v35
	v_mov_b32_e32 v38, v36
	s_nop 1
	v_permlane32_swap_b32_e32 v38, v36
	v_max_f32_e32 v36, v36, v38
	v_mov_b32_e32 v38, v37
	s_nop 1
	v_permlane32_swap_b32_e32 v38, v37
	v_max_f32_e32 v37, v37, v38
	v_mov_b32_e32 v38, v36
	s_nop 1
	v_permlane16_swap_b32_e32 v38, v36
	v_max_f32_e32 v36, v36, v38
	v_mov_b32_e32 v38, v37
	v_max_f32_e32 v144, v177, v36
	s_nop 0
	v_permlane16_swap_b32_e32 v38, v37
	v_sub_f32_e32 v36, v177, v144
	v_exp_f32_e32 v60, v36
	v_sub_f32_e32 v36, v80, v144
	v_max_f32_e32 v62, v37, v38
	v_exp_f32_e32 v36, v36
	v_sub_f32_e32 v38, v81, v144
	v_exp_f32_e32 v38, v38
	v_sub_f32_e32 v39, v82, v144
	v_exp_f32_e32 v39, v39
	v_sub_f32_e32 v63, v83, v144
	v_max_f32_e32 v146, v179, v62
	v_exp_f32_e32 v63, v63
	v_sub_f32_e32 v80, v84, v144
	v_sub_f32_e32 v56, v56, v146
	v_exp_f32_e32 v80, v80
	v_sub_f32_e32 v81, v85, v144
	v_exp_f32_e32 v56, v56
	v_sub_f32_e32 v57, v57, v146
	v_exp_f32_e32 v81, v81
	v_sub_f32_e32 v82, v86, v144
	v_exp_f32_e32 v57, v57
	v_sub_f32_e32 v58, v58, v146
	v_add_f32_e32 v37, v38, v36
	v_exp_f32_e32 v82, v82
	v_sub_f32_e32 v83, v87, v144
	v_exp_f32_e32 v58, v58
	v_sub_f32_e32 v59, v59, v146
	v_add_f32_e32 v37, v39, v37
	v_exp_f32_e32 v83, v83
	v_exp_f32_e32 v59, v59
	v_sub_f32_e32 v32, v32, v146
	v_add_f32_e32 v37, v63, v37
	v_sub_f32_e32 v61, v179, v146
	v_exp_f32_e32 v32, v32
	v_sub_f32_e32 v33, v33, v146
	v_add_f32_e32 v37, v80, v37
	v_exp_f32_e32 v62, v61
	v_exp_f32_e32 v33, v33
	v_add_f32_e32 v37, v81, v37
	v_add_f32_e32 v61, v57, v56
	v_add_f32_e32 v37, v82, v37
	v_add_f32_e32 v61, v58, v61
	v_add_f32_e32 v145, v83, v37
	v_cvt_pk_bf16_f32 v37, v39, v63
	v_add_f32_e32 v61, v59, v61
	v_cndmask_b32_e64 v63, v32, 0, s[46:47]
	v_add_f32_e32 v32, v63, v61
	v_cndmask_b32_e64 v61, v33, 0, s[48:49]
	v_sub_f32_e32 v33, v34, v146
	v_exp_f32_e32 v33, v33
	v_cvt_pk_bf16_f32 v36, v36, v38
	v_cvt_pk_bf16_f32 v38, v80, v81
	v_add_f32_e32 v32, v61, v32
	v_cndmask_b32_e64 v80, v33, 0, s[50:51]
	v_sub_f32_e32 v33, v35, v146
	v_exp_f32_e32 v33, v33
	v_cvt_pk_bf16_f32 v39, v82, v83
	v_add_f32_e32 v32, v80, v32
	v_pk_mul_f32 v[26:27], v[26:27], v[60:61] op_sel_hi:[1,0]
	v_cndmask_b32_e64 v35, v33, 0, s[52:53]
	v_pk_mul_f32 v[24:25], v[24:25], v[60:61] op_sel_hi:[1,0]
	v_add_f32_e32 v147, v35, v32
	v_cvt_pk_bf16_f32 v32, v56, v57
	v_cvt_pk_bf16_f32 v33, v58, v59
	v_cvt_pk_bf16_f32 v34, v63, v61
	v_cvt_pk_bf16_f32 v35, v80, v35
	s_waitcnt lgkmcnt(10)
	v_mfma_f32_16x16x32_bf16 v[92:95], v[140:143], v[36:39], v[24:27]
	v_fmac_f32_e32 v145, v178, v60
	v_fmac_f32_e32 v147, v180, v62
	s_nop 0
	v_pk_mul_f32 v[26:27], v[102:103], v[62:63] op_sel_hi:[1,0]
	v_pk_mul_f32 v[24:25], v[100:101], v[62:63] op_sel_hi:[1,0]
	s_nop 1
	v_mfma_f32_16x16x32_bf16 v[100:103], v[140:143], v[32:35], v[24:27]
	s_nop 2
	v_mul_f32_e64 v26, v106, v60
	v_mul_f32_e64 v27, v107, v60
	v_pk_mul_f32 v[24:25], v[104:105], v[60:61] op_sel_hi:[1,0]
	s_waitcnt lgkmcnt(8)
	s_nop 0
	v_mfma_f32_16x16x32_bf16 v[104:107], v[136:139], v[36:39], v[24:27]
	s_nop 2
	v_mul_f32_e64 v26, v110, v62
	v_mul_f32_e64 v27, v111, v62
	v_pk_mul_f32 v[24:25], v[108:109], v[62:63] op_sel_hi:[1,0]
	s_nop 1
	v_mfma_f32_16x16x32_bf16 v[108:111], v[136:139], v[32:35], v[24:27]
	s_nop 2
	v_mul_f32_e64 v26, v114, v60
	v_mul_f32_e64 v27, v115, v60
	v_pk_mul_f32 v[24:25], v[112:113], v[60:61] op_sel_hi:[1,0]
	s_waitcnt lgkmcnt(6)
	s_nop 0
	v_mfma_f32_16x16x32_bf16 v[112:115], v[132:135], v[36:39], v[24:27]
	s_nop 2
	v_mul_f32_e64 v26, v118, v62
	v_mul_f32_e64 v27, v119, v62
	v_pk_mul_f32 v[24:25], v[116:117], v[62:63] op_sel_hi:[1,0]
	s_nop 1
	v_mfma_f32_16x16x32_bf16 v[116:119], v[132:135], v[32:35], v[24:27]
	s_nop 2
	v_mul_f32_e64 v26, v122, v60
	v_mul_f32_e64 v27, v123, v60
	v_pk_mul_f32 v[24:25], v[120:121], v[60:61] op_sel_hi:[1,0]
	s_waitcnt lgkmcnt(4)
	s_nop 0
	v_mfma_f32_16x16x32_bf16 v[120:123], v[128:131], v[36:39], v[24:27]
	s_nop 2
	v_mul_f32_e64 v26, v126, v62
	v_mul_f32_e64 v27, v127, v62
	v_pk_mul_f32 v[24:25], v[124:125], v[62:63] op_sel_hi:[1,0]
	s_nop 1
	v_mfma_f32_16x16x32_bf16 v[124:127], v[128:131], v[32:35], v[24:27]
	s_nop 2
	v_add_u32_e32 v24, s76, v214
	v_med3_i32 v24, v24, 0, s75
	v_lshl_add_u32 v24, v24, 9, v152
	global_load_dwordx4 v[60:63], v24, s[98:99]
	v_add_u32_e32 v24, s76, v216
	v_med3_i32 v24, v24, 0, s75
	v_lshl_add_u32 v24, v24, 9, v152
	global_load_dwordx4 v[80:83], v24, s[98:99]
	v_add_u32_e32 v24, s76, v218
	v_med3_i32 v24, v24, 0, s75
	v_lshl_add_u32 v24, v24, 9, v152
	global_load_dwordx4 v[84:87], v24, s[98:99]
	v_add_u32_e32 v24, s76, v220
	v_med3_i32 v24, v24, 0, s75
	v_lshl_add_u32 v24, v24, 9, v152
	global_load_dwordx4 v[88:91], v24, s[98:99]
	v_add_u32_e32 v24, s76, v221
	v_med3_i32 v24, v24, 0, s75
	v_lshl_add_u32 v24, v24, 9, v158
	global_load_dwordx4 v[56:59], v24, s[100:101]
	global_load_dwordx4 v[36:39], v24, s[100:101] offset:64
	v_or_b32_e32 v24, 0x100, v221
	v_add_u32_e32 v24, s76, v24
	v_med3_i32 v24, v24, 0, s75
	v_lshl_add_u32 v24, v24, 9, v158
	global_load_dwordx4 v[32:35], v24, s[100:101]
	global_load_dwordx4 v[24:27], v24, s[100:101] offset:64
	ds_read_b64_tr_b16 v[142:143], v169 offset:2304
	ds_read_b64_tr_b16 v[140:141], v169
	ds_read_b64_tr_b16 v[136:137], v169 offset:32
	ds_read_b64_tr_b16 v[138:139], v169 offset:2336
	ds_read_b64_tr_b16 v[132:133], v169 offset:64
	ds_read_b64_tr_b16 v[134:135], v169 offset:2368
	ds_read_b64_tr_b16 v[128:129], v169 offset:96
	ds_read_b64_tr_b16 v[130:131], v169 offset:2400
	s_waitcnt vmcnt(15)
	ds_write_b128 v241, v[68:71] offset:4608
	s_waitcnt vmcnt(14)
	ds_write_b128 v242, v[72:75] offset:4608
	s_waitcnt vmcnt(13)
	ds_write_b128 v243, v[76:79] offset:4608
	s_waitcnt vmcnt(12)
	ds_write_b128 v244, v[96:99] offset:4608
	v_mfma_f32_16x16x32_bf16 v[68:71], v[52:55], v[4:7], 0
	v_mfma_f32_16x16x32_bf16 v[72:75], v[28:31], v[4:7], 0
	v_mfma_f32_16x16x32_bf16 v[28:31], v[28:31], v[12:15], 0
	v_mfma_f32_16x16x32_bf16 v[68:71], v[44:47], v[8:11], v[68:71]
	v_mfma_f32_16x16x32_bf16 v[72:75], v[20:23], v[8:11], v[72:75]
	v_mfma_f32_16x16x32_bf16 v[20:23], v[20:23], v[0:3], v[28:31]
	s_nop 4
	v_sub_u32_e32 v28, v198, v176
	v_mfma_f32_16x16x32_bf16 v[52:55], v[52:55], v[12:15], 0
	v_add_u32_e32 v31, 1, v28
	v_cmp_gt_u32_e64 s[0:1], v31, v175
	v_cmp_gt_u32_e32 vcc, v28, v175
	s_nop 0
	v_cndmask_b32_e64 v69, v69, v246, s[0:1]
	s_nop 0
	v_cndmask_b32_e32 v68, v68, v246, vcc
	v_mfma_f32_16x16x32_bf16 v[44:47], v[44:47], v[0:3], v[52:55]
	v_max_f32_e32 v30, v68, v69
	v_add_u32_e32 v31, 2, v28
	v_cmp_gt_u32_e64 s[22:23], v31, v175
	v_add_u32_e32 v52, 3, v28
	v_cmp_gt_u32_e64 s[24:25], v52, v175
	v_cndmask_b32_e64 v70, v70, v246, s[22:23]
	v_sub_u32_e32 v29, v198, v181
	v_cndmask_b32_e64 v71, v71, v246, s[24:25]
	v_max3_f32 v30, v30, v70, v71
	v_add_u32_e32 v31, 16, v28
	v_add_u32_e32 v52, 17, v28
	v_cmp_gt_u32_e64 s[26:27], v31, v175
	v_cmp_gt_u32_e64 s[28:29], v52, v175
	v_cmp_gt_u32_e64 s[38:39], v29, v252
	v_cndmask_b32_e64 v72, v72, v246, s[26:27]
	v_cndmask_b32_e64 v73, v73, v246, s[28:29]
	v_max3_f32 v30, v30, v72, v73
	v_add_u32_e32 v31, 18, v28
	v_add_u32_e32 v28, 19, v28
	v_cmp_gt_u32_e64 s[30:31], v31, v175
	v_cmp_gt_u32_e64 s[34:35], v28, v175
	v_add_u32_e32 v52, 3, v29
	v_cndmask_b32_e64 v74, v74, v246, s[30:31]
	v_cndmask_b32_e64 v75, v75, v246, s[34:35]
	v_max3_f32 v28, v30, v74, v75
	v_add_u32_e32 v31, 1, v29
	v_cmp_gt_u32_e64 s[40:41], v31, v252
	v_cndmask_b32_e64 v44, v44, v246, s[38:39]
	s_nop 0
	v_cndmask_b32_e64 v45, v45, v246, s[40:41]
	v_max_f32_e32 v30, v44, v45
	v_add_u32_e32 v31, 2, v29
	v_cmp_gt_u32_e64 s[42:43], v31, v252
	v_cmp_gt_u32_e64 s[44:45], v52, v252
	s_nop 0
	v_cndmask_b32_e64 v46, v46, v246, s[42:43]
	v_cndmask_b32_e64 v47, v47, v246, s[44:45]
	v_max3_f32 v30, v30, v46, v47
	v_add_u32_e32 v31, 16, v29
	v_add_u32_e32 v52, 17, v29
	v_cmp_gt_u32_e64 s[46:47], v31, v252
	v_cmp_gt_u32_e64 s[48:49], v52, v252
	s_nop 0
	v_cndmask_b32_e64 v20, v20, v246, s[46:47]
	v_cndmask_b32_e64 v21, v21, v246, s[48:49]
	v_max3_f32 v30, v30, v20, v21
	v_add_u32_e32 v31, 18, v29
	v_add_u32_e32 v29, 19, v29
	v_cmp_gt_u32_e64 s[50:51], v31, v252
	v_cmp_gt_u32_e64 s[52:53], v29, v252
	s_nop 0
	v_cndmask_b32_e64 v22, v22, v246, s[50:51]
	v_cndmask_b32_e64 v23, v23, v246, s[52:53]
	v_max3_f32 v29, v30, v22, v23
	v_mov_b32_e32 v30, v28
	s_nop 1
	v_permlane32_swap_b32_e32 v30, v28
	v_max_f32_e32 v28, v28, v30
	v_mov_b32_e32 v30, v29
	s_nop 1
	v_permlane32_swap_b32_e32 v30, v29
	v_max_f32_e32 v29, v29, v30
	v_mov_b32_e32 v30, v28
	s_nop 1
	v_permlane16_swap_b32_e32 v30, v28
	v_max_f32_e32 v28, v28, v30
	v_mov_b32_e32 v30, v29
	v_max_f32_e32 v148, v144, v28
	s_nop 0
	v_permlane16_swap_b32_e32 v30, v29
	v_sub_f32_e32 v28, v144, v148
	v_exp_f32_e32 v52, v28
	v_sub_f32_e32 v28, v68, v148
	v_max_f32_e32 v54, v29, v30
	v_exp_f32_e32 v28, v28
	v_sub_f32_e32 v30, v69, v148
	v_exp_f32_e32 v30, v30
	v_sub_f32_e32 v31, v70, v148
	v_exp_f32_e32 v31, v31
	v_sub_f32_e32 v55, v71, v148
	v_max_f32_e32 v149, v146, v54
	v_exp_f32_e32 v55, v55
	v_sub_f32_e32 v68, v72, v148
	v_sub_f32_e32 v44, v44, v149
	v_exp_f32_e32 v68, v68
	v_sub_f32_e32 v69, v73, v148
	v_exp_f32_e32 v44, v44
	v_sub_f32_e32 v45, v45, v149
	v_exp_f32_e32 v69, v69
	v_sub_f32_e32 v70, v74, v148
	v_exp_f32_e32 v45, v45
	v_sub_f32_e32 v46, v46, v149
	v_add_f32_e32 v29, v30, v28
	v_exp_f32_e32 v70, v70
	v_sub_f32_e32 v71, v75, v148
	v_exp_f32_e32 v46, v46
	v_sub_f32_e32 v47, v47, v149
	v_add_f32_e32 v29, v31, v29
	v_exp_f32_e32 v71, v71
	v_exp_f32_e32 v47, v47
	v_sub_f32_e32 v20, v20, v149
	v_add_f32_e32 v29, v55, v29
	v_sub_f32_e32 v53, v146, v149
	v_exp_f32_e32 v20, v20
	v_sub_f32_e32 v21, v21, v149
	v_add_f32_e32 v29, v68, v29
	v_exp_f32_e32 v54, v53
	v_exp_f32_e32 v21, v21
	v_add_f32_e32 v29, v69, v29
	v_add_f32_e32 v53, v45, v44
	v_add_f32_e32 v29, v70, v29
	v_add_f32_e32 v53, v46, v53
	v_add_f32_e32 v144, v71, v29
	v_cvt_pk_bf16_f32 v29, v31, v55
	v_add_f32_e32 v53, v47, v53
	v_cndmask_b32_e64 v55, v20, 0, s[46:47]
	v_add_f32_e32 v20, v55, v53
	v_cndmask_b32_e64 v53, v21, 0, s[48:49]
	v_sub_f32_e32 v21, v22, v149
	v_exp_f32_e32 v21, v21
	v_cvt_pk_bf16_f32 v28, v28, v30
	v_cvt_pk_bf16_f32 v30, v68, v69
	v_add_f32_e32 v20, v53, v20
	v_cndmask_b32_e64 v68, v21, 0, s[50:51]
	v_sub_f32_e32 v21, v23, v149
	v_exp_f32_e32 v21, v21
	v_add_f32_e32 v20, v68, v20
	v_fmac_f32_e32 v144, v145, v52
	v_cvt_pk_bf16_f32 v31, v70, v71
	v_cndmask_b32_e64 v23, v21, 0, s[52:53]
	v_add_f32_e32 v145, v23, v20
	v_cvt_pk_bf16_f32 v20, v44, v45
	v_cvt_pk_bf16_f32 v21, v46, v47
	v_pk_mul_f32 v[46:47], v[94:95], v[52:53] op_sel_hi:[1,0]
	v_pk_mul_f32 v[44:45], v[92:93], v[52:53] op_sel_hi:[1,0]
	v_cvt_pk_bf16_f32 v22, v55, v53
	v_cvt_pk_bf16_f32 v23, v68, v23
	s_waitcnt lgkmcnt(10)
	v_mfma_f32_16x16x32_bf16 v[96:99], v[140:143], v[28:31], v[44:47]
	v_fmac_f32_e32 v145, v147, v54
	s_nop 1
	v_pk_mul_f32 v[46:47], v[102:103], v[54:55] op_sel_hi:[1,0]
	v_pk_mul_f32 v[44:45], v[100:101], v[54:55] op_sel_hi:[1,0]
	s_nop 1
	v_mfma_f32_16x16x32_bf16 v[100:103], v[140:143], v[20:23], v[44:47]
	s_nop 2
	v_mul_f32_e64 v46, v106, v52
	v_mul_f32_e64 v47, v107, v52
	v_pk_mul_f32 v[44:45], v[104:105], v[52:53] op_sel_hi:[1,0]
	s_waitcnt lgkmcnt(8)
	s_nop 0
	v_mfma_f32_16x16x32_bf16 v[104:107], v[136:139], v[28:31], v[44:47]
	s_nop 2
	v_mul_f32_e64 v46, v110, v54
	v_mul_f32_e64 v47, v111, v54
	v_pk_mul_f32 v[44:45], v[108:109], v[54:55] op_sel_hi:[1,0]
	s_nop 1
	v_mfma_f32_16x16x32_bf16 v[108:111], v[136:139], v[20:23], v[44:47]
	s_nop 2
	v_mul_f32_e64 v46, v114, v52
	v_mul_f32_e64 v47, v115, v52
	v_pk_mul_f32 v[44:45], v[112:113], v[52:53] op_sel_hi:[1,0]
	s_waitcnt lgkmcnt(6)
	s_nop 0
	v_mfma_f32_16x16x32_bf16 v[112:115], v[132:135], v[28:31], v[44:47]
	s_nop 2
	v_mul_f32_e64 v46, v118, v54
	v_mul_f32_e64 v47, v119, v54
	v_pk_mul_f32 v[44:45], v[116:117], v[54:55] op_sel_hi:[1,0]
	s_nop 1
	v_mfma_f32_16x16x32_bf16 v[116:119], v[132:135], v[20:23], v[44:47]
	s_nop 2
	v_mul_f32_e64 v46, v122, v52
	v_mul_f32_e64 v47, v123, v52
	v_pk_mul_f32 v[44:45], v[120:121], v[52:53] op_sel_hi:[1,0]
	s_waitcnt lgkmcnt(4)
	s_nop 0
	v_mfma_f32_16x16x32_bf16 v[120:123], v[128:131], v[28:31], v[44:47]
	v_mul_f32_e64 v30, v126, v54
	v_mul_f32_e64 v31, v127, v54
	v_pk_mul_f32 v[28:29], v[124:125], v[54:55] op_sel_hi:[1,0]
	s_nop 1
	v_mfma_f32_16x16x32_bf16 v[124:127], v[128:131], v[20:23], v[28:31]
	v_add_u32_e32 v20, s76, v222
	v_med3_i32 v20, v20, 0, s75
	v_lshl_add_u32 v20, v20, 9, v152
	global_load_dwordx4 v[68:71], v20, s[98:99]
	v_add_u32_e32 v20, s76, v223
	v_med3_i32 v20, v20, 0, s75
	v_lshl_add_u32 v20, v20, 9, v152
	global_load_dwordx4 v[72:75], v20, s[98:99]
	v_add_u32_e32 v20, s76, v224
	v_med3_i32 v20, v20, 0, s75
	v_lshl_add_u32 v20, v20, 9, v152
	global_load_dwordx4 v[76:79], v20, s[98:99]
	v_add_u32_e32 v20, s76, v225
	v_med3_i32 v20, v20, 0, s75
	v_lshl_add_u32 v20, v20, 9, v152
	global_load_dwordx4 v[92:95], v20, s[98:99]
	v_add_u32_e32 v20, s76, v226
	v_med3_i32 v20, v20, 0, s75
	v_lshl_add_u32 v20, v20, 9, v158
	global_load_dwordx4 v[52:55], v20, s[100:101]
	global_load_dwordx4 v[44:47], v20, s[100:101] offset:64
	v_add_u32_e32 v20, s76, v227
	v_med3_i32 v20, v20, 0, s75
	v_lshl_add_u32 v20, v20, 9, v158
	global_load_dwordx4 v[28:31], v20, s[100:101]
	global_load_dwordx4 v[20:23], v20, s[100:101] offset:64
	ds_read_b64_tr_b16 v[142:143], v169 offset:6912
	ds_read_b64_tr_b16 v[140:141], v169 offset:4608
	ds_read_b64_tr_b16 v[136:137], v169 offset:4640
	ds_read_b64_tr_b16 v[138:139], v169 offset:6944
	ds_read_b64_tr_b16 v[132:133], v169 offset:4672
	ds_read_b64_tr_b16 v[134:135], v169 offset:6976
	ds_read_b64_tr_b16 v[128:129], v169 offset:4704
	ds_read_b64_tr_b16 v[130:131], v169 offset:7008
	s_waitcnt vmcnt(15)
	ds_write_b128 v241, v[60:63]
	s_waitcnt vmcnt(14)
	ds_write_b128 v242, v[80:83]
	s_waitcnt vmcnt(13)
	ds_write_b128 v243, v[84:87]
	s_waitcnt vmcnt(12)
	ds_write_b128 v244, v[88:91]
	v_mfma_f32_16x16x32_bf16 v[60:63], v[64:67], v[4:7], 0
	v_mfma_f32_16x16x32_bf16 v[80:83], v[40:43], v[4:7], 0
	v_mfma_f32_16x16x32_bf16 v[40:43], v[40:43], v[12:15], 0
	v_mfma_f32_16x16x32_bf16 v[60:63], v[48:51], v[8:11], v[60:63]
	v_mfma_f32_16x16x32_bf16 v[80:83], v[16:19], v[8:11], v[80:83]
	v_mfma_f32_16x16x32_bf16 v[16:19], v[16:19], v[0:3], v[40:43]
	s_nop 4
	v_sub_u32_e32 v40, v199, v176
	v_mfma_f32_16x16x32_bf16 v[64:67], v[64:67], v[12:15], 0
	v_add_u32_e32 v43, 1, v40
	v_cmp_gt_u32_e64 s[0:1], v43, v175
	v_cmp_gt_u32_e32 vcc, v40, v175
	s_nop 0
	v_cndmask_b32_e64 v61, v61, v246, s[0:1]
	s_nop 0
	v_cndmask_b32_e32 v60, v60, v246, vcc
	v_mfma_f32_16x16x32_bf16 v[48:51], v[48:51], v[0:3], v[64:67]
	v_max_f32_e32 v42, v60, v61
	v_add_u32_e32 v43, 2, v40
	v_cmp_gt_u32_e64 s[22:23], v43, v175
	v_add_u32_e32 v64, 3, v40
	v_cmp_gt_u32_e64 s[24:25], v64, v175
	v_cndmask_b32_e64 v62, v62, v246, s[22:23]
	v_sub_u32_e32 v41, v199, v181
	v_cndmask_b32_e64 v63, v63, v246, s[24:25]
	v_max3_f32 v42, v42, v62, v63
	v_add_u32_e32 v43, 16, v40
	v_add_u32_e32 v64, 17, v40
	v_cmp_gt_u32_e64 s[26:27], v43, v175
	v_cmp_gt_u32_e64 s[28:29], v64, v175
	v_cmp_gt_u32_e64 s[38:39], v41, v252
	v_cndmask_b32_e64 v80, v80, v246, s[26:27]
	v_cndmask_b32_e64 v81, v81, v246, s[28:29]
	v_max3_f32 v42, v42, v80, v81
	v_add_u32_e32 v43, 18, v40
	v_add_u32_e32 v40, 19, v40
	v_cmp_gt_u32_e64 s[30:31], v43, v175
	v_cmp_gt_u32_e64 s[34:35], v40, v175
	v_add_u32_e32 v64, 3, v41
	v_cndmask_b32_e64 v82, v82, v246, s[30:31]
	v_cndmask_b32_e64 v83, v83, v246, s[34:35]
	v_max3_f32 v40, v42, v82, v83
	v_add_u32_e32 v43, 1, v41
	v_cmp_gt_u32_e64 s[40:41], v43, v252
	v_cndmask_b32_e64 v48, v48, v246, s[38:39]
	s_nop 0
	v_cndmask_b32_e64 v49, v49, v246, s[40:41]
	v_max_f32_e32 v42, v48, v49
	v_add_u32_e32 v43, 2, v41
	v_cmp_gt_u32_e64 s[42:43], v43, v252
	v_cmp_gt_u32_e64 s[44:45], v64, v252
	s_nop 0
	v_cndmask_b32_e64 v50, v50, v246, s[42:43]
	v_cndmask_b32_e64 v51, v51, v246, s[44:45]
	v_max3_f32 v42, v42, v50, v51
	v_add_u32_e32 v43, 16, v41
	v_add_u32_e32 v64, 17, v41
	v_cmp_gt_u32_e64 s[46:47], v43, v252
	v_cmp_gt_u32_e64 s[48:49], v64, v252
	s_nop 0
	v_cndmask_b32_e64 v16, v16, v246, s[46:47]
	v_cndmask_b32_e64 v17, v17, v246, s[48:49]
	v_max3_f32 v42, v42, v16, v17
	v_add_u32_e32 v43, 18, v41
	v_add_u32_e32 v41, 19, v41
	v_cmp_gt_u32_e64 s[50:51], v43, v252
	v_cmp_gt_u32_e64 s[52:53], v41, v252
	s_nop 0
	v_cndmask_b32_e64 v18, v18, v246, s[50:51]
	v_cndmask_b32_e64 v19, v19, v246, s[52:53]
	v_max3_f32 v41, v42, v18, v19
	v_mov_b32_e32 v42, v40
	s_nop 1
	v_permlane32_swap_b32_e32 v42, v40
	v_max_f32_e32 v40, v40, v42
	v_mov_b32_e32 v42, v41
	s_nop 1
	v_permlane32_swap_b32_e32 v42, v41
	v_max_f32_e32 v41, v41, v42
	v_mov_b32_e32 v42, v40
	s_nop 1
	v_permlane16_swap_b32_e32 v42, v40
	v_max3_f32 v147, v148, v40, v42
	v_sub_f32_e32 v40, v148, v147
	v_exp_f32_e32 v84, v40
	v_sub_f32_e32 v40, v60, v147
	v_exp_f32_e32 v40, v40
	v_mov_b32_e32 v42, v41
	s_nop 1
	v_permlane16_swap_b32_e32 v42, v41
	v_cndmask_b32_e64 v85, v40, 0, vcc
	v_sub_f32_e32 v40, v61, v147
	v_exp_f32_e32 v40, v40
	v_max3_f32 v146, v149, v41, v42
	v_cndmask_b32_e64 v61, v40, 0, s[0:1]
	v_sub_f32_e32 v40, v62, v147
	v_exp_f32_e32 v40, v40
	v_sub_f32_e32 v48, v48, v146
	v_sub_f32_e32 v16, v16, v146
	v_exp_f32_e32 v48, v48
	v_cndmask_b32_e64 v62, v40, 0, s[22:23]
	v_sub_f32_e32 v40, v63, v147
	v_exp_f32_e32 v40, v40
	v_exp_f32_e32 v16, v16
	v_cndmask_b32_e64 v86, v48, 0, s[38:39]
	v_sub_f32_e32 v48, v49, v146
	v_cndmask_b32_e64 v63, v40, 0, s[24:25]
	v_sub_f32_e32 v40, v80, v147
	v_exp_f32_e32 v40, v40
	v_cndmask_b32_e64 v90, v16, 0, s[46:47]
	v_sub_f32_e32 v16, v17, v146
	v_exp_f32_e32 v48, v48
	v_cndmask_b32_e64 v80, v40, 0, s[26:27]
	v_sub_f32_e32 v40, v81, v147
	v_exp_f32_e32 v40, v40
	v_exp_f32_e32 v16, v16
	v_cndmask_b32_e64 v87, v48, 0, s[40:41]
	v_sub_f32_e32 v48, v50, v146
	v_cndmask_b32_e64 v81, v40, 0, s[28:29]
	v_sub_f32_e32 v40, v82, v147
	v_exp_f32_e32 v40, v40
	v_cndmask_b32_e64 v91, v16, 0, s[48:49]
	v_sub_f32_e32 v16, v18, v146
	v_exp_f32_e32 v48, v48
	v_exp_f32_e32 v16, v16
	v_cndmask_b32_e64 v82, v40, 0, s[30:31]
	v_sub_f32_e32 v40, v83, v147
	v_exp_f32_e32 v40, v40
	v_cndmask_b32_e64 v88, v48, 0, s[42:43]
	v_sub_f32_e32 v48, v51, v146
	v_cndmask_b32_e64 v148, v16, 0, s[50:51]
	v_sub_f32_e32 v16, v19, v146
	v_sub_f32_e32 v60, v149, v146
	v_exp_f32_e32 v48, v48
	v_exp_f32_e32 v16, v16
	v_exp_f32_e32 v60, v60
	v_cndmask_b32_e64 v83, v40, 0, s[34:35]
	v_cvt_pk_bf16_f32 v40, v85, v61
	v_cvt_pk_bf16_f32 v41, v62, v63
	v_cvt_pk_bf16_f32 v42, v80, v81
	v_cvt_pk_bf16_f32 v43, v82, v83
	v_cndmask_b32_e64 v89, v48, 0, s[44:45]
	v_cndmask_b32_e64 v149, v16, 0, s[52:53]
	v_pk_mul_f32 v[50:51], v[98:99], v[84:85] op_sel_hi:[1,0]
	v_pk_mul_f32 v[48:49], v[96:97], v[84:85] op_sel_hi:[1,0]
	v_cvt_pk_bf16_f32 v16, v86, v87
	v_cvt_pk_bf16_f32 v17, v88, v89
	v_cvt_pk_bf16_f32 v18, v90, v91
	v_cvt_pk_bf16_f32 v19, v148, v149
	s_waitcnt lgkmcnt(10)
	v_mfma_f32_16x16x32_bf16 v[64:67], v[140:143], v[40:43], v[48:51]
	s_cselect_b64 s[38:39], -1, 0
	s_add_i32 s0, s76, 0xfffffc00
	s_min_i32 s1, s0, 0
	v_pk_mul_f32 v[50:51], v[102:103], v[60:61] op_sel_hi:[1,0]
	v_pk_mul_f32 v[48:49], v[100:101], v[60:61] op_sel_hi:[1,0]
	s_sub_i32 s1, 15, s1
	s_ashr_i32 s1, s1, 4
	v_mfma_f32_16x16x32_bf16 v[100:103], v[140:143], v[16:19], v[48:51]
	s_sub_i32 s0, s75, s0
	s_ashr_i32 s0, s0, 4
	s_or_b32 s40, s76, 8
	v_pk_mul_f32 v[50:51], v[106:107], v[84:85] op_sel_hi:[1,0]
	v_pk_mul_f32 v[48:49], v[104:105], v[84:85] op_sel_hi:[1,0]
	s_lshl_b32 s56, s56, 7
	s_add_i32 s71, s71, s78
	s_waitcnt lgkmcnt(8)
	v_mfma_f32_16x16x32_bf16 v[104:107], v[136:139], v[40:43], v[48:51]
	s_nop 2
	v_mul_f32_e64 v50, v110, v60
	v_mul_f32_e64 v51, v111, v60
	v_pk_mul_f32 v[48:49], v[108:109], v[60:61] op_sel_hi:[1,0]
	s_nop 1
	v_mfma_f32_16x16x32_bf16 v[108:111], v[136:139], v[16:19], v[48:51]
	s_nop 2
	v_mul_f32_e64 v50, v114, v84
	v_mul_f32_e64 v51, v115, v84
	v_pk_mul_f32 v[48:49], v[112:113], v[84:85] op_sel_hi:[1,0]
	s_waitcnt lgkmcnt(6)
	s_nop 0
	v_mfma_f32_16x16x32_bf16 v[112:115], v[132:135], v[40:43], v[48:51]
	s_nop 2
	v_mul_f32_e64 v50, v118, v60
	v_mul_f32_e64 v51, v119, v60
	v_pk_mul_f32 v[48:49], v[116:117], v[60:61] op_sel_hi:[1,0]
	s_nop 1
	v_mfma_f32_16x16x32_bf16 v[116:119], v[132:135], v[16:19], v[48:51]
	s_nop 2
	v_mul_f32_e64 v50, v122, v84
	v_mul_f32_e64 v51, v123, v84
	v_pk_mul_f32 v[48:49], v[120:121], v[84:85] op_sel_hi:[1,0]
	s_waitcnt lgkmcnt(4)
	s_nop 0
	v_mfma_f32_16x16x32_bf16 v[120:123], v[128:131], v[40:43], v[48:51]
	v_mul_f32_e64 v42, v126, v60
	v_mul_f32_e64 v43, v127, v60
	v_pk_mul_f32 v[40:41], v[124:125], v[60:61] op_sel_hi:[1,0]
	s_nop 1
	v_mfma_f32_16x16x32_bf16 v[124:127], v[128:131], v[16:19], v[40:43]
	v_add_f32_e32 v16, v87, v86
	v_add_f32_e32 v16, v88, v16
	v_add_f32_e32 v16, v89, v16
	v_add_f32_e32 v16, v90, v16
	v_add_f32_e32 v16, v91, v16
	v_add_f32_e32 v16, v148, v16
	v_add_f32_e32 v151, v149, v16
	v_add_f32_e32 v16, v61, v85
	v_add_f32_e32 v16, v62, v16
	v_add_f32_e32 v16, v63, v16
	v_add_f32_e32 v16, v80, v16
	v_add_f32_e32 v16, v81, v16
	v_add_f32_e32 v16, v82, v16
	v_fmac_f32_e32 v151, v145, v60
	v_add_f32_e32 v145, v83, v16
	v_add_u32_e32 v16, s76, v213
	v_fmac_f32_e32 v145, v144, v84
	v_ashrrev_i32_e32 v148, 4, v250
	v_med3_i32 v16, v16, 0, s75
	v_lshl_add_u32 v16, v16, 9, v152
	global_load_dwordx4 v[80:83], v16, s[98:99]
	v_add_u32_e32 v16, s76, v215
	v_max_i32_e32 v150, s1, v148
	s_nop 0
	v_med3_i32 v16, v16, 0, s75
	v_lshl_add_u32 v16, v16, 9, v152
	global_load_dwordx4 v[84:87], v16, s[98:99]
	v_add_u32_e32 v16, s76, v217
	v_med3_i32 v16, v16, 0, s75
	v_lshl_add_u32 v16, v16, 9, v152
	global_load_dwordx4 v[88:91], v16, s[98:99]
	v_add_u32_e32 v16, s76, v219
	v_med3_i32 v16, v16, 0, s75
	v_lshl_add_u32 v16, v16, 9, v152
	global_load_dwordx4 v[96:99], v16, s[98:99]
	v_min_i32_e32 v16, s75, v251
	v_cndmask_b32_e64 v16, v16, 0, s[38:39]
	v_lshl_add_u32 v16, v16, 9, v158
	global_load_dwordx4 v[48:51], v16, s[100:101]
	global_load_dwordx4 v[60:63], v16, s[100:101] offset:64
	v_add_u32_e32 v16, s76, v228
	v_med3_i32 v16, v16, 0, s75
	v_lshl_add_u32 v16, v16, 9, v158
	global_load_dwordx4 v[40:43], v16, s[100:101]
	global_load_dwordx4 v[16:19], v16, s[100:101] offset:64
	ds_read_b64_tr_b16 v[142:143], v169 offset:2304
	ds_read_b64_tr_b16 v[140:141], v169
	ds_read_b64_tr_b16 v[136:137], v169 offset:32
	ds_read_b64_tr_b16 v[138:139], v169 offset:2336
	ds_read_b64_tr_b16 v[132:133], v169 offset:64
	ds_read_b64_tr_b16 v[134:135], v169 offset:2368
	ds_read_b64_tr_b16 v[128:129], v169 offset:96
	ds_read_b64_tr_b16 v[130:131], v169 offset:2400
	s_waitcnt vmcnt(15)
	ds_write_b128 v241, v[68:71] offset:4608
	s_waitcnt vmcnt(14)
	ds_write_b128 v242, v[72:75] offset:4608
	s_waitcnt vmcnt(13)
	ds_write_b128 v243, v[76:79] offset:4608
	s_waitcnt vmcnt(12)
	ds_write_b128 v244, v[92:95] offset:4608
	v_mfma_f32_16x16x32_bf16 v[72:75], v[32:35], v[4:7], 0
	v_mfma_f32_16x16x32_bf16 v[68:71], v[56:59], v[4:7], 0
	v_mfma_f32_16x16x32_bf16 v[72:75], v[24:27], v[8:11], v[72:75]
	v_mfma_f32_16x16x32_bf16 v[68:71], v[36:39], v[8:11], v[68:71]
	s_nop 5
	v_add_u32_e32 v25, 0x800, v250
	v_ashrrev_i32_e32 v25, 4, v25
	v_min3_i32 v25, v25, s0, v248
	v_sub_u32_e32 v26, v154, v150
	v_sub_u32_e32 v149, v25, v150
	v_add_u32_e32 v27, 1, v26
	v_cmp_gt_u32_e64 s[0:1], v27, v149
	v_cmp_gt_u32_e32 vcc, v26, v149
	s_nop 0
	v_cndmask_b32_e64 v69, v69, v246, s[0:1]
	s_nop 0
	v_cndmask_b32_e32 v68, v68, v246, vcc
	v_max_f32_e32 v25, v68, v69
	v_add_u32_e32 v27, 2, v26
	v_add_u32_e32 v32, 3, v26
	v_cmp_gt_u32_e64 s[22:23], v27, v149
	v_cmp_gt_u32_e64 s[24:25], v32, v149
	s_nop 0
	v_cndmask_b32_e64 v70, v70, v246, s[22:23]
	s_nop 0
	v_cndmask_b32_e64 v71, v71, v246, s[24:25]
	v_max3_f32 v25, v25, v70, v71
	v_add_u32_e32 v27, 16, v26
	v_add_u32_e32 v32, 17, v26
	v_cmp_gt_u32_e64 s[26:27], v27, v149
	v_cmp_gt_u32_e64 s[28:29], v32, v149
	s_nop 0
	v_cndmask_b32_e64 v72, v72, v246, s[26:27]
	v_cndmask_b32_e64 v73, v73, v246, s[28:29]
	v_max3_f32 v25, v25, v72, v73
	v_add_u32_e32 v27, 18, v26
	v_add_u32_e32 v26, 19, v26
	v_cmp_gt_u32_e64 s[30:31], v27, v149
	v_cmp_gt_u32_e64 s[34:35], v26, v149
	s_nop 0
	v_cndmask_b32_e64 v74, v74, v246, s[30:31]
	v_cndmask_b32_e64 v75, v75, v246, s[34:35]
	v_max3_f32 v25, v25, v74, v75
	v_mov_b32_e32 v27, v25
	s_nop 1
	v_permlane32_swap_b32_e32 v27, v25
	v_max_f32_e32 v25, v25, v27
	s_nop 1
	v_mov_b32_e32 v27, v25
	s_nop 1
	v_permlane16_swap_b32_e32 v27, v25
	v_max3_f32 v144, v147, v25, v27
	v_sub_f32_e32 v25, v147, v144
	v_exp_f32_e32 v56, v25
	v_sub_f32_e32 v25, v68, v144
	v_exp_f32_e32 v25, v25
	v_sub_f32_e32 v32, v69, v144
	v_exp_f32_e32 v32, v32
	v_sub_f32_e32 v33, v70, v144
	v_exp_f32_e32 v33, v33
	v_sub_f32_e32 v34, v71, v144
	v_exp_f32_e32 v34, v34
	v_sub_f32_e32 v35, v72, v144
	v_exp_f32_e32 v35, v35
	v_sub_f32_e32 v38, v73, v144
	v_exp_f32_e32 v38, v38
	v_sub_f32_e32 v39, v74, v144
	v_add_f32_e32 v27, v32, v25
	v_exp_f32_e32 v39, v39
	v_sub_f32_e32 v57, v75, v144
	v_add_f32_e32 v27, v33, v27
	v_exp_f32_e32 v57, v57
	v_add_f32_e32 v27, v34, v27
	v_add_f32_e32 v27, v35, v27
	v_add_f32_e32 v27, v38, v27
	v_add_f32_e32 v27, v39, v27
	v_add_f32_e32 v147, v57, v27
	v_fmac_f32_e32 v147, v145, v56
	v_mov_b32_e32 v145, v146
	v_cvt_pk_bf16_f32 v32, v25, v32
	v_mov_b32_e32 v58, 1.0
	v_cvt_pk_bf16_f32 v33, v33, v34
	v_mov_b32_e32 v25, 0
	v_cvt_pk_bf16_f32 v34, v35, v38
	v_cvt_pk_bf16_f32 v35, v39, v57
	v_mov_b32_e32 v27, 0
	v_pk_mul_f32 v[38:39], v[66:67], v[56:57] op_sel_hi:[1,0]
	v_pk_mul_f32 v[36:37], v[64:65], v[56:57] op_sel_hi:[1,0]
	v_add_f32_e32 v146, v27, v25
	v_cvt_pk_bf16_f32 v24, v25, 0
	v_cvt_pk_bf16_f32 v26, v27, 0
	v_mov_b32_e32 v25, v153
	v_mov_b32_e32 v27, v153
	s_waitcnt lgkmcnt(10)
	v_mfma_f32_16x16x32_bf16 v[76:79], v[140:143], v[32:35], v[36:39]
	v_fmac_f32_e32 v146, v151, v58
	s_nop 1
	v_pk_mul_f32 v[38:39], v[102:103], v[58:59] op_sel_hi:[1,0]
	v_pk_mul_f32 v[36:37], v[100:101], v[58:59] op_sel_hi:[1,0]
	s_nop 1
	v_mfma_f32_16x16x32_bf16 v[100:103], v[140:143], v[24:27], v[36:39]
	s_nop 2
	v_mul_f32_e64 v38, v106, v56
	v_mul_f32_e64 v39, v107, v56
	v_pk_mul_f32 v[36:37], v[104:105], v[56:57] op_sel_hi:[1,0]
	s_waitcnt lgkmcnt(8)
	s_nop 0
	v_mfma_f32_16x16x32_bf16 v[104:107], v[136:139], v[32:35], v[36:39]
	s_nop 2
	v_mul_f32_e64 v38, v110, v58
	v_mul_f32_e64 v39, v111, v58
	v_pk_mul_f32 v[36:37], v[108:109], v[58:59] op_sel_hi:[1,0]
	s_nop 1
	v_mfma_f32_16x16x32_bf16 v[108:111], v[136:139], v[24:27], v[36:39]
	s_nop 2
	v_mul_f32_e64 v38, v114, v56
	v_mul_f32_e64 v39, v115, v56
	v_pk_mul_f32 v[36:37], v[112:113], v[56:57] op_sel_hi:[1,0]
	s_waitcnt lgkmcnt(6)
	s_nop 0
	v_mfma_f32_16x16x32_bf16 v[112:115], v[132:135], v[32:35], v[36:39]
	s_nop 2
	v_mul_f32_e64 v38, v118, v58
	v_mul_f32_e64 v39, v119, v58
	v_pk_mul_f32 v[36:37], v[116:117], v[58:59] op_sel_hi:[1,0]
	s_nop 1
	v_mfma_f32_16x16x32_bf16 v[116:119], v[132:135], v[24:27], v[36:39]
	s_nop 2
	v_mul_f32_e64 v38, v122, v56
	v_mul_f32_e64 v39, v123, v56
	v_pk_mul_f32 v[36:37], v[120:121], v[56:57] op_sel_hi:[1,0]
	v_add_u32_e32 v56, s76, v232
	s_waitcnt lgkmcnt(4)
	v_mfma_f32_16x16x32_bf16 v[120:123], v[128:131], v[32:35], v[36:39]
	v_mul_f32_e64 v34, v126, v58
	v_mul_f32_e64 v35, v127, v58
	v_pk_mul_f32 v[32:33], v[124:125], v[58:59] op_sel_hi:[1,0]
	v_add_u32_e32 v36, s76, v231
	s_nop 0
	v_mfma_f32_16x16x32_bf16 v[124:127], v[128:131], v[24:27], v[32:35]
	v_add_u32_e32 v24, s76, v229
	s_nop 1
	v_add_u32_e32 v32, s76, v230
	v_med3_i32 v24, v24, 0, s75
	v_med3_i32 v32, v32, 0, s75
	v_med3_i32 v36, v36, 0, s75
	v_med3_i32 v56, v56, 0, s75
	v_lshl_add_u32 v36, v36, 9, v152
	v_lshl_add_u32 v56, v56, 9, v152
	global_load_dwordx4 v[36:39], v36, s[98:99]
	global_load_dwordx4 v[92:95], v56, s[98:99]
	v_add_u32_e32 v56, s76, v233
	v_med3_i32 v56, v56, 0, s75
	v_lshl_add_u32 v24, v24, 9, v152
	v_lshl_add_u32 v32, v32, 9, v152
	v_lshl_add_u32 v56, v56, 9, v158
	global_load_dwordx4 v[24:27], v24, s[98:99]
	global_load_dwordx4 v[32:35], v32, s[98:99]
	global_load_dwordx4 v[72:75], v56, s[100:101]
	global_load_dwordx4 v[68:71], v56, s[100:101] offset:64
	v_add_u32_e32 v56, s76, v234
	v_med3_i32 v56, v56, 0, s75
	v_lshl_add_u32 v56, v56, 9, v158
	global_load_dwordx4 v[64:67], v56, s[100:101]
	global_load_dwordx4 v[56:59], v56, s[100:101] offset:64
	ds_read_b64_tr_b16 v[142:143], v169 offset:6912
	ds_read_b64_tr_b16 v[140:141], v169 offset:4608
	ds_read_b64_tr_b16 v[136:137], v169 offset:4640
	ds_read_b64_tr_b16 v[138:139], v169 offset:6944
	ds_read_b64_tr_b16 v[132:133], v169 offset:4672
	ds_read_b64_tr_b16 v[134:135], v169 offset:6976
	ds_read_b64_tr_b16 v[128:129], v169 offset:4704
	ds_read_b64_tr_b16 v[130:131], v169 offset:7008
	s_waitcnt vmcnt(15)
	ds_write_b128 v241, v[80:83]
	s_waitcnt vmcnt(14)
	ds_write_b128 v242, v[84:87]
	s_waitcnt vmcnt(13)
	ds_write_b128 v243, v[88:91]
	s_waitcnt vmcnt(12)
	ds_write_b128 v244, v[96:99]
	v_mfma_f32_16x16x32_bf16 v[80:83], v[52:55], v[4:7], 0
	v_mfma_f32_16x16x32_bf16 v[84:87], v[28:31], v[4:7], 0
	v_mfma_f32_16x16x32_bf16 v[80:83], v[44:47], v[8:11], v[80:83]
	v_mfma_f32_16x16x32_bf16 v[84:87], v[20:23], v[8:11], v[84:87]
	s_nop 5
	v_sub_u32_e32 v21, v187, v150
	v_add_u32_e32 v23, 1, v21
	v_cmp_gt_u32_e64 s[0:1], v23, v149
	v_cmp_gt_u32_e32 vcc, v21, v149
	s_nop 0
	v_cndmask_b32_e64 v81, v81, v246, s[0:1]
	s_nop 0
	v_cndmask_b32_e32 v80, v80, v246, vcc
	v_max_f32_e32 v22, v80, v81
	v_add_u32_e32 v23, 2, v21
	v_add_u32_e32 v28, 3, v21
	v_cmp_gt_u32_e64 s[22:23], v23, v149
	v_cmp_gt_u32_e64 s[24:25], v28, v149
	s_nop 0
	v_cndmask_b32_e64 v82, v82, v246, s[22:23]
	v_cndmask_b32_e64 v83, v83, v246, s[24:25]
	v_max3_f32 v22, v22, v82, v83
	v_add_u32_e32 v23, 16, v21
	v_add_u32_e32 v28, 17, v21
	v_cmp_gt_u32_e64 s[26:27], v23, v149
	v_cmp_gt_u32_e64 s[28:29], v28, v149
	s_nop 0
	v_cndmask_b32_e64 v84, v84, v246, s[26:27]
	v_cndmask_b32_e64 v85, v85, v246, s[28:29]
	v_max3_f32 v22, v22, v84, v85
	v_add_u32_e32 v23, 18, v21
	v_add_u32_e32 v21, 19, v21
	v_cmp_gt_u32_e64 s[30:31], v23, v149
	v_cmp_gt_u32_e64 s[34:35], v21, v149
	s_nop 0
	v_cndmask_b32_e64 v86, v86, v246, s[30:31]
	v_cndmask_b32_e64 v87, v87, v246, s[34:35]
	v_max3_f32 v21, v22, v86, v87
	v_mov_b32_e32 v23, v21
	s_nop 1
	v_permlane32_swap_b32_e32 v23, v21
	v_max_f32_e32 v21, v21, v23
	s_nop 1
	v_mov_b32_e32 v23, v21
	s_nop 1
	v_permlane16_swap_b32_e32 v23, v21
	v_max3_f32 v175, v144, v21, v23
	v_sub_f32_e32 v21, v144, v175
	v_exp_f32_e32 v144, v21
	v_sub_f32_e32 v21, v80, v175
	v_sub_f32_e32 v28, v81, v175
	v_exp_f32_e32 v21, v21
	v_exp_f32_e32 v28, v28
	v_sub_f32_e32 v30, v82, v175
	v_exp_f32_e32 v30, v30
	v_sub_f32_e32 v31, v83, v175
	v_exp_f32_e32 v31, v31
	v_sub_f32_e32 v45, v84, v175
	v_exp_f32_e32 v45, v45
	v_sub_f32_e32 v46, v85, v175
	v_mov_b32_e32 v176, v145
	v_exp_f32_e32 v46, v46
	v_sub_f32_e32 v47, v86, v175
	v_cvt_pk_bf16_f32 v80, v21, v28
	v_add_f32_e32 v23, v28, v21
	v_exp_f32_e32 v47, v47
	v_sub_f32_e32 v52, v87, v175
	v_mov_b32_e32 v84, 1.0
	v_add_f32_e32 v23, v30, v23
	v_exp_f32_e32 v52, v52
	v_add_f32_e32 v23, v31, v23
	v_add_f32_e32 v23, v45, v23
	v_add_f32_e32 v23, v46, v23
	v_add_f32_e32 v23, v47, v23
	v_mov_b32_e32 v21, 0
	v_add_f32_e32 v151, v52, v23
	v_mov_b32_e32 v23, 0
	v_fmac_f32_e32 v151, v147, v144
	v_cvt_pk_bf16_f32 v81, v30, v31
	v_add_f32_e32 v147, v23, v21
	v_cvt_pk_bf16_f32 v20, v21, 0
	v_cvt_pk_bf16_f32 v22, v23, 0
	v_mov_b32_e32 v21, v153
	v_mov_b32_e32 v23, v153
	v_pk_mul_f32 v[30:31], v[78:79], v[144:145] op_sel_hi:[1,0]
	v_pk_mul_f32 v[28:29], v[76:77], v[144:145] op_sel_hi:[1,0]
	v_pk_mul_f32 v[78:79], v[110:111], v[84:85] op_sel_hi:[1,0]
	v_pk_mul_f32 v[76:77], v[108:109], v[84:85] op_sel_hi:[1,0]
	v_cvt_pk_bf16_f32 v82, v45, v46
	v_cvt_pk_bf16_f32 v83, v47, v52
	s_waitcnt lgkmcnt(8)
	v_mfma_f32_16x16x32_bf16 v[88:91], v[136:139], v[20:23], v[76:79]
	v_mul_f32_e64 v46, v102, v84
	v_mul_f32_e64 v47, v103, v84
	v_pk_mul_f32 v[44:45], v[100:101], v[84:85] op_sel_hi:[1,0]
	v_pk_mul_f32 v[54:55], v[106:107], v[144:145] op_sel_hi:[1,0]
	v_pk_mul_f32 v[78:79], v[114:115], v[144:145] op_sel_hi:[1,0]
	v_pk_mul_f32 v[76:77], v[112:113], v[144:145] op_sel_hi:[1,0]
	v_pk_mul_f32 v[52:53], v[104:105], v[144:145] op_sel_hi:[1,0]
	v_mfma_f32_16x16x32_bf16 v[44:47], v[140:143], v[20:23], v[44:47]
	v_fmac_f32_e32 v147, v146, v84
	s_waitcnt lgkmcnt(6)
	v_mfma_f32_16x16x32_bf16 v[96:99], v[132:135], v[80:83], v[76:79]
	s_nop 2
	v_mul_f32_e64 v78, v118, v84
	v_mul_f32_e64 v79, v119, v84
	v_pk_mul_f32 v[76:77], v[116:117], v[84:85] op_sel_hi:[1,0]
	v_mfma_f32_16x16x32_bf16 v[28:31], v[140:143], v[80:83], v[28:31]
	s_nop 0
	v_mfma_f32_16x16x32_bf16 v[100:103], v[132:135], v[20:23], v[76:79]
	s_nop 2
	v_mul_f32_e64 v78, v122, v144
	v_mul_f32_e64 v79, v123, v144
	v_pk_mul_f32 v[76:77], v[120:121], v[144:145] op_sel_hi:[1,0]
	v_mfma_f32_16x16x32_bf16 v[52:55], v[136:139], v[80:83], v[52:55]
	s_waitcnt lgkmcnt(4)
	v_mfma_f32_16x16x32_bf16 v[104:107], v[128:131], v[80:83], v[76:79]
	s_nop 2
	v_mul_f32_e64 v78, v126, v84
	v_mul_f32_e64 v79, v127, v84
	v_pk_mul_f32 v[76:77], v[124:125], v[84:85] op_sel_hi:[1,0]
	s_nop 1
	v_mfma_f32_16x16x32_bf16 v[108:111], v[128:131], v[20:23], v[76:79]
	v_add_u32_e32 v20, s76, v235
	v_med3_i32 v20, v20, 0, s75
	v_lshl_add_u32 v20, v20, 9, v152
	global_load_dwordx4 v[112:115], v20, s[98:99]
	v_add_u32_e32 v20, s76, v236
	v_med3_i32 v20, v20, 0, s75
	v_lshl_add_u32 v20, v20, 9, v152
	global_load_dwordx4 v[116:119], v20, s[98:99]
	v_add_u32_e32 v20, s76, v237
	v_med3_i32 v20, v20, 0, s75
	v_lshl_add_u32 v20, v20, 9, v152
	global_load_dwordx4 v[120:123], v20, s[98:99]
	v_add_u32_e32 v20, s76, v238
	v_med3_i32 v20, v20, 0, s75
	v_lshl_add_u32 v20, v20, 9, v152
	global_load_dwordx4 v[124:127], v20, s[98:99]
	v_add_u32_e32 v20, s76, v239
	v_med3_i32 v20, v20, 0, s75
	v_lshl_add_u32 v20, v20, 9, v158
	global_load_dwordx4 v[84:87], v20, s[100:101]
	global_load_dwordx4 v[80:83], v20, s[100:101] offset:64
	v_add_u32_e32 v20, s76, v240
	s_addk_i32 s76, 0xfc08
	s_nop 0
	v_med3_i32 v20, v20, 0, s75
	v_lshl_add_u32 v20, v20, 9, v158
	global_load_dwordx4 v[76:79], v20, s[100:101]
	global_load_dwordx4 v[20:23], v20, s[100:101] offset:64
	ds_read_b64_tr_b16 v[142:143], v169 offset:2304
	ds_read_b64_tr_b16 v[140:141], v169
	ds_read_b64_tr_b16 v[136:137], v169 offset:32
	ds_read_b64_tr_b16 v[138:139], v169 offset:2336
	ds_read_b64_tr_b16 v[132:133], v169 offset:64
	ds_read_b64_tr_b16 v[134:135], v169 offset:2368
	ds_read_b64_tr_b16 v[128:129], v169 offset:96
	ds_read_b64_tr_b16 v[130:131], v169 offset:2400
	s_waitcnt vmcnt(13)
	ds_write_b128 v241, v[24:27] offset:4608
	s_waitcnt vmcnt(12)
	ds_write_b128 v242, v[32:35] offset:4608
	ds_write_b128 v243, v[36:39] offset:4608
	ds_write_b128 v244, v[92:95] offset:4608
	v_mfma_f32_16x16x32_bf16 v[24:27], v[48:51], v[4:7], 0
	v_mfma_f32_16x16x32_bf16 v[32:35], v[40:43], v[4:7], 0
	v_mfma_f32_16x16x32_bf16 v[24:27], v[60:63], v[8:11], v[24:27]
	v_mfma_f32_16x16x32_bf16 v[32:35], v[16:19], v[8:11], v[32:35]
	s_nop 7
	v_sub_u32_e32 v17, v192, v150
	v_add_u32_e32 v19, 1, v17
	v_cmp_gt_u32_e64 s[0:1], v19, v149
	v_cmp_gt_u32_e32 vcc, v17, v149
	s_nop 0
	v_cndmask_b32_e64 v25, v25, v246, s[0:1]
	s_nop 0
	v_cndmask_b32_e32 v24, v24, v246, vcc
	v_max_f32_e32 v18, v24, v25
	v_add_u32_e32 v19, 2, v17
	v_add_u32_e32 v37, 3, v17
	v_cmp_gt_u32_e64 s[22:23], v19, v149
	v_cmp_gt_u32_e64 s[24:25], v37, v149
	s_nop 0
	v_cndmask_b32_e64 v26, v26, v246, s[22:23]
	v_cndmask_b32_e64 v27, v27, v246, s[24:25]
	v_max3_f32 v18, v18, v26, v27
	v_add_u32_e32 v19, 16, v17
	v_add_u32_e32 v37, 17, v17
	v_cmp_gt_u32_e64 s[26:27], v19, v149
	v_cmp_gt_u32_e64 s[28:29], v37, v149
	s_nop 0
	v_cndmask_b32_e64 v32, v32, v246, s[26:27]
	v_cndmask_b32_e64 v33, v33, v246, s[28:29]
	v_max3_f32 v18, v18, v32, v33
	v_add_u32_e32 v19, 18, v17
	v_add_u32_e32 v17, 19, v17
	v_cmp_gt_u32_e64 s[30:31], v19, v149
	v_cmp_gt_u32_e64 s[34:35], v17, v149
	s_nop 0
	v_cndmask_b32_e64 v34, v34, v246, s[30:31]
	v_cndmask_b32_e64 v35, v35, v246, s[34:35]
	v_max3_f32 v17, v18, v34, v35
	v_mov_b32_e32 v19, v17
	s_nop 1
	v_permlane32_swap_b32_e32 v19, v17
	v_max_f32_e32 v17, v17, v19
	s_nop 1
	v_mov_b32_e32 v19, v17
	s_nop 1
	v_permlane16_swap_b32_e32 v19, v17
	v_max3_f32 v145, v175, v17, v19
	v_sub_f32_e32 v17, v175, v145
	v_exp_f32_e32 v38, v17
	v_sub_f32_e32 v17, v24, v145
	v_exp_f32_e32 v17, v17
	s_nop 1
	v_cndmask_b32_e64 v37, v17, 0, vcc
	v_sub_f32_e32 v17, v25, v145
	v_exp_f32_e32 v17, v17
	v_mov_b32_e32 v144, v176
	v_cndmask_b32_e64 v60, v17, 0, s[0:1]
	v_sub_f32_e32 v17, v26, v145
	v_exp_f32_e32 v17, v17
	v_cvt_pk_bf16_f32 v24, v37, v60
	v_cndmask_b32_e64 v61, v17, 0, s[22:23]
	v_sub_f32_e32 v17, v27, v145
	v_exp_f32_e32 v17, v17
	v_mov_b32_e32 v39, 0
	v_pk_mul_f32 v[30:31], v[30:31], v[38:39] op_sel_hi:[1,0]
	v_pk_mul_f32 v[28:29], v[28:29], v[38:39] op_sel_hi:[1,0]
	v_cndmask_b32_e64 v62, v17, 0, s[24:25]
	v_sub_f32_e32 v17, v32, v145
	v_exp_f32_e32 v17, v17
	v_cvt_pk_bf16_f32 v25, v61, v62
	v_cvt_pk_bf16_f32 v18, v39, 0
	v_mov_b32_e32 v19, v153
	v_cndmask_b32_e64 v63, v17, 0, s[26:27]
	v_sub_f32_e32 v17, v33, v145
	v_exp_f32_e32 v17, v17
	s_nop 0
	v_cndmask_b32_e64 v33, v17, 0, s[28:29]
	v_sub_f32_e32 v17, v34, v145
	v_exp_f32_e32 v17, v17
	v_cvt_pk_bf16_f32 v26, v63, v33
	v_cndmask_b32_e64 v34, v17, 0, s[30:31]
	v_sub_f32_e32 v17, v35, v145
	v_exp_f32_e32 v17, v17
	s_nop 0
	v_cndmask_b32_e64 v35, v17, 0, s[34:35]
	v_mov_b32_e32 v32, 1.0
	v_cvt_pk_bf16_f32 v27, v34, v35
	v_mov_b32_e32 v36, 0
	v_cvt_pk_bf16_f32 v16, v36, 0
	v_mov_b32_e32 v17, v153
	s_waitcnt lgkmcnt(10)
	v_mfma_f32_16x16x32_bf16 v[40:43], v[140:143], v[24:27], v[28:31]
	s_nop 2
	v_mul_f32_e64 v30, v46, v32
	v_mul_f32_e64 v31, v47, v32
	v_pk_mul_f32 v[28:29], v[44:45], v[32:33] op_sel_hi:[1,0]
	s_nop 1
	v_mfma_f32_16x16x32_bf16 v[44:47], v[140:143], v[16:19], v[28:31]
	s_nop 2
	v_mul_f32_e64 v30, v54, v38
	v_mul_f32_e64 v31, v55, v38
	v_pk_mul_f32 v[28:29], v[52:53], v[38:39] op_sel_hi:[1,0]
	s_waitcnt lgkmcnt(8)
	s_nop 0
	v_mfma_f32_16x16x32_bf16 v[48:51], v[136:139], v[24:27], v[28:31]
	s_nop 2
	v_mul_f32_e64 v30, v90, v32
	v_mul_f32_e64 v31, v91, v32
	v_pk_mul_f32 v[28:29], v[88:89], v[32:33] op_sel_hi:[1,0]
	s_nop 1
	v_mfma_f32_16x16x32_bf16 v[52:55], v[136:139], v[16:19], v[28:31]
	s_nop 2
	v_mul_f32_e64 v30, v98, v38
	v_mul_f32_e64 v31, v99, v38
	v_pk_mul_f32 v[28:29], v[96:97], v[38:39] op_sel_hi:[1,0]
	s_waitcnt lgkmcnt(6)
	s_nop 0
	v_mfma_f32_16x16x32_bf16 v[88:91], v[132:135], v[24:27], v[28:31]
	s_nop 2
	v_mul_f32_e64 v30, v102, v32
	v_mul_f32_e64 v31, v103, v32
	v_pk_mul_f32 v[28:29], v[100:101], v[32:33] op_sel_hi:[1,0]
	s_nop 1
	v_mfma_f32_16x16x32_bf16 v[100:103], v[132:135], v[16:19], v[28:31]
	s_nop 2
	v_mul_f32_e64 v30, v106, v38
	v_mul_f32_e64 v31, v107, v38
	v_pk_mul_f32 v[28:29], v[104:105], v[38:39] op_sel_hi:[1,0]
	s_waitcnt lgkmcnt(4)
	s_nop 0
	v_mfma_f32_16x16x32_bf16 v[104:107], v[128:131], v[24:27], v[28:31]
	v_mul_f32_e64 v26, v110, v32
	v_mul_f32_e64 v27, v111, v32
	v_pk_mul_f32 v[24:25], v[108:109], v[32:33] op_sel_hi:[1,0]
	s_nop 1
	v_mfma_f32_16x16x32_bf16 v[108:111], v[128:131], v[16:19], v[24:27]
	v_add_f32_e32 v146, v39, v36
	v_add_f32_e32 v16, v60, v37
	v_add_f32_e32 v16, v61, v16
	v_add_f32_e32 v16, v62, v16
	v_add_f32_e32 v16, v63, v16
	v_add_f32_e32 v16, v33, v16
	v_add_f32_e32 v16, v34, v16
	v_fmac_f32_e32 v146, v147, v32
	v_add_f32_e32 v147, v35, v16
	v_add_u32_e32 v16, s40, v214
	v_add_u32_e32 v24, s40, v216
	v_med3_i32 v16, v16, 0, s75
	v_med3_i32 v24, v24, 0, s75
	v_lshl_add_u32 v16, v16, 9, v152
	v_lshl_add_u32 v24, v24, 9, v152
	global_load_dwordx4 v[16:19], v16, s[98:99]
	v_or_b32_e32 v32, 0xfffffd00, v167
	global_load_dwordx4 v[60:63], v24, s[98:99]
	v_add_u32_e32 v24, s40, v218
	v_add_u32_e32 v32, s40, v32
	v_med3_i32 v24, v24, 0, s75
	v_lshl_add_u32 v24, v24, 9, v152
	global_load_dwordx4 v[92:95], v24, s[98:99]
	v_add_u32_e32 v24, s40, v220
	v_fmac_f32_e32 v147, v151, v38
	s_nop 0
	v_med3_i32 v24, v24, 0, s75
	v_lshl_add_u32 v24, v24, 9, v152
	global_load_dwordx4 v[96:99], v24, s[98:99]
	v_add_u32_e32 v24, s40, v221
	v_med3_i32 v24, v24, 0, s75
	v_med3_i32 v32, v32, 0, s75
	v_lshl_add_u32 v28, v24, 9, v158
	v_lshl_add_u32 v36, v32, 9, v158
	global_load_dwordx4 v[24:27], v28, s[100:101]
	global_load_dwordx4 v[28:31], v28, s[100:101] offset:64
	global_load_dwordx4 v[32:35], v36, s[100:101]
	global_load_dwordx4 v[36:39], v36, s[100:101] offset:64
	ds_read_b64_tr_b16 v[142:143], v169 offset:6912
	ds_read_b64_tr_b16 v[140:141], v169 offset:4608
	ds_read_b64_tr_b16 v[132:133], v169 offset:4640
	ds_read_b64_tr_b16 v[134:135], v169 offset:6944
	ds_read_b64_tr_b16 v[128:129], v169 offset:4672
	ds_read_b64_tr_b16 v[130:131], v169 offset:6976
	ds_read_b64_tr_b16 v[136:137], v169 offset:4704
	ds_read_b64_tr_b16 v[138:139], v169 offset:7008
	s_waitcnt vmcnt(15)
	ds_write_b128 v241, v[112:115]
	s_waitcnt vmcnt(14)
	ds_write_b128 v242, v[116:119]
	s_waitcnt vmcnt(13)
	ds_write_b128 v243, v[120:123]
	s_waitcnt vmcnt(12)
	ds_write_b128 v244, v[124:127]
	v_mfma_f32_16x16x32_bf16 v[112:115], v[72:75], v[4:7], 0
	v_mfma_f32_16x16x32_bf16 v[116:119], v[64:67], v[4:7], 0
	v_mfma_f32_16x16x32_bf16 v[112:115], v[68:71], v[8:11], v[112:115]
	v_mfma_f32_16x16x32_bf16 v[116:119], v[56:59], v[8:11], v[116:119]
	s_nop 5
	v_sub_u32_e32 v57, v197, v150
	v_add_u32_e32 v59, 1, v57
	v_cmp_gt_u32_e64 s[0:1], v59, v149
	v_cmp_gt_u32_e32 vcc, v57, v149
	s_nop 0
	v_cndmask_b32_e64 v113, v113, v246, s[0:1]
	s_nop 0
	v_cndmask_b32_e32 v112, v112, v246, vcc
	v_max_f32_e32 v58, v112, v113
	v_add_u32_e32 v59, 2, v57
	v_add_u32_e32 v64, 3, v57
	v_cmp_gt_u32_e64 s[22:23], v59, v149
	v_cmp_gt_u32_e64 s[24:25], v64, v149
	s_nop 0
	v_cndmask_b32_e64 v114, v114, v246, s[22:23]
	v_cndmask_b32_e64 v115, v115, v246, s[24:25]
	v_max3_f32 v58, v58, v114, v115
	v_add_u32_e32 v59, 16, v57
	v_add_u32_e32 v64, 17, v57
	v_cmp_gt_u32_e64 s[26:27], v59, v149
	v_cmp_gt_u32_e64 s[28:29], v64, v149
	s_nop 0
	v_cndmask_b32_e64 v116, v116, v246, s[26:27]
	v_cndmask_b32_e64 v117, v117, v246, s[28:29]
	v_max3_f32 v58, v58, v116, v117
	v_add_u32_e32 v59, 18, v57
	v_add_u32_e32 v57, 19, v57
	v_cmp_gt_u32_e64 s[30:31], v59, v149
	v_cmp_gt_u32_e64 s[34:35], v57, v149
	s_nop 0
	v_cndmask_b32_e64 v118, v118, v246, s[30:31]
	v_cndmask_b32_e64 v119, v119, v246, s[34:35]
	v_max3_f32 v57, v58, v118, v119
	v_mov_b32_e32 v59, v57
	s_nop 1
	v_permlane32_swap_b32_e32 v59, v57
	v_max_f32_e32 v57, v57, v59
	s_nop 1
	v_mov_b32_e32 v59, v57
	s_nop 1
	v_permlane16_swap_b32_e32 v59, v57
	v_max3_f32 v175, v145, v57, v59
	v_sub_f32_e32 v57, v145, v175
	v_exp_f32_e32 v72, v57
	v_sub_f32_e32 v57, v112, v175
	v_exp_f32_e32 v57, v57
	v_sub_f32_e32 v64, v113, v175
	v_exp_f32_e32 v64, v64
	s_nop 0
	v_sub_f32_e32 v65, v114, v175
	v_exp_f32_e32 v65, v65
	v_sub_f32_e32 v66, v115, v175
	v_exp_f32_e32 v66, v66
	v_sub_f32_e32 v67, v116, v175
	v_mov_b32_e32 v177, v144
	v_add_f32_e32 v59, v64, v57
	v_exp_f32_e32 v67, v67
	v_sub_f32_e32 v70, v117, v175
	v_cvt_pk_bf16_f32 v64, v57, v64
	v_exp_f32_e32 v70, v70
	v_sub_f32_e32 v71, v118, v175
	v_sub_f32_e32 v73, v119, v175
	v_mov_b32_e32 v74, 1.0
	v_exp_f32_e32 v71, v71
	v_exp_f32_e32 v73, v73
	v_add_f32_e32 v59, v65, v59
	v_add_f32_e32 v59, v66, v59
	v_add_f32_e32 v59, v67, v59
	v_add_f32_e32 v59, v70, v59
	v_mov_b32_e32 v57, 0
	v_add_f32_e32 v59, v71, v59
	v_cvt_pk_bf16_f32 v65, v65, v66
	v_cvt_pk_bf16_f32 v66, v67, v70
	v_cvt_pk_bf16_f32 v67, v71, v73
	v_mov_b32_e32 v56, 0
	v_pk_mul_f32 v[42:43], v[42:43], v[72:73] op_sel_hi:[1,0]
	v_pk_mul_f32 v[40:41], v[40:41], v[72:73] op_sel_hi:[1,0]
	v_add_f32_e32 v176, v73, v59
	v_add_f32_e32 v178, v56, v57
	v_cvt_pk_bf16_f32 v68, v57, 0
	v_cvt_pk_bf16_f32 v70, v56, 0
	v_mov_b32_e32 v69, v153
	v_mov_b32_e32 v71, v153
	s_waitcnt lgkmcnt(10)
	v_mfma_f32_16x16x32_bf16 v[56:59], v[140:143], v[64:67], v[40:43]
	v_fmac_f32_e32 v176, v147, v72
	v_fmac_f32_e32 v178, v146, v74
	s_nop 0
	v_pk_mul_f32 v[42:43], v[46:47], v[74:75] op_sel_hi:[1,0]
	v_pk_mul_f32 v[40:41], v[44:45], v[74:75] op_sel_hi:[1,0]
	s_nop 1
	v_mfma_f32_16x16x32_bf16 v[112:115], v[140:143], v[68:71], v[40:43]
	s_nop 2
	v_mul_f32_e64 v42, v50, v72
	v_mul_f32_e64 v43, v51, v72
	v_pk_mul_f32 v[40:41], v[48:49], v[72:73] op_sel_hi:[1,0]
	v_add_u32_e32 v48, s40, v227
	v_min_i32_e32 v49, s75, v48
	s_waitcnt lgkmcnt(8)
	v_mfma_f32_16x16x32_bf16 v[116:119], v[132:135], v[64:67], v[40:43]
	s_nop 2
	v_mul_f32_e64 v42, v54, v74
	v_mul_f32_e64 v43, v55, v74
	v_pk_mul_f32 v[40:41], v[52:53], v[74:75] op_sel_hi:[1,0]
	s_nop 1
	v_mfma_f32_16x16x32_bf16 v[120:123], v[132:135], v[68:71], v[40:43]
	s_nop 2
	v_mul_f32_e64 v42, v90, v72
	v_mul_f32_e64 v43, v91, v72
	v_pk_mul_f32 v[40:41], v[88:89], v[72:73] op_sel_hi:[1,0]
	s_waitcnt lgkmcnt(6)
	s_nop 0
	v_mfma_f32_16x16x32_bf16 v[124:127], v[128:131], v[64:67], v[40:43]
	s_nop 2
	v_mul_f32_e64 v42, v102, v74
	v_mul_f32_e64 v43, v103, v74
	v_pk_mul_f32 v[40:41], v[100:101], v[74:75] op_sel_hi:[1,0]
	s_nop 1
	v_mfma_f32_16x16x32_bf16 v[128:131], v[128:131], v[68:71], v[40:43]
	s_nop 2
	v_mul_f32_e64 v42, v106, v72
	v_mul_f32_e64 v43, v107, v72
	v_pk_mul_f32 v[40:41], v[104:105], v[72:73] op_sel_hi:[1,0]
	s_waitcnt lgkmcnt(4)
	s_nop 0
	v_mfma_f32_16x16x32_bf16 v[132:135], v[136:139], v[64:67], v[40:43]
	s_nop 2
	v_mul_f32_e64 v42, v110, v74
	v_mul_f32_e64 v43, v111, v74
	v_pk_mul_f32 v[40:41], v[108:109], v[74:75] op_sel_hi:[1,0]
	s_nop 1
	v_mfma_f32_16x16x32_bf16 v[136:139], v[136:139], v[68:71], v[40:43]
	s_nop 2
	v_add_u32_e32 v40, s40, v222
	v_med3_i32 v40, v40, 0, s75
	v_lshl_add_u32 v40, v40, 9, v152
	global_load_dwordx4 v[64:67], v40, s[98:99]
	v_add_u32_e32 v40, s40, v223
	v_med3_i32 v40, v40, 0, s75
	v_lshl_add_u32 v40, v40, 9, v152
	global_load_dwordx4 v[68:71], v40, s[98:99]
	v_add_u32_e32 v40, s40, v224
	v_med3_i32 v40, v40, 0, s75
	v_lshl_add_u32 v40, v40, 9, v152
	global_load_dwordx4 v[72:75], v40, s[98:99]
	v_add_u32_e32 v40, s40, v225
	v_med3_i32 v40, v40, 0, s75
	v_lshl_add_u32 v40, v40, 9, v152
	global_load_dwordx4 v[88:91], v40, s[98:99]
	v_add_u32_e32 v40, s40, v226
	v_med3_i32 v40, v40, 0, s75
	v_cmp_lt_i32_e32 vcc, -1, v48
	s_nop 1
	v_cndmask_b32_e32 v48, 0, v49, vcc
	v_lshl_add_u32 v44, v40, 9, v158
	v_lshl_add_u32 v52, v48, 9, v158
	global_load_dwordx4 v[40:43], v44, s[100:101]
	global_load_dwordx4 v[44:47], v44, s[100:101] offset:64
	global_load_dwordx4 v[48:51], v52, s[100:101]
	global_load_dwordx4 v[52:55], v52, s[100:101] offset:64
	ds_read_b64_tr_b16 v[102:103], v169 offset:2304
	ds_read_b64_tr_b16 v[100:101], v169
	ds_read_b64_tr_b16 v[108:109], v169 offset:32
	ds_read_b64_tr_b16 v[110:111], v169 offset:2336
	ds_read_b64_tr_b16 v[144:145], v169 offset:64
	ds_read_b64_tr_b16 v[146:147], v169 offset:2368
	ds_read_b64_tr_b16 v[140:141], v169 offset:96
	ds_read_b64_tr_b16 v[142:143], v169 offset:2400
	s_waitcnt vmcnt(15)
	ds_write_b128 v241, v[16:19] offset:4608
	s_waitcnt vmcnt(14)
	ds_write_b128 v242, v[60:63] offset:4608
	s_waitcnt vmcnt(13)
	ds_write_b128 v243, v[92:95] offset:4608
	s_waitcnt vmcnt(12)
	ds_write_b128 v244, v[96:99] offset:4608
	v_mfma_f32_16x16x32_bf16 v[16:19], v[84:87], v[4:7], 0
	v_mfma_f32_16x16x32_bf16 v[60:63], v[76:79], v[4:7], 0
	v_mfma_f32_16x16x32_bf16 v[16:19], v[80:83], v[8:11], v[16:19]
	v_mfma_f32_16x16x32_bf16 v[60:63], v[20:23], v[8:11], v[60:63]
	s_nop 5
	v_sub_u32_e32 v21, v198, v150
	v_add_u32_e32 v23, 1, v21
	v_cmp_gt_u32_e64 s[0:1], v23, v149
	v_cmp_gt_u32_e32 vcc, v21, v149
	s_nop 0
	v_cndmask_b32_e64 v17, v17, v246, s[0:1]
	s_nop 0
	v_cndmask_b32_e32 v16, v16, v246, vcc
	v_max_f32_e32 v22, v16, v17
	v_add_u32_e32 v23, 2, v21
	v_add_u32_e32 v76, 3, v21
	v_cmp_gt_u32_e64 s[22:23], v23, v149
	v_cmp_gt_u32_e64 s[24:25], v76, v149
	s_nop 0
	v_cndmask_b32_e64 v18, v18, v246, s[22:23]
	v_cndmask_b32_e64 v19, v19, v246, s[24:25]
	v_max3_f32 v22, v22, v18, v19
	v_add_u32_e32 v23, 16, v21
	v_add_u32_e32 v76, 17, v21
	v_cmp_gt_u32_e64 s[26:27], v23, v149
	v_cmp_gt_u32_e64 s[28:29], v76, v149
	s_nop 0
	v_cndmask_b32_e64 v60, v60, v246, s[26:27]
	v_cndmask_b32_e64 v61, v61, v246, s[28:29]
	v_max3_f32 v22, v22, v60, v61
	v_add_u32_e32 v23, 18, v21
	v_add_u32_e32 v21, 19, v21
	v_cmp_gt_u32_e64 s[30:31], v23, v149
	v_cmp_gt_u32_e64 s[34:35], v21, v149
	s_nop 0
	v_cndmask_b32_e64 v62, v62, v246, s[30:31]
	v_cndmask_b32_e64 v63, v63, v246, s[34:35]
	v_max3_f32 v21, v22, v62, v63
	v_mov_b32_e32 v23, v21
	s_nop 1
	v_permlane32_swap_b32_e32 v23, v21
	v_max_f32_e32 v21, v21, v23
	s_nop 1
	v_mov_b32_e32 v23, v21
	s_nop 1
	v_permlane16_swap_b32_e32 v23, v21
	v_max3_f32 v151, v175, v21, v23
	v_sub_f32_e32 v16, v16, v151
	v_exp_f32_e32 v16, v16
	v_sub_f32_e32 v17, v17, v151
	v_exp_f32_e32 v17, v17
	v_sub_f32_e32 v18, v18, v151
	v_exp_f32_e32 v18, v18
	v_sub_f32_e32 v19, v19, v151
	v_exp_f32_e32 v19, v19
	v_sub_f32_e32 v23, v60, v151
	v_sub_f32_e32 v21, v175, v151
	v_exp_f32_e32 v23, v23
	v_sub_f32_e32 v60, v61, v151
	v_exp_f32_e32 v76, v21
	v_exp_f32_e32 v60, v60
	v_sub_f32_e32 v61, v62, v151
	v_add_f32_e32 v21, v17, v16
	v_exp_f32_e32 v61, v61
	v_sub_f32_e32 v62, v63, v151
	v_add_f32_e32 v21, v18, v21
	v_exp_f32_e32 v62, v62
	v_add_f32_e32 v21, v19, v21
	v_add_f32_e32 v21, v23, v21
	v_add_f32_e32 v21, v60, v21
	v_add_f32_e32 v21, v61, v21
	v_mov_b32_e32 v175, v177
	v_add_f32_e32 v149, v62, v21
	v_cvt_pk_bf16_f32 v16, v16, v17
	v_cvt_pk_bf16_f32 v17, v18, v19
	v_cvt_pk_bf16_f32 v18, v23, v60
	v_mov_b32_e32 v60, 1.0
	v_cvt_pk_bf16_f32 v19, v61, v62
	v_mov_b32_e32 v21, 0
	v_mov_b32_e32 v23, 0
	v_pk_mul_f32 v[58:59], v[58:59], v[76:77] op_sel_hi:[1,0]
	v_pk_mul_f32 v[56:57], v[56:57], v[76:77] op_sel_hi:[1,0]
	v_add_f32_e32 v150, v23, v21
	v_cvt_pk_bf16_f32 v20, v21, 0
	v_cvt_pk_bf16_f32 v22, v23, 0
	v_mov_b32_e32 v21, v153
	v_mov_b32_e32 v23, v153
	s_waitcnt lgkmcnt(10)
	v_mfma_f32_16x16x32_bf16 v[96:99], v[100:103], v[16:19], v[56:59]
	v_fmac_f32_e32 v149, v176, v76
	v_fmac_f32_e32 v150, v178, v60
	s_min_i32 s0, s76, 0
	v_pk_mul_f32 v[58:59], v[114:115], v[60:61] op_sel_hi:[1,0]
	v_pk_mul_f32 v[56:57], v[112:113], v[60:61] op_sel_hi:[1,0]
	s_sub_i32 s0, 15, s0
	s_sub_i32 s1, s75, s76
	v_mfma_f32_16x16x32_bf16 v[100:103], v[100:103], v[20:23], v[56:59]
	s_ashr_i32 s0, s0, 4
	s_ashr_i32 s1, s1, 4
	s_cmpk_lt_i32 s71, 0x3000
	v_pk_mul_f32 v[58:59], v[118:119], v[76:77] op_sel_hi:[1,0]
	v_pk_mul_f32 v[56:57], v[116:117], v[76:77] op_sel_hi:[1,0]
	s_waitcnt lgkmcnt(8)
	s_nop 0
	v_mfma_f32_16x16x32_bf16 v[104:107], v[108:111], v[16:19], v[56:59]
	s_nop 2
	v_mul_f32_e64 v58, v122, v60
	v_mul_f32_e64 v59, v123, v60
	v_pk_mul_f32 v[56:57], v[120:121], v[60:61] op_sel_hi:[1,0]
	s_nop 1
	v_mfma_f32_16x16x32_bf16 v[108:111], v[108:111], v[20:23], v[56:59]
	s_nop 2
	v_mul_f32_e64 v58, v126, v76
	v_mul_f32_e64 v59, v127, v76
	v_pk_mul_f32 v[56:57], v[124:125], v[76:77] op_sel_hi:[1,0]
	s_waitcnt lgkmcnt(6)
	s_nop 0
	v_mfma_f32_16x16x32_bf16 v[112:115], v[144:147], v[16:19], v[56:59]
	s_nop 2
	v_mul_f32_e64 v58, v130, v60
	v_mul_f32_e64 v59, v131, v60
	v_pk_mul_f32 v[56:57], v[128:129], v[60:61] op_sel_hi:[1,0]
	s_nop 1
	v_mfma_f32_16x16x32_bf16 v[116:119], v[144:147], v[20:23], v[56:59]
	v_max_i32_e32 v145, s0, v148
	s_nop 1
	v_pk_mul_f32 v[58:59], v[134:135], v[76:77] op_sel_hi:[1,0]
	v_pk_mul_f32 v[56:57], v[132:133], v[76:77] op_sel_hi:[1,0]
	s_waitcnt lgkmcnt(4)
	s_nop 0
	v_mfma_f32_16x16x32_bf16 v[120:123], v[140:143], v[16:19], v[56:59]
	v_mul_f32_e64 v18, v138, v60
	v_mul_f32_e64 v19, v139, v60
	v_pk_mul_f32 v[16:17], v[136:137], v[60:61] op_sel_hi:[1,0]
	v_add_u32_e32 v56, s40, v228
	s_nop 0
	v_mfma_f32_16x16x32_bf16 v[124:127], v[140:143], v[20:23], v[16:19]
	s_nop 1
	s_nop 0
	v_add_u32_e32 v16, s40, v213
	v_med3_i32 v16, v16, 0, s75
	v_lshl_add_u32 v16, v16, 9, v152
	global_load_dwordx4 v[76:79], v16, s[98:99]
	v_add_u32_e32 v16, s40, v215
	v_med3_i32 v16, v16, 0, s75
	v_lshl_add_u32 v16, v16, 9, v152
	global_load_dwordx4 v[80:83], v16, s[98:99]
	v_add_u32_e32 v16, s40, v217
	v_med3_i32 v16, v16, 0, s75
	v_lshl_add_u32 v16, v16, 9, v152
	global_load_dwordx4 v[84:87], v16, s[98:99]
	v_add_u32_e32 v16, s40, v219
	v_med3_i32 v16, v16, 0, s75
	v_lshl_add_u32 v16, v16, 9, v152
	global_load_dwordx4 v[92:95], v16, s[98:99]
	v_or_b32_e32 v16, s40, v167
	v_min_i32_e32 v16, s75, v16
	v_cndmask_b32_e64 v16, v16, 0, s[38:39]
	v_med3_i32 v56, v56, 0, s75
	v_lshl_add_u32 v20, v16, 9, v158
	v_lshl_add_u32 v60, v56, 9, v158
	global_load_dwordx4 v[16:19], v20, s[100:101]
	global_load_dwordx4 v[20:23], v20, s[100:101] offset:64
	global_load_dwordx4 v[56:59], v60, s[100:101]
	global_load_dwordx4 v[60:63], v60, s[100:101] offset:64
	ds_read_b64_tr_b16 v[132:133], v169 offset:6912
	ds_read_b64_tr_b16 v[130:131], v169 offset:4608
	ds_read_b64_tr_b16 v[134:135], v169 offset:4640
	ds_read_b64_tr_b16 v[136:137], v169 offset:6944
	ds_read_b64_tr_b16 v[138:139], v169 offset:4672
	ds_read_b64_tr_b16 v[140:141], v169 offset:6976
	ds_read_b64_tr_b16 v[176:177], v169 offset:4704
	ds_read_b64_tr_b16 v[178:179], v169 offset:7008
	s_waitcnt vmcnt(15)
	ds_write_b128 v241, v[64:67]
	s_waitcnt vmcnt(14)
	ds_write_b128 v242, v[68:71]
	s_waitcnt vmcnt(13)
	ds_write_b128 v243, v[72:75]
	s_waitcnt vmcnt(12)
	ds_write_b128 v244, v[88:91]
	v_mfma_f32_16x16x32_bf16 v[24:27], v[24:27], v[12:15], 0
	v_mfma_f32_16x16x32_bf16 v[24:27], v[28:31], v[0:3], v[24:27]
	v_mfma_f32_16x16x32_bf16 v[28:31], v[32:35], v[12:15], 0
	v_add_u32_e32 v32, 0x7f8, v249
	v_ashrrev_i32_e32 v32, 4, v32
	v_min3_i32 v32, v32, s1, v248
	v_sub_u32_e32 v144, v32, v145
	v_sub_u32_e32 v33, v154, v145
	s_nop 2
	v_add_u32_e32 v35, 1, v33
	v_cmp_gt_u32_e64 s[0:1], v35, v144
	v_cmp_gt_u32_e32 vcc, v33, v144
	s_nop 0
	v_cndmask_b32_e64 v25, v25, v246, s[0:1]
	s_nop 0
	v_cndmask_b32_e32 v24, v24, v246, vcc
	v_mfma_f32_16x16x32_bf16 v[28:31], v[36:39], v[0:3], v[28:31]
	v_max_f32_e32 v34, v24, v25
	v_add_u32_e32 v35, 2, v33
	v_add_u32_e32 v36, 3, v33
	v_cmp_gt_u32_e64 s[22:23], v35, v144
	v_cmp_gt_u32_e64 s[24:25], v36, v144
	s_nop 0
	v_cndmask_b32_e64 v26, v26, v246, s[22:23]
	v_cndmask_b32_e64 v27, v27, v246, s[24:25]
	v_max3_f32 v34, v34, v26, v27
	v_add_u32_e32 v35, 16, v33
	v_add_u32_e32 v36, 17, v33
	v_cmp_gt_u32_e64 s[26:27], v35, v144
	v_cmp_gt_u32_e64 s[28:29], v36, v144
	s_nop 0
	v_cndmask_b32_e64 v28, v28, v246, s[26:27]
	v_cndmask_b32_e64 v29, v29, v246, s[28:29]
	v_max3_f32 v34, v34, v28, v29
	v_add_u32_e32 v35, 18, v33
	v_add_u32_e32 v33, 19, v33
	v_cmp_gt_u32_e64 s[30:31], v35, v144
	v_cmp_gt_u32_e64 s[34:35], v33, v144
	s_nop 0
	v_cndmask_b32_e64 v30, v30, v246, s[30:31]
	v_cndmask_b32_e64 v31, v31, v246, s[34:35]
	v_max3_f32 v33, v34, v30, v31
	s_nop 1
	v_mov_b32_e32 v34, v33
	s_nop 1
	v_permlane32_swap_b32_e32 v34, v33
	v_max_f32_e32 v33, v33, v34
	s_nop 1
	v_mov_b32_e32 v34, v33
	s_nop 1
	v_permlane16_swap_b32_e32 v34, v33
	v_max3_f32 v128, v175, v33, v34
	v_sub_f32_e32 v24, v24, v128
	v_exp_f32_e32 v24, v24
	v_sub_f32_e32 v37, v175, v128
	v_exp_f32_e32 v38, v37
	v_mov_b32_e32 v129, v151
	v_cndmask_b32_e64 v37, v24, 0, vcc
	v_sub_f32_e32 v24, v25, v128
	v_exp_f32_e32 v24, v24
	v_mov_b32_e32 v36, 1.0
	v_cndmask_b32_e64 v65, v24, 0, s[0:1]
	v_sub_f32_e32 v24, v26, v128
	v_exp_f32_e32 v24, v24
	v_mov_b32_e32 v33, v153
	v_mov_b32_e32 v35, v153
	v_mov_b32_e32 v39, 0
	v_cndmask_b32_e64 v66, v24, 0, s[22:23]
	v_sub_f32_e32 v24, v27, v128
	v_exp_f32_e32 v24, v24
	s_nop 0
	v_cndmask_b32_e64 v67, v24, 0, s[24:25]
	v_sub_f32_e32 v24, v28, v128
	v_exp_f32_e32 v24, v24
	v_mov_b32_e32 v64, 0
	v_cvt_pk_bf16_f32 v32, v39, 0
	v_cvt_pk_bf16_f32 v34, v64, 0
	v_cndmask_b32_e64 v68, v24, 0, s[26:27]
	v_sub_f32_e32 v24, v29, v128
	v_exp_f32_e32 v24, v24
	v_pk_mul_f32 v[28:29], v[96:97], v[36:37] op_sel_hi:[1,0]
	v_cvt_pk_bf16_f32 v25, v66, v67
	v_cndmask_b32_e64 v69, v24, 0, s[28:29]
	v_sub_f32_e32 v24, v30, v128
	v_exp_f32_e32 v24, v24
	v_cvt_pk_bf16_f32 v26, v68, v69
	v_cndmask_b32_e64 v70, v24, 0, s[30:31]
	v_sub_f32_e32 v24, v31, v128
	v_exp_f32_e32 v24, v24
	v_pk_mul_f32 v[30:31], v[98:99], v[36:37] op_sel_hi:[1,0]
	v_cndmask_b32_e64 v71, v24, 0, s[34:35]
	v_cvt_pk_bf16_f32 v24, v37, v65
	v_cvt_pk_bf16_f32 v27, v70, v71
	s_waitcnt lgkmcnt(10)
	v_mfma_f32_16x16x32_bf16 v[96:99], v[130:133], v[32:35], v[28:31]
	s_nop 2
	v_mul_f32_e64 v30, v102, v38
	v_mul_f32_e64 v31, v103, v38
	v_pk_mul_f32 v[28:29], v[100:101], v[38:39] op_sel_hi:[1,0]
	s_nop 1
	v_mfma_f32_16x16x32_bf16 v[100:103], v[130:133], v[24:27], v[28:31]
	s_nop 2
	v_mul_f32_e64 v30, v106, v36
	v_mul_f32_e64 v31, v107, v36
	v_pk_mul_f32 v[28:29], v[104:105], v[36:37] op_sel_hi:[1,0]
	s_waitcnt lgkmcnt(8)
	s_nop 0
	v_mfma_f32_16x16x32_bf16 v[104:107], v[134:137], v[32:35], v[28:31]
	s_nop 2
	v_mul_f32_e64 v30, v110, v38
	v_mul_f32_e64 v31, v111, v38
	v_pk_mul_f32 v[28:29], v[108:109], v[38:39] op_sel_hi:[1,0]
	s_nop 1
	v_mfma_f32_16x16x32_bf16 v[108:111], v[134:137], v[24:27], v[28:31]
	s_nop 2
	v_mul_f32_e64 v30, v114, v36
	v_mul_f32_e64 v31, v115, v36
	v_pk_mul_f32 v[28:29], v[112:113], v[36:37] op_sel_hi:[1,0]
	s_waitcnt lgkmcnt(6)
	s_nop 0
	v_mfma_f32_16x16x32_bf16 v[112:115], v[138:141], v[32:35], v[28:31]
	s_nop 2
	v_mul_f32_e64 v30, v118, v38
	v_mul_f32_e64 v31, v119, v38
	v_pk_mul_f32 v[28:29], v[116:117], v[38:39] op_sel_hi:[1,0]
	s_nop 1
	v_mfma_f32_16x16x32_bf16 v[116:119], v[138:141], v[24:27], v[28:31]
	s_nop 2
	v_mul_f32_e64 v30, v122, v36
	v_mul_f32_e64 v31, v123, v36
	v_pk_mul_f32 v[28:29], v[120:121], v[36:37] op_sel_hi:[1,0]
	s_waitcnt lgkmcnt(4)
	s_nop 0
	v_mfma_f32_16x16x32_bf16 v[120:123], v[176:179], v[32:35], v[28:31]
	v_add_u32_e32 v32, s40, v234
	s_nop 0
	s_nop 0
	v_pk_mul_f32 v[30:31], v[126:127], v[38:39] op_sel_hi:[1,0]
	v_pk_mul_f32 v[28:29], v[124:125], v[38:39] op_sel_hi:[1,0]
	s_nop 1
	v_mfma_f32_16x16x32_bf16 v[124:127], v[176:179], v[24:27], v[28:31]
	v_add_f32_e32 v24, v65, v37
	v_add_f32_e32 v24, v66, v24
	v_add_f32_e32 v24, v67, v24
	v_add_f32_e32 v24, v68, v24
	v_add_f32_e32 v24, v69, v24
	v_add_f32_e32 v24, v70, v24
	v_add_f32_e32 v130, v71, v24
	v_add_f32_e32 v131, v64, v39
	v_add_u32_e32 v24, s40, v229
	v_fmac_f32_e32 v131, v149, v36
	v_fmac_f32_e32 v130, v150, v38
	v_med3_i32 v24, v24, 0, s75
	v_lshl_add_u32 v24, v24, 9, v152
	global_load_dwordx4 v[64:67], v24, s[98:99]
	v_add_u32_e32 v24, s40, v230
	v_med3_i32 v24, v24, 0, s75
	v_lshl_add_u32 v24, v24, 9, v152
	global_load_dwordx4 v[68:71], v24, s[98:99]
	v_add_u32_e32 v24, s40, v231
	v_med3_i32 v24, v24, 0, s75
	v_lshl_add_u32 v24, v24, 9, v152
	global_load_dwordx4 v[72:75], v24, s[98:99]
	v_add_u32_e32 v24, s40, v232
	v_med3_i32 v24, v24, 0, s75
	v_lshl_add_u32 v24, v24, 9, v152
	global_load_dwordx4 v[88:91], v24, s[98:99]
	v_add_u32_e32 v24, s40, v233
	v_med3_i32 v24, v24, 0, s75
	v_med3_i32 v32, v32, 0, s75
	v_lshl_add_u32 v28, v24, 9, v158
	v_lshl_add_u32 v36, v32, 9, v158
	global_load_dwordx4 v[24:27], v28, s[100:101]
	global_load_dwordx4 v[28:31], v28, s[100:101] offset:64
	global_load_dwordx4 v[32:35], v36, s[100:101]
	global_load_dwordx4 v[36:39], v36, s[100:101] offset:64
	ds_read_b64_tr_b16 v[134:135], v169 offset:2304
	ds_read_b64_tr_b16 v[132:133], v169
	ds_read_b64_tr_b16 v[136:137], v169 offset:32
	ds_read_b64_tr_b16 v[138:139], v169 offset:2336
	ds_read_b64_tr_b16 v[140:141], v169 offset:64
	ds_read_b64_tr_b16 v[142:143], v169 offset:2368
	ds_read_b64_tr_b16 v[176:177], v169 offset:96
	ds_read_b64_tr_b16 v[178:179], v169 offset:2400
	s_waitcnt vmcnt(15)
	ds_write_b128 v241, v[76:79] offset:4608
	s_waitcnt vmcnt(14)
	ds_write_b128 v242, v[80:83] offset:4608
	s_waitcnt vmcnt(13)
	ds_write_b128 v243, v[84:87] offset:4608
	s_waitcnt vmcnt(12)
	ds_write_b128 v244, v[92:95] offset:4608
	v_mfma_f32_16x16x32_bf16 v[40:43], v[40:43], v[12:15], 0
	s_nop 5
	v_mov_b32_e32 v77, v153
	v_mfma_f32_16x16x32_bf16 v[40:43], v[44:47], v[0:3], v[40:43]
	v_mfma_f32_16x16x32_bf16 v[44:47], v[48:51], v[12:15], 0
	v_sub_u32_e32 v48, v187, v145
	s_nop 1
	v_add_u32_e32 v51, 1, v48
	v_cmp_gt_u32_e64 s[0:1], v51, v144
	v_cmp_gt_u32_e32 vcc, v48, v144
	s_nop 0
	v_cndmask_b32_e64 v41, v41, v246, s[0:1]
	s_nop 0
	v_cndmask_b32_e32 v40, v40, v246, vcc
	v_mfma_f32_16x16x32_bf16 v[44:47], v[52:55], v[0:3], v[44:47]
	v_max_f32_e32 v50, v40, v41
	v_add_u32_e32 v51, 2, v48
	v_add_u32_e32 v52, 3, v48
	v_cmp_gt_u32_e64 s[22:23], v51, v144
	v_cmp_gt_u32_e64 s[24:25], v52, v144
	v_mov_b32_e32 v79, v153
	v_cndmask_b32_e64 v42, v42, v246, s[22:23]
	v_cndmask_b32_e64 v43, v43, v246, s[24:25]
	v_max3_f32 v50, v50, v42, v43
	v_add_u32_e32 v51, 16, v48
	v_add_u32_e32 v52, 17, v48
	v_cmp_gt_u32_e64 s[26:27], v51, v144
	v_cmp_gt_u32_e64 s[28:29], v52, v144
	s_nop 0
	v_cndmask_b32_e64 v44, v44, v246, s[26:27]
	v_cndmask_b32_e64 v45, v45, v246, s[28:29]
	v_max3_f32 v50, v50, v44, v45
	v_add_u32_e32 v51, 18, v48
	v_add_u32_e32 v48, 19, v48
	v_cmp_gt_u32_e64 s[30:31], v51, v144
	v_cmp_gt_u32_e64 s[34:35], v48, v144
	s_nop 0
	v_cndmask_b32_e64 v46, v46, v246, s[30:31]
	v_cndmask_b32_e64 v47, v47, v246, s[34:35]
	v_max3_f32 v48, v50, v46, v47
	s_nop 1
	v_mov_b32_e32 v50, v48
	s_nop 1
	v_permlane32_swap_b32_e32 v50, v48
	v_max_f32_e32 v48, v48, v50
	s_nop 1
	v_mov_b32_e32 v50, v48
	s_nop 1
	v_permlane16_swap_b32_e32 v50, v48
	v_max3_f32 v148, v128, v48, v50
	v_sub_f32_e32 v40, v40, v148
	v_exp_f32_e32 v40, v40
	v_sub_f32_e32 v41, v41, v148
	v_exp_f32_e32 v41, v41
	v_sub_f32_e32 v42, v42, v148
	v_exp_f32_e32 v42, v42
	v_sub_f32_e32 v43, v43, v148
	v_exp_f32_e32 v43, v43
	v_sub_f32_e32 v44, v44, v148
	v_mov_b32_e32 v146, v129
	v_sub_f32_e32 v48, v128, v148
	v_exp_f32_e32 v44, v44
	v_sub_f32_e32 v45, v45, v148
	v_exp_f32_e32 v86, v48
	v_exp_f32_e32 v45, v45
	v_sub_f32_e32 v46, v46, v148
	v_sub_f32_e32 v47, v47, v148
	v_mov_b32_e32 v84, 1.0
	v_add_f32_e32 v48, v41, v40
	v_exp_f32_e32 v46, v46
	v_exp_f32_e32 v47, v47
	v_add_f32_e32 v48, v42, v48
	v_add_f32_e32 v48, v43, v48
	v_add_f32_e32 v48, v44, v48
	v_add_f32_e32 v48, v45, v48
	v_mov_b32_e32 v49, 0
	v_mov_b32_e32 v51, 0
	v_add_f32_e32 v48, v46, v48
	v_cvt_pk_bf16_f32 v40, v40, v41
	v_cvt_pk_bf16_f32 v41, v42, v43
	v_cvt_pk_bf16_f32 v42, v44, v45
	v_cvt_pk_bf16_f32 v43, v46, v47
	v_pk_mul_f32 v[82:83], v[110:111], v[86:87] op_sel_hi:[1,0]
	v_pk_mul_f32 v[80:81], v[108:109], v[86:87] op_sel_hi:[1,0]
	v_cvt_pk_bf16_f32 v76, v49, 0
	v_cvt_pk_bf16_f32 v78, v51, 0
	v_add_f32_e32 v149, v47, v48
	v_pk_mul_f32 v[46:47], v[98:99], v[84:85] op_sel_hi:[1,0]
	v_pk_mul_f32 v[44:45], v[96:97], v[84:85] op_sel_hi:[1,0]
	s_waitcnt lgkmcnt(8)
	v_mfma_f32_16x16x32_bf16 v[96:99], v[136:139], v[40:43], v[80:83]
	v_add_f32_e32 v147, v51, v49
	v_pk_mul_f32 v[50:51], v[102:103], v[86:87] op_sel_hi:[1,0]
	v_pk_mul_f32 v[48:49], v[100:101], v[86:87] op_sel_hi:[1,0]
	v_pk_mul_f32 v[82:83], v[114:115], v[84:85] op_sel_hi:[1,0]
	v_pk_mul_f32 v[80:81], v[112:113], v[84:85] op_sel_hi:[1,0]
	v_pk_mul_f32 v[54:55], v[106:107], v[84:85] op_sel_hi:[1,0]
	v_pk_mul_f32 v[52:53], v[104:105], v[84:85] op_sel_hi:[1,0]
	s_waitcnt lgkmcnt(6)
	v_mfma_f32_16x16x32_bf16 v[100:103], v[140:143], v[76:79], v[80:83]
	v_fmac_f32_e32 v147, v131, v84
	v_fmac_f32_e32 v149, v130, v86
	s_nop 0
	v_pk_mul_f32 v[82:83], v[118:119], v[86:87] op_sel_hi:[1,0]
	v_pk_mul_f32 v[80:81], v[116:117], v[86:87] op_sel_hi:[1,0]
	v_mfma_f32_16x16x32_bf16 v[44:47], v[132:135], v[76:79], v[44:47]
	s_nop 0
	v_mfma_f32_16x16x32_bf16 v[104:107], v[140:143], v[40:43], v[80:83]
	s_nop 2
	v_mul_f32_e64 v82, v122, v84
	v_mul_f32_e64 v83, v123, v84
	v_pk_mul_f32 v[80:81], v[120:121], v[84:85] op_sel_hi:[1,0]
	v_mfma_f32_16x16x32_bf16 v[52:55], v[136:139], v[76:79], v[52:55]
	v_add_u32_e32 v84, s40, v240
	s_waitcnt lgkmcnt(4)
	v_mfma_f32_16x16x32_bf16 v[108:111], v[176:179], v[76:79], v[80:83]
	v_mul_f32_e64 v78, v126, v86
	v_mul_f32_e64 v79, v127, v86
	v_pk_mul_f32 v[76:77], v[124:125], v[86:87] op_sel_hi:[1,0]
	v_mfma_f32_16x16x32_bf16 v[48:51], v[132:135], v[40:43], v[48:51]
	s_nop 0
	v_mfma_f32_16x16x32_bf16 v[112:115], v[176:179], v[40:43], v[76:79]
	v_add_u32_e32 v40, s40, v235
	s_nop 1
	v_add_u32_e32 v76, s40, v236
	v_med3_i32 v40, v40, 0, s75
	v_med3_i32 v76, v76, 0, s75
	v_lshl_add_u32 v40, v40, 9, v152
	v_lshl_add_u32 v76, v76, 9, v152
	global_load_dwordx4 v[40:43], v40, s[98:99]
	global_load_dwordx4 v[116:119], v76, s[98:99]
	v_add_u32_e32 v76, s40, v237
	v_med3_i32 v76, v76, 0, s75
	v_lshl_add_u32 v76, v76, 9, v152
	global_load_dwordx4 v[120:123], v76, s[98:99]
	v_add_u32_e32 v76, s40, v238
	v_med3_i32 v76, v76, 0, s75
	v_lshl_add_u32 v76, v76, 9, v152
	global_load_dwordx4 v[124:127], v76, s[98:99]
	v_add_u32_e32 v76, s40, v239
	v_med3_i32 v76, v76, 0, s75
	v_med3_i32 v84, v84, 0, s75
	v_lshl_add_u32 v80, v76, 9, v158
	v_lshl_add_u32 v84, v84, 9, v158
	global_load_dwordx4 v[76:79], v80, s[100:101]
	global_load_dwordx4 v[80:83], v80, s[100:101] offset:64
	global_load_dwordx4 v[92:95], v84, s[100:101]
	global_load_dwordx4 v[84:87], v84, s[100:101] offset:64
	ds_read_b64_tr_b16 v[142:143], v169 offset:6912
	ds_read_b64_tr_b16 v[140:141], v169 offset:4608
	ds_read_b64_tr_b16 v[136:137], v169 offset:4640
	ds_read_b64_tr_b16 v[138:139], v169 offset:6944
	ds_read_b64_tr_b16 v[132:133], v169 offset:4672
	ds_read_b64_tr_b16 v[134:135], v169 offset:6976
	ds_read_b64_tr_b16 v[128:129], v169 offset:4704
	ds_read_b64_tr_b16 v[130:131], v169 offset:7008
	s_waitcnt vmcnt(15)
	ds_write_b128 v241, v[64:67]
	s_waitcnt vmcnt(14)
	ds_write_b128 v242, v[68:71]
	s_waitcnt vmcnt(13)
	ds_write_b128 v243, v[72:75]
	s_waitcnt vmcnt(12)
	ds_write_b128 v244, v[88:91]
	v_mfma_f32_16x16x32_bf16 v[16:19], v[16:19], v[12:15], 0
	v_mfma_f32_16x16x32_bf16 v[16:19], v[20:23], v[0:3], v[16:19]
	v_mfma_f32_16x16x32_bf16 v[20:23], v[56:59], v[12:15], 0
	s_nop 2
	v_sub_u32_e32 v56, v192, v145
	v_add_u32_e32 v59, 1, v56
	v_cmp_gt_u32_e64 s[0:1], v59, v144
	v_cmp_gt_u32_e32 vcc, v56, v144
	s_nop 0
	v_cndmask_b32_e64 v17, v17, v246, s[0:1]
	s_nop 0
	v_cndmask_b32_e32 v16, v16, v246, vcc
	v_mfma_f32_16x16x32_bf16 v[20:23], v[60:63], v[0:3], v[20:23]
	v_max_f32_e32 v58, v16, v17
	v_add_u32_e32 v59, 2, v56
	v_add_u32_e32 v60, 3, v56
	v_cmp_gt_u32_e64 s[22:23], v59, v144
	v_cmp_gt_u32_e64 s[24:25], v60, v144
	v_mov_b32_e32 v61, v153
	v_cndmask_b32_e64 v18, v18, v246, s[22:23]
	v_cndmask_b32_e64 v19, v19, v246, s[24:25]
	v_max3_f32 v58, v58, v18, v19
	v_add_u32_e32 v59, 16, v56
	v_add_u32_e32 v60, 17, v56
	v_cmp_gt_u32_e64 s[26:27], v59, v144
	v_cmp_gt_u32_e64 s[28:29], v60, v144
	v_mov_b32_e32 v63, v153
	v_cndmask_b32_e64 v20, v20, v246, s[26:27]
	v_cndmask_b32_e64 v60, v21, v246, s[28:29]
	v_max3_f32 v58, v58, v20, v60
	v_add_u32_e32 v59, 18, v56
	v_add_u32_e32 v56, 19, v56
	v_cmp_gt_u32_e64 s[30:31], v59, v144
	v_cmp_gt_u32_e64 s[34:35], v56, v144
	s_nop 0
	v_cndmask_b32_e64 v22, v22, v246, s[30:31]
	v_cndmask_b32_e64 v23, v23, v246, s[34:35]
	v_max3_f32 v56, v58, v22, v23
	s_nop 1
	v_mov_b32_e32 v58, v56
	s_nop 1
	v_permlane32_swap_b32_e32 v58, v56
	v_max_f32_e32 v56, v56, v58
	s_nop 1
	v_mov_b32_e32 v58, v56
	s_nop 1
	v_permlane16_swap_b32_e32 v58, v56
	v_max3_f32 v151, v148, v56, v58
	v_sub_f32_e32 v16, v16, v151
	v_exp_f32_e32 v16, v16
	v_sub_f32_e32 v17, v17, v151
	v_mov_b32_e32 v150, v146
	v_exp_f32_e32 v17, v17
	v_sub_f32_e32 v18, v18, v151
	v_exp_f32_e32 v18, v18
	v_sub_f32_e32 v19, v19, v151
	v_mov_b32_e32 v68, 1.0
	v_exp_f32_e32 v19, v19
	v_sub_f32_e32 v20, v20, v151
	v_sub_f32_e32 v56, v148, v151
	v_exp_f32_e32 v20, v20
	v_sub_f32_e32 v21, v21, v151
	v_exp_f32_e32 v72, v56
	v_exp_f32_e32 v21, v21
	v_sub_f32_e32 v22, v22, v151
	v_add_f32_e32 v56, v17, v16
	v_exp_f32_e32 v22, v22
	v_sub_f32_e32 v23, v23, v151
	v_add_f32_e32 v56, v18, v56
	v_exp_f32_e32 v23, v23
	v_mov_b32_e32 v57, 0
	v_add_f32_e32 v56, v19, v56
	v_mov_b32_e32 v59, 0
	v_add_f32_e32 v56, v20, v56
	v_cndmask_b32_e64 v21, v21, 0, s[28:29]
	v_add_f32_e32 v146, v59, v57
	v_add_f32_e32 v56, v21, v56
	v_fmac_f32_e32 v146, v147, v68
	v_cvt_pk_bf16_f32 v60, v57, 0
	v_cvt_pk_bf16_f32 v62, v59, 0
	v_add_f32_e32 v56, v22, v56
	v_cvt_pk_bf16_f32 v64, v16, v17
	v_cvt_pk_bf16_f32 v65, v18, v19
	v_pk_mul_f32 v[18:19], v[46:47], v[68:69] op_sel_hi:[1,0]
	v_pk_mul_f32 v[16:17], v[44:45], v[68:69] op_sel_hi:[1,0]
	v_pk_mul_f32 v[46:47], v[54:55], v[68:69] op_sel_hi:[1,0]
	v_pk_mul_f32 v[44:45], v[52:53], v[68:69] op_sel_hi:[1,0]
	v_pk_mul_f32 v[54:55], v[102:103], v[68:69] op_sel_hi:[1,0]
	v_pk_mul_f32 v[52:53], v[100:101], v[68:69] op_sel_hi:[1,0]
	v_pk_mul_f32 v[70:71], v[110:111], v[68:69] op_sel_hi:[1,0]
	v_pk_mul_f32 v[68:69], v[108:109], v[68:69] op_sel_hi:[1,0]
	v_add_f32_e32 v147, v23, v56
	v_cvt_pk_bf16_f32 v66, v20, v21
	v_cvt_pk_bf16_f32 v67, v22, v23
	s_waitcnt lgkmcnt(10)
	v_mfma_f32_16x16x32_bf16 v[16:19], v[140:143], v[60:63], v[16:19]
	v_mul_f32_e64 v22, v50, v72
	v_mul_f32_e64 v23, v51, v72
	v_pk_mul_f32 v[20:21], v[48:49], v[72:73] op_sel_hi:[1,0]
	v_pk_mul_f32 v[50:51], v[98:99], v[72:73] op_sel_hi:[1,0]
	s_waitcnt lgkmcnt(8)
	v_mfma_f32_16x16x32_bf16 v[44:47], v[136:139], v[60:63], v[44:47]
	v_mul_f32_e64 v48, v96, v72
	v_mul_f32_e64 v49, v97, v72
	v_pk_mul_f32 v[58:59], v[106:107], v[72:73] op_sel_hi:[1,0]
	v_pk_mul_f32 v[56:57], v[104:105], v[72:73] op_sel_hi:[1,0]
	s_waitcnt lgkmcnt(6)
	v_mfma_f32_16x16x32_bf16 v[52:55], v[132:135], v[60:63], v[52:55]
	v_fmac_f32_e32 v147, v149, v72
	s_waitcnt lgkmcnt(4)
	v_mfma_f32_16x16x32_bf16 v[60:63], v[128:131], v[60:63], v[68:71]
	s_nop 2
	v_mul_f32_e64 v70, v114, v72
	v_mul_f32_e64 v71, v115, v72
	v_pk_mul_f32 v[68:69], v[112:113], v[72:73] op_sel_hi:[1,0]
	v_mfma_f32_16x16x32_bf16 v[20:23], v[140:143], v[64:67], v[20:23]
	v_mfma_f32_16x16x32_bf16 v[48:51], v[136:139], v[64:67], v[48:51]
	v_mfma_f32_16x16x32_bf16 v[56:59], v[132:135], v[64:67], v[56:59]
	v_mfma_f32_16x16x32_bf16 v[64:67], v[128:131], v[64:67], v[68:71]
	ds_read_b64_tr_b16 v[98:99], v169 offset:2304
	ds_read_b64_tr_b16 v[96:97], v169
	ds_read_b64_tr_b16 v[88:89], v169 offset:32
	ds_read_b64_tr_b16 v[90:91], v169 offset:2336
	ds_read_b64_tr_b16 v[72:73], v169 offset:64
	ds_read_b64_tr_b16 v[74:75], v169 offset:2368
	ds_read_b64_tr_b16 v[68:69], v169 offset:96
	ds_read_b64_tr_b16 v[70:71], v169 offset:2400
	s_waitcnt vmcnt(7)
	ds_write_b128 v241, v[40:43] offset:4608
	s_waitcnt vmcnt(6)
	ds_write_b128 v242, v[116:119] offset:4608
	s_waitcnt vmcnt(5)
	ds_write_b128 v243, v[120:123] offset:4608
	s_waitcnt vmcnt(4)
	ds_write_b128 v244, v[124:127] offset:4608
	v_mfma_f32_16x16x32_bf16 v[24:27], v[24:27], v[12:15], 0
	v_mfma_f32_16x16x32_bf16 v[24:27], v[28:31], v[0:3], v[24:27]
	s_nop 5
	v_mov_b32_e32 v41, v153
	v_mov_b32_e32 v43, v153
	v_mfma_f32_16x16x32_bf16 v[28:31], v[32:35], v[12:15], 0
	v_sub_u32_e32 v32, v197, v145
	v_add_u32_e32 v35, 1, v32
	v_cmp_gt_u32_e64 s[0:1], v35, v144
	v_cmp_gt_u32_e32 vcc, v32, v144
	s_nop 0
	v_cndmask_b32_e64 v25, v25, v246, s[0:1]
	s_nop 0
	v_cndmask_b32_e32 v24, v24, v246, vcc
	v_mfma_f32_16x16x32_bf16 v[28:31], v[36:39], v[0:3], v[28:31]
	v_max_f32_e32 v34, v24, v25
	v_add_u32_e32 v35, 2, v32
	v_add_u32_e32 v36, 3, v32
	v_cmp_gt_u32_e64 s[22:23], v35, v144
	v_cmp_gt_u32_e64 s[24:25], v36, v144
	s_nop 0
	v_cndmask_b32_e64 v26, v26, v246, s[22:23]
	v_cndmask_b32_e64 v27, v27, v246, s[24:25]
	v_max3_f32 v34, v34, v26, v27
	v_add_u32_e32 v35, 16, v32
	v_add_u32_e32 v36, 17, v32
	v_cmp_gt_u32_e64 s[26:27], v35, v144
	v_cmp_gt_u32_e64 s[28:29], v36, v144
	s_nop 0
	v_cndmask_b32_e64 v28, v28, v246, s[26:27]
	v_cndmask_b32_e64 v29, v29, v246, s[28:29]
	v_max3_f32 v34, v34, v28, v29
	v_add_u32_e32 v35, 18, v32
	v_add_u32_e32 v32, 19, v32
	v_cmp_gt_u32_e64 s[30:31], v35, v144
	v_cmp_gt_u32_e64 s[34:35], v32, v144
	s_nop 0
	v_cndmask_b32_e64 v30, v30, v246, s[30:31]
	v_cndmask_b32_e64 v31, v31, v246, s[34:35]
	v_max3_f32 v32, v34, v30, v31
	s_nop 1
	v_mov_b32_e32 v34, v32
	s_nop 1
	v_permlane32_swap_b32_e32 v34, v32
	v_max_f32_e32 v32, v32, v34
	s_nop 1
	v_mov_b32_e32 v101, v150
	v_mov_b32_e32 v106, 1.0
	v_mov_b32_e32 v34, v32
	s_nop 0
	s_nop 0
	v_permlane16_swap_b32_e32 v34, v32
	v_mov_b32_e32 v107, 0
	v_max3_f32 v100, v151, v32, v34
	v_sub_f32_e32 v24, v24, v100
	v_exp_f32_e32 v24, v24
	v_sub_f32_e32 v32, v151, v100
	v_exp_f32_e32 v108, v32
	v_cndmask_b32_e64 v110, v24, 0, vcc
	v_sub_f32_e32 v24, v25, v100
	v_exp_f32_e32 v24, v24
	v_mov_b32_e32 v109, 0
	v_cvt_pk_bf16_f32 v40, v107, 0
	v_cvt_pk_bf16_f32 v42, v109, 0
	v_cndmask_b32_e64 v111, v24, 0, s[0:1]
	v_sub_f32_e32 v24, v26, v100
	v_exp_f32_e32 v24, v24
	v_pk_mul_f32 v[18:19], v[18:19], v[106:107] op_sel_hi:[1,0]
	v_pk_mul_f32 v[16:17], v[16:17], v[106:107] op_sel_hi:[1,0]
	v_pk_mul_f32 v[34:35], v[54:55], v[106:107] op_sel_hi:[1,0]
	v_cndmask_b32_e64 v112, v24, 0, s[22:23]
	v_sub_f32_e32 v24, v27, v100
	v_exp_f32_e32 v24, v24
	v_pk_mul_f32 v[26:27], v[46:47], v[106:107] op_sel_hi:[1,0]
	v_pk_mul_f32 v[32:33], v[52:53], v[106:107] op_sel_hi:[1,0]
	v_pk_mul_f32 v[46:47], v[62:63], v[106:107] op_sel_hi:[1,0]
	v_cndmask_b32_e64 v113, v24, 0, s[24:25]
	v_sub_f32_e32 v24, v28, v100
	v_exp_f32_e32 v24, v24
	s_waitcnt lgkmcnt(10)
	v_mfma_f32_16x16x32_bf16 v[16:19], v[96:99], v[40:43], v[16:19]
	v_cvt_pk_bf16_f32 v102, v110, v111
	v_cvt_pk_bf16_f32 v103, v112, v113
	v_cndmask_b32_e64 v114, v24, 0, s[26:27]
	v_sub_f32_e32 v24, v29, v100
	v_exp_f32_e32 v24, v24
	s_waitcnt lgkmcnt(6)
	v_mfma_f32_16x16x32_bf16 v[32:35], v[72:75], v[40:43], v[32:35]
	v_mul_f32_e64 v28, v48, v108
	v_mul_f32_e64 v29, v49, v108
	v_cndmask_b32_e64 v115, v24, 0, s[28:29]
	v_sub_f32_e32 v24, v30, v100
	v_exp_f32_e32 v24, v24
	v_add_f32_e32 v48, v111, v110
	v_add_f32_e32 v48, v112, v48
	v_add_f32_e32 v48, v113, v48
	v_cndmask_b32_e64 v116, v24, 0, s[30:31]
	v_sub_f32_e32 v24, v31, v100
	v_exp_f32_e32 v24, v24
	v_add_f32_e32 v48, v114, v48
	v_add_f32_e32 v48, v115, v48
	v_cvt_pk_bf16_f32 v104, v114, v115
	v_cndmask_b32_e64 v117, v24, 0, s[34:35]
	v_pk_mul_f32 v[24:25], v[44:45], v[106:107] op_sel_hi:[1,0]
	v_pk_mul_f32 v[44:45], v[60:61], v[106:107] op_sel_hi:[1,0]
	v_cvt_pk_bf16_f32 v105, v116, v117
	v_mfma_f32_16x16x32_bf16 v[24:27], v[88:91], v[40:43], v[24:27]
	v_add_f32_e32 v48, v116, v48
	v_pk_mul_f32 v[38:39], v[58:59], v[108:109] op_sel_hi:[1,0]
	v_pk_mul_f32 v[36:37], v[56:57], v[108:109] op_sel_hi:[1,0]
	s_waitcnt lgkmcnt(4)
	v_mfma_f32_16x16x32_bf16 v[40:43], v[68:71], v[40:43], v[44:47]
	v_mul_f32_e64 v30, v50, v108
	v_mul_f32_e64 v31, v51, v108
	v_pk_mul_f32 v[22:23], v[22:23], v[108:109] op_sel_hi:[1,0]
	v_pk_mul_f32 v[20:21], v[20:21], v[108:109] op_sel_hi:[1,0]
	v_pk_mul_f32 v[46:47], v[66:67], v[108:109] op_sel_hi:[1,0]
	v_pk_mul_f32 v[44:45], v[64:65], v[108:109] op_sel_hi:[1,0]
	s_waitcnt vmcnt(3)
	s_waitcnt vmcnt(1)
	s_waitcnt vmcnt(0)
	v_mfma_f32_16x16x32_bf16 v[4:7], v[76:79], v[12:15], 0
	v_mfma_f32_16x16x32_bf16 v[10:13], v[92:95], v[12:15], 0
	s_nop 5
	v_sub_u32_e32 v9, v198, v145
	v_cmp_gt_u32_e64 s[34:35], v9, v144
	v_mov_b32_e32 v15, v153
	v_mfma_f32_16x16x32_bf16 v[4:7], v[80:83], v[0:3], v[4:7]
	v_mfma_f32_16x16x32_bf16 v[0:3], v[84:87], v[0:3], v[10:13]
	s_nop 2
	v_add_u32_e32 v12, 1, v9
	v_cmp_gt_u32_e64 s[30:31], v12, v144
	s_nop 1
	v_cndmask_b32_e64 v4, v4, v246, s[34:35]
	s_nop 0
	v_cndmask_b32_e64 v5, v5, v246, s[30:31]
	v_max_f32_e32 v11, v4, v5
	v_add_u32_e32 v12, 2, v9
	v_add_u32_e32 v13, 3, v9
	v_cmp_gt_u32_e64 s[28:29], v12, v144
	v_cmp_gt_u32_e64 s[26:27], v13, v144
	v_mfma_f32_16x16x32_bf16 v[44:47], v[68:71], v[102:105], v[44:47]
	v_cndmask_b32_e64 v6, v6, v246, s[28:29]
	v_cndmask_b32_e64 v7, v7, v246, s[26:27]
	v_max3_f32 v11, v11, v6, v7
	v_add_u32_e32 v12, 16, v9
	v_add_u32_e32 v13, 17, v9
	v_cmp_gt_u32_e64 s[24:25], v12, v144
	v_cmp_gt_u32_e64 s[22:23], v13, v144
	v_add_f32_e32 v68, v117, v48
	v_cndmask_b32_e64 v0, v0, v246, s[24:25]
	v_cndmask_b32_e64 v13, v1, v246, s[22:23]
	v_max3_f32 v11, v11, v0, v13
	v_add_u32_e32 v12, 18, v9
	v_add_u32_e32 v9, 19, v9
	v_cmp_gt_u32_e64 s[0:1], v12, v144
	v_cmp_gt_u32_e32 vcc, v9, v144
	s_nop 0
	v_cndmask_b32_e64 v2, v2, v246, s[0:1]
	s_nop 0
	v_cndmask_b32_e64 v3, v3, v246, vcc
	v_max3_f32 v9, v11, v2, v3
	s_nop 1
	v_mov_b32_e32 v11, v9
	s_nop 1
	v_permlane32_swap_b32_e32 v11, v9
	v_max_f32_e32 v9, v9, v11
	s_nop 1
	v_mov_b32_e32 v11, v9
	s_nop 1
	v_permlane16_swap_b32_e32 v11, v9
	v_max_f32_e32 v9, v9, v11
	v_mov_b32_e32 v66, 1.0
	v_add_f32_e32 v69, v109, v107
	v_mov_b32_e32 v11, 0
	v_mov_b32_e32 v8, 0
	v_fmac_f32_e32 v69, v146, v106
	v_add_f32_e32 v65, v8, v11
	v_cvt_pk_bf16_f32 v14, v8, 0
	v_max_f32_e32 v8, v100, v9
	v_fmac_f32_e32 v65, v69, v66
	v_sub_f32_e32 v4, v4, v8
	v_cvt_pk_bf16_f32 v12, v11, 0
	v_exp_f32_e32 v4, v4
	v_sub_f32_e32 v5, v5, v8
	v_pk_mul_f32 v[10:11], v[34:35], v[66:67] op_sel_hi:[1,0]
	ds_bpermute_b32 v34, v170, v65
	v_exp_f32_e32 v5, v5
	v_sub_f32_e32 v6, v6, v8
	v_exp_f32_e32 v6, v6
	v_sub_f32_e32 v7, v7, v8
	v_exp_f32_e32 v7, v7
	v_sub_f32_e32 v0, v0, v8
	v_sub_f32_e32 v9, v100, v8
	v_exp_f32_e32 v0, v0
	v_sub_f32_e32 v1, v1, v8
	v_mfma_f32_16x16x32_bf16 v[36:39], v[72:75], v[102:105], v[36:39]
	v_exp_f32_e32 v72, v9
	v_exp_f32_e32 v1, v1
	v_sub_f32_e32 v2, v2, v8
	s_waitcnt lgkmcnt(0)
	v_add_f32_e32 v34, v65, v34
	v_add_f32_e32 v9, v5, v4
	v_exp_f32_e32 v2, v2
	v_sub_f32_e32 v3, v3, v8
	ds_bpermute_b32 v35, v171, v34
	v_add_f32_e32 v9, v6, v9
	v_exp_f32_e32 v3, v3
	v_add_f32_e32 v9, v7, v9
	v_add_f32_e32 v9, v0, v9
	v_cndmask_b32_e64 v1, v1, 0, s[22:23]
	ds_read_b64_tr_b16 v[62:63], v169 offset:6912
	ds_read_b64_tr_b16 v[60:61], v169 offset:4608
	ds_read_b64_tr_b16 v[56:57], v169 offset:4640
	ds_read_b64_tr_b16 v[58:59], v169 offset:6944
	ds_read_b64_tr_b16 v[52:53], v169 offset:4672
	ds_read_b64_tr_b16 v[54:55], v169 offset:6976
	ds_read_b64_tr_b16 v[48:49], v169 offset:4704
	ds_read_b64_tr_b16 v[50:51], v169 offset:7008
	v_add_f32_e32 v9, v1, v9
	v_add_f32_e32 v9, v2, v9
	s_waitcnt lgkmcnt(8)
	v_add_f32_e32 v34, v34, v35
	v_fmac_f32_e32 v68, v147, v108
	v_mov_b32_e32 v13, v153
	v_add_f32_e32 v64, v3, v9
	v_pk_mul_f32 v[8:9], v[32:33], v[66:67] op_sel_hi:[1,0]
	v_div_scale_f32 v35, s[0:1], v34, v34, 1.0
	v_fmac_f32_e32 v64, v68, v72
	v_cvt_pk_bf16_f32 v68, v4, v5
	v_cvt_pk_bf16_f32 v69, v6, v7
	v_pk_mul_f32 v[6:7], v[26:27], v[66:67] op_sel_hi:[1,0]
	v_pk_mul_f32 v[4:5], v[24:25], v[66:67] op_sel_hi:[1,0]
	s_waitcnt lgkmcnt(2)
	v_mfma_f32_16x16x32_bf16 v[24:27], v[52:55], v[12:15], v[8:11]
	v_cvt_pk_bf16_f32 v70, v0, v1
	v_cvt_pk_bf16_f32 v71, v2, v3
	v_pk_mul_f32 v[2:3], v[18:19], v[66:67] op_sel_hi:[1,0]
	v_pk_mul_f32 v[8:9], v[36:37], v[72:73] op_sel_hi:[1,0]
	v_rcp_f32_e32 v36, v35
	v_mfma_f32_16x16x32_bf16 v[20:23], v[96:99], v[102:105], v[20:23]
	v_mul_f32_e64 v10, v38, v72
	v_mul_f32_e64 v11, v39, v72
	v_pk_mul_f32 v[0:1], v[16:17], v[66:67] op_sel_hi:[1,0]
	v_fma_f32 v37, -v35, v36, 1.0
	v_fmac_f32_e32 v36, v37, v36
	v_div_scale_f32 v37, vcc, 1.0, v34, 1.0
	v_mul_f32_e32 v38, v37, v36
	v_fma_f32 v39, -v35, v38, v37
	v_mfma_f32_16x16x32_bf16 v[16:19], v[60:63], v[12:15], v[0:3]
	v_fmac_f32_e32 v38, v39, v36
	v_fma_f32 v35, -v35, v38, v37
	v_div_fmas_f32 v35, v35, v36, v38
	v_mfma_f32_16x16x32_bf16 v[28:31], v[88:91], v[102:105], v[28:31]
	v_mul_f32_e64 v2, v22, v72
	v_mul_f32_e64 v3, v23, v72
	v_pk_mul_f32 v[0:1], v[20:21], v[72:73] op_sel_hi:[1,0]
	v_div_fixup_f32 v34, v35, v34, 1.0
	v_mfma_f32_16x16x32_bf16 v[20:23], v[56:59], v[12:15], v[4:7]
	v_lshl_add_u64 v[32:33], v[156:157], 0, s[56:57]
	v_lshlrev_b64 v[36:37], 11, v[162:163]
	v_pk_mul_f32 v[16:17], v[16:17], v[34:35] op_sel_hi:[1,0]
	v_pk_mul_f32 v[18:19], v[18:19], v[34:35] op_sel_hi:[1,0]
	v_pk_mul_f32 v[6:7], v[30:31], v[72:73] op_sel_hi:[1,0]
	v_pk_mul_f32 v[4:5], v[28:29], v[72:73] op_sel_hi:[1,0]
	v_pk_mul_f32 v[30:31], v[42:43], v[66:67] op_sel_hi:[1,0]
	v_pk_mul_f32 v[28:29], v[40:41], v[66:67] op_sel_hi:[1,0]
	v_lshl_add_u64 v[36:37], v[32:33], 0, v[36:37]
	v_cvt_pk_bf16_f32 v16, v16, v17
	v_cvt_pk_bf16_f32 v17, v18, v19
	s_waitcnt lgkmcnt(0)
	v_mfma_f32_16x16x32_bf16 v[28:31], v[48:51], v[12:15], v[28:31]
	global_store_dwordx2 v[36:37], v[16:17], off
	v_pk_mul_f32 v[16:17], v[20:21], v[34:35] op_sel_hi:[1,0]
	v_pk_mul_f32 v[18:19], v[22:23], v[34:35] op_sel_hi:[1,0]
	v_cvt_pk_bf16_f32 v16, v16, v17
	v_cvt_pk_bf16_f32 v17, v18, v19
	global_store_dwordx2 v[36:37], v[16:17], off offset:32
	v_pk_mul_f32 v[16:17], v[24:25], v[34:35] op_sel_hi:[1,0]
	v_pk_mul_f32 v[18:19], v[26:27], v[34:35] op_sel_hi:[1,0]
	v_cvt_pk_bf16_f32 v16, v16, v17
	v_cvt_pk_bf16_f32 v17, v18, v19
	global_store_dwordx2 v[36:37], v[16:17], off offset:64
	v_pk_mul_f32 v[16:17], v[28:29], v[34:35] op_sel_hi:[1,0]
	v_pk_mul_f32 v[18:19], v[30:31], v[34:35] op_sel_hi:[1,0]
	v_cvt_pk_bf16_f32 v16, v16, v17
	v_cvt_pk_bf16_f32 v17, v18, v19
	global_store_dwordx2 v[36:37], v[16:17], off offset:96
	ds_bpermute_b32 v16, v170, v64
	v_mfma_f32_16x16x32_bf16 v[0:3], v[60:63], v[68:71], v[0:3]
	v_mul_f32_e64 v14, v46, v72
	v_mul_f32_e64 v15, v47, v72
	v_pk_mul_f32 v[12:13], v[44:45], v[72:73] op_sel_hi:[1,0]
	s_waitcnt lgkmcnt(0)
	v_add_f32_e32 v16, v64, v16
	ds_bpermute_b32 v17, v171, v16
	v_mfma_f32_16x16x32_bf16 v[4:7], v[56:59], v[68:71], v[4:7]
	s_waitcnt lgkmcnt(0)
	v_add_f32_e32 v16, v16, v17
	v_div_scale_f32 v17, s[0:1], v16, v16, 1.0
	v_rcp_f32_e32 v18, v17
	v_mfma_f32_16x16x32_bf16 v[8:11], v[52:55], v[68:71], v[8:11]
	v_fma_f32 v19, -v17, v18, 1.0
	v_fmac_f32_e32 v18, v19, v18
	v_div_scale_f32 v19, vcc, 1.0, v16, 1.0
	v_mul_f32_e32 v20, v19, v18
	v_fma_f32 v21, -v17, v20, v19
	v_fmac_f32_e32 v20, v21, v18
	v_fma_f32 v17, -v17, v20, v19
	v_div_fmas_f32 v17, v17, v18, v20
	v_div_fixup_f32 v16, v17, v16, 1.0
	v_lshlrev_b64 v[18:19], 11, v[160:161]
	v_pk_mul_f32 v[0:1], v[0:1], v[16:17] op_sel_hi:[1,0]
	v_pk_mul_f32 v[2:3], v[2:3], v[16:17] op_sel_hi:[1,0]
	v_lshl_add_u64 v[18:19], v[32:33], 0, v[18:19]
	v_cvt_pk_bf16_f32 v0, v0, v1
	v_cvt_pk_bf16_f32 v1, v2, v3
	v_mfma_f32_16x16x32_bf16 v[12:15], v[48:51], v[68:71], v[12:15]
	global_store_dwordx2 v[18:19], v[0:1], off
	v_pk_mul_f32 v[0:1], v[4:5], v[16:17] op_sel_hi:[1,0]
	v_pk_mul_f32 v[2:3], v[6:7], v[16:17] op_sel_hi:[1,0]
	v_cvt_pk_bf16_f32 v0, v0, v1
	v_cvt_pk_bf16_f32 v1, v2, v3
	global_store_dwordx2 v[18:19], v[0:1], off offset:32
	v_pk_mul_f32 v[0:1], v[8:9], v[16:17] op_sel_hi:[1,0]
	v_pk_mul_f32 v[2:3], v[10:11], v[16:17] op_sel_hi:[1,0]
	v_cvt_pk_bf16_f32 v0, v0, v1
	v_cvt_pk_bf16_f32 v1, v2, v3
	global_store_dwordx2 v[18:19], v[0:1], off offset:64
	v_pk_mul_f32 v[0:1], v[12:13], v[16:17] op_sel_hi:[1,0]
	v_pk_mul_f32 v[2:3], v[14:15], v[16:17] op_sel_hi:[1,0]
	v_cvt_pk_bf16_f32 v0, v0, v1
	v_cvt_pk_bf16_f32 v1, v2, v3
	global_store_dwordx2 v[18:19], v[0:1], off offset:96
	s_cbranch_scc1 .LBB0_246
	s_mov_b32 s76, s79
	v_readlane_b32 s72, v253, 43
	v_xor_b32_e32 v240, 32, v174
	v_xor_b32_e32 v241, 16, v174
	v_xor_b32_e32 v242, 8, v174
	v_xor_b32_e32 v243, 4, v174
	v_xor_b32_e32 v244, 2, v174
	v_xor_b32_e32 v245, 1, v174
	v_and_b32_e32 v246, 64, v174
